# combo1: removed redundant vmcnt(0) waits (P1 K-loop top, k/vs epilogues), de-serialized P2 prompt-epilogue and P3 sample-tile loads, barrier followers poll the top generation word
# speedup vs baseline: 1.0132x; 1.0132x over previous
; __device__ __forceinline__ unsigned xb_ld(unsigned* p)              { return __hip_atomic_load(p, __ATOMIC_RELAXED, __HIP_MEMORY_SCOPE_AGENT); }
; __device__ __forceinline__ unsigned xb_add(unsigned* p, unsigned v) { return __hip_atomic_fetch_add(p, v, __ATOMIC_RELAXED, __HIP_MEMORY_SCOPE_AGENT); }
; #define XB_SPIN(cond, bar) do { unsigned _sp = 0; while (cond) { __builtin_amdgcn_s_sleep(1); \
;     if ((++_sp & 255u) == 0u) { if (xb_ld(&(bar)[XB_TMO])) break; if (_sp > XB_SPIN_CAP) { atomicAdd(&(bar)[XB_TMO], 1u); break; } } } } while (0)
; __device__ __forceinline__ void xcd_barrier(const XcdBarrier& b) {
;     ...
;         const unsigned old = xb_add(&bar[XB_XSUB(b.x)], 1u);
;         const unsigned gen = old / nloc;
;         if (old + 1u == (gen + 1u) * nloc) {
;             __builtin_amdgcn_fence(__ATOMIC_RELEASE, "agent");
;             asm volatile("s_waitcnt vmcnt(0)" ::: "memory");
;             const unsigned og = xb_add(&bar[XB_TOP], 1u);
;             const unsigned tg = og / nx;
;             if (og + 1u == (tg + 1u) * nx) xb_add(&bar[XB_TOPGEN], 1u);
;             else XB_SPIN(xb_ld(&bar[XB_TOPGEN]) == tg, bar);
;             __builtin_amdgcn_fence(__ATOMIC_ACQUIRE, "agent");
;             xb_add(&bar[XB_XGEN(b.x)], 1u);
;             asm volatile("s_waitcnt vmcnt(0)" ::: "memory");
;         } else {
;             XB_SPIN(xb_ld(&bar[XB_XGEN(b.x)]) == gen, bar);
.LBB0_92:
	s_or_b64 exec, exec, s[6:7]
	v_cvt_f32_u32_e32 v4, v2
	s_waitcnt vmcnt(0)
	v_readfirstlane_b32 s4, v3
	v_sub_u32_e32 v3, 0, v2
	v_rcp_iflag_f32_e32 v4, v4
	v_add_u32_e32 v5, s4, v1
	v_mul_f32_e32 v4, 0x4f7ffffe, v4
	v_cvt_u32_f32_e32 v4, v4
	v_mul_lo_u32 v1, v3, v4
	v_mul_hi_u32 v1, v4, v1
	v_add_u32_e32 v1, v4, v1
	v_mul_hi_u32 v1, v5, v1
	v_mul_lo_u32 v3, v1, v2
	v_sub_u32_e32 v3, v5, v3
	v_add_u32_e32 v4, 1, v1
	v_cmp_ge_u32_e32 vcc, v3, v2
	s_nop 1
	v_cndmask_b32_e32 v1, v1, v4, vcc
	v_sub_u32_e32 v4, v3, v2
	v_cndmask_b32_e32 v3, v3, v4, vcc
	v_add_u32_e32 v4, 1, v1
	v_cmp_ge_u32_e32 vcc, v3, v2
	v_add_u32_e32 v3, 1, v5
	s_nop 0
	v_cndmask_b32_e32 v1, v1, v4, vcc
	v_mul_lo_u32 v4, v2, v1
	v_add_u32_e32 v2, v4, v2
	v_cmp_ne_u32_e32 vcc, v3, v2
	s_and_saveexec_b64 s[4:5], vcc
	s_xor_b64 s[4:5], exec, s[4:5]
	s_cbranch_execz .LBB0_106
	s_waitcnt lgkmcnt(0)
	v_mov_b32_e32 v0, 0
	s_add_u32 s10, s68, 0xd6b0500
	s_addc_u32 s11, s69, 0
	s_nop 0
	global_load_dword v0, v0, s[10:11] sc1
	s_waitcnt vmcnt(0)
	v_cmp_eq_u32_e32 vcc, v0, v1
	s_and_saveexec_b64 s[6:7], vcc
	s_cbranch_execz .LBB0_105
	s_add_u32 s8, s68, 0xd6ad200
	s_addc_u32 s9, s69, 0
	s_mov_b32 s22, 1
	s_mov_b64 s[12:13], 0
	v_mov_b32_e32 v0, 0
	s_branch .LBB0_96

; #define PG8_STAGE(bufoff, gbase, voff) do { _Pragma("unroll") for (int _i = 0; _i < 2; ++_i) \
;         __builtin_amdgcn_global_load_lds((const unsigned*)((const char*)(gbase) + (voff)[_i]), (LAS unsigned*)(lds + (bufoff) + ldsw + _i * 8192), 16, 0, 0); } while (0)
; #define PG8_LDA(dst, b, h) do { _Pragma("unroll") for (int m = 0; m < 4; ++m) _Pragma("unroll") for (int k = 0; k < 2; ++k) dst[m][k] = *(const LAS bf16x8*)(lds + PG8_SA(b, h) + aoff + m * 2048 + k * 1024); } while (0)
; #define PG8_LDB(dst, b, h) do { _Pragma("unroll") for (int n = 0; n < 2; ++n) _Pragma("unroll") for (int k = 0; k < 2; ++k) dst[n][k] = *(const LAS bf16x8*)(lds + PG8_SB(b, h) + boff + n * 2048 + k * 1024); } while (0)
; #define PG8_MMA(ai, bj, At, Bt) do { __builtin_amdgcn_s_setprio(1); _Pragma("unroll") for (int m = 0; m < 4; ++m) _Pragma("unroll") for (int n = 0; n < 2; ++n) _Pragma("unroll") for (int k = 0; k < 2; ++k) \
;         acc[ai][bj][m][n] = __builtin_amdgcn_mfma_f32_16x16x32_bf16(Bt[n][k], At[m][k], acc[ai][bj][m][n], 0, 0, 0); __builtin_amdgcn_s_setprio(0); } while (0)
; #define PG8_WAIT_V(n) asm volatile("s_waitcnt vmcnt(" #n ")" ::: "memory")
; #define PG8_WAIT_L(n) asm volatile("s_waitcnt lgkmcnt(" #n ")" ::: "memory")
; #define PG8_BAR __builtin_amdgcn_s_barrier()
; #define PG8_SCHED __builtin_amdgcn_sched_barrier(0)
; #define PG8_WAIT_V(n) asm volatile("s_waitcnt vmcnt(" #n ")" ::: "memory")
; #define PG8_BAR __builtin_amdgcn_s_barrier()
; template <class Epi, class Sched, bool SP2 = false>
; __device__ __forceinline__ void gemm_phase(LAS unsigned char* lds, const Gemm g, const Sched& S, const Epi& E) {
;     ...
;             const bool last = (t == nt - 2);
;             const char* a1 = cA + (size_t)(t + 1) * kstep;
;             const char* a2 = last ? nA : cA + (size_t)(t + 2) * kstep; const char* b2 = last ? nB : cB + (size_t)(t + 2) * kstep;
;             const char* a3 = a2 + kstep; const char* b3 = b2 + kstep;
;             if constexpr (SP2) {
;             PG8_LDB(B0, 0, 0); PG8_LDB(B1, 0, 1); PG8_SCHED; PG8_LDA(At, 0, 0); PG8_STAGE(PG8_SA(1, 1), a1 + hstep, voffA);
;             PG8_WAIT_V(8); PG8_WAIT_L(0); PG8_BAR; PG8_MMA(0, 0, At, B0); PG8_MMA(0, 1, At, B1); PG8_BAR; PG8_SCHED;
;             PG8_LDA(At, 0, 1); PG8_STAGE(PG8_SB(0, 0), b2, voffB); PG8_STAGE(PG8_SB(0, 1), b2 + hstep, voffB); PG8_STAGE(PG8_SA(0, 0), a2, voffA);
.LBB0_146:
	ds_read_b128 v[128:131], v187
	ds_read_b128 v[132:135], v187 offset:1024
	ds_read_b128 v[136:139], v187 offset:2048
	ds_read_b128 v[140:143], v187 offset:3072
	ds_read_b128 v[162:165], v188
	ds_read_b128 v[166:169], v188 offset:1024
	ds_read_b128 v[170:173], v188 offset:2048
	ds_read_b128 v[174:177], v188 offset:3072
	s_add_u32 s2, s0, 0xfffc0080
	s_addc_u32 s3, s1, -1
	s_cmp_eq_u32 s12, 12
	s_cselect_b32 s5, s6, s3
	s_cselect_b32 s4, s7, s2
	s_cselect_b32 s3, s8, s11
	s_cselect_b32 s2, s9, s10
	v_lshl_add_u64 v[182:183], s[0:1], 0, v[154:155]
	s_add_i32 m0, s61, 0xc000
	ds_read_b128 v[178:181], v189
	ds_read_b128 v[200:203], v189 offset:1024
	ds_read_b128 v[204:207], v189 offset:2048
	ds_read_b128 v[208:211], v189 offset:3072
	ds_read_b128 v[212:215], v189 offset:4096
	ds_read_b128 v[216:219], v189 offset:5120
	ds_read_b128 v[220:223], v189 offset:6144
	ds_read_b128 v[224:227], v189 offset:7168
	global_load_lds_dwordx4 v[182:183], off
	v_lshl_add_u64 v[182:183], s[0:1], 0, v[156:157]
	s_add_i32 m0, s61, 0xe000
	s_nop 0
	global_load_lds_dwordx4 v[182:183], off
	s_waitcnt vmcnt(8)
	s_waitcnt lgkmcnt(0)
	s_barrier
	s_setprio 1
	s_waitcnt lgkmcnt(0)
	v_mfma_f32_16x16x32_bf16 v[124:127], v[128:131], v[178:181], v[124:127]
	v_mfma_f32_16x16x32_bf16 v[120:123], v[136:139], v[178:181], v[120:123]
	v_mfma_f32_16x16x32_bf16 v[116:119], v[128:131], v[204:207], v[116:119]
	v_mfma_f32_16x16x32_bf16 v[112:115], v[136:139], v[204:207], v[112:115]
	v_mfma_f32_16x16x32_bf16 v[108:111], v[128:131], v[212:215], v[108:111]
	v_mfma_f32_16x16x32_bf16 v[104:107], v[136:139], v[212:215], v[104:107]
	v_mfma_f32_16x16x32_bf16 v[100:103], v[128:131], v[220:223], v[100:103]
	v_mfma_f32_16x16x32_bf16 v[96:99], v[136:139], v[220:223], v[96:99]
	v_mfma_f32_16x16x32_bf16 v[124:127], v[132:135], v[200:203], v[124:127]
	v_mfma_f32_16x16x32_bf16 v[120:123], v[140:143], v[200:203], v[120:123]
	v_mfma_f32_16x16x32_bf16 v[116:119], v[132:135], v[208:211], v[116:119]
	v_mfma_f32_16x16x32_bf16 v[112:115], v[140:143], v[208:211], v[112:115]
	v_mfma_f32_16x16x32_bf16 v[108:111], v[132:135], v[216:219], v[108:111]
	v_mfma_f32_16x16x32_bf16 v[104:107], v[140:143], v[216:219], v[104:107]
	v_mfma_f32_16x16x32_bf16 v[100:103], v[132:135], v[224:227], v[100:103]
	v_mfma_f32_16x16x32_bf16 v[96:99], v[140:143], v[224:227], v[96:99]
	s_setprio 0
	s_setprio 1
	v_mfma_f32_16x16x32_bf16 v[60:63], v[162:165], v[178:181], v[60:63]
	v_mfma_f32_16x16x32_bf16 v[56:59], v[170:173], v[178:181], v[56:59]
	v_mfma_f32_16x16x32_bf16 v[52:55], v[162:165], v[204:207], v[52:55]
	v_mfma_f32_16x16x32_bf16 v[48:51], v[170:173], v[204:207], v[48:51]
	v_mfma_f32_16x16x32_bf16 v[44:47], v[162:165], v[212:215], v[44:47]
	v_mfma_f32_16x16x32_bf16 v[40:43], v[170:173], v[212:215], v[40:43]
	v_mfma_f32_16x16x32_bf16 v[36:39], v[162:165], v[220:223], v[36:39]
	v_mfma_f32_16x16x32_bf16 v[32:35], v[170:173], v[220:223], v[32:35]
	v_mfma_f32_16x16x32_bf16 v[60:63], v[166:169], v[200:203], v[60:63]
	v_mfma_f32_16x16x32_bf16 v[56:59], v[174:177], v[200:203], v[56:59]
	v_mfma_f32_16x16x32_bf16 v[52:55], v[166:169], v[208:211], v[52:55]
	v_mfma_f32_16x16x32_bf16 v[48:51], v[174:177], v[208:211], v[48:51]
	v_mfma_f32_16x16x32_bf16 v[44:47], v[166:169], v[216:219], v[44:47]
	v_mfma_f32_16x16x32_bf16 v[40:43], v[174:177], v[216:219], v[40:43]
	v_mfma_f32_16x16x32_bf16 v[36:39], v[166:169], v[224:227], v[36:39]
	v_mfma_f32_16x16x32_bf16 v[32:35], v[174:177], v[224:227], v[32:35]
	s_setprio 0
	s_barrier
	s_add_i32 s13, s46, s73
	v_lshl_add_u64 v[182:183], s[2:3], 0, v[146:147]
	s_mov_b32 m0, s13
	ds_read_b128 v[178:181], v189 offset:16384
	ds_read_b128 v[200:203], v189 offset:17408
	ds_read_b128 v[204:207], v189 offset:18432
	ds_read_b128 v[208:211], v189 offset:19456
	ds_read_b128 v[212:215], v189 offset:20480
	ds_read_b128 v[216:219], v189 offset:21504
	ds_read_b128 v[220:223], v189 offset:22528
	ds_read_b128 v[224:227], v189 offset:23552
	global_load_lds_dwordx4 v[182:183], off
	s_add_i32 m0, s13, 0x2000
	s_add_u32 s14, s2, 0x40000
	v_lshl_add_u64 v[196:197], s[2:3], 0, v[150:151]
	s_addc_u32 s15, s3, 0
	s_add_i32 s13, s47, s73
	global_load_lds_dwordx4 v[196:197], off
	v_lshl_add_u64 v[228:229], s[14:15], 0, v[146:147]
	s_mov_b32 m0, s13
	v_lshl_add_u64 v[230:231], s[4:5], 0, v[148:149]
	global_load_lds_dwordx4 v[228:229], off
	v_lshl_add_u64 v[228:229], s[14:15], 0, v[150:151]
	s_add_i32 m0, s13, 0x2000
	s_nop 0
	global_load_lds_dwordx4 v[228:229], off
	v_lshl_add_u64 v[228:229], s[4:5], 0, v[144:145]
	s_mov_b32 m0, s61
	s_nop 0
	global_load_lds_dwordx4 v[228:229], off
	s_mov_b32 m0, s75
	s_nop 0
	global_load_lds_dwordx4 v[230:231], off
	s_waitcnt vmcnt(8)
	s_waitcnt lgkmcnt(0)
	s_barrier
; #define PG8_STAGE(bufoff, gbase, voff) do { _Pragma("unroll") for (int _i = 0; _i < 2; ++_i) \
;         __builtin_amdgcn_global_load_lds((const unsigned*)((const char*)(gbase) + (voff)[_i]), (LAS unsigned*)(lds + (bufoff) + ldsw + _i * 8192), 16, 0, 0); } while (0)
; #define PG8_LDA(dst, b, h) do { _Pragma("unroll") for (int m = 0; m < 4; ++m) _Pragma("unroll") for (int k = 0; k < 2; ++k) dst[m][k] = *(const LAS bf16x8*)(lds + PG8_SA(b, h) + aoff + m * 2048 + k * 1024); } while (0)
; #define PG8_LDB(dst, b, h) do { _Pragma("unroll") for (int n = 0; n < 2; ++n) _Pragma("unroll") for (int k = 0; k < 2; ++k) dst[n][k] = *(const LAS bf16x8*)(lds + PG8_SB(b, h) + boff + n * 2048 + k * 1024); } while (0)
; #define PG8_MMA(ai, bj, At, Bt) do { __builtin_amdgcn_s_setprio(1); _Pragma("unroll") for (int m = 0; m < 4; ++m) _Pragma("unroll") for (int n = 0; n < 2; ++n) _Pragma("unroll") for (int k = 0; k < 2; ++k) \
;         acc[ai][bj][m][n] = __builtin_amdgcn_mfma_f32_16x16x32_bf16(Bt[n][k], At[m][k], acc[ai][bj][m][n], 0, 0, 0); __builtin_amdgcn_s_setprio(0); } while (0)
; #define PG8_WAIT_V(n) asm volatile("s_waitcnt vmcnt(" #n ")" ::: "memory")
; #define PG8_WAIT_L(n) asm volatile("s_waitcnt lgkmcnt(" #n ")" ::: "memory")
; #define PG8_BAR __builtin_amdgcn_s_barrier()
; #define PG8_SCHED __builtin_amdgcn_sched_barrier(0)
; #define PG8_STAGE(bufoff, gbase, voff) do { _Pragma("unroll") for (int _i = 0; _i < 2; ++_i) \
;         __builtin_amdgcn_global_load_lds((const unsigned*)((const char*)(gbase) + (voff)[_i]), (LAS unsigned*)(lds + (bufoff) + ldsw + _i * 8192), 16, 0, 0); } while (0)
; #define PG8_LDA(dst, b, h) do { _Pragma("unroll") for (int m = 0; m < 4; ++m) _Pragma("unroll") for (int k = 0; k < 2; ++k) dst[m][k] = *(const LAS bf16x8*)(lds + PG8_SA(b, h) + aoff + m * 2048 + k * 1024); } while (0)
; template <class Epi, class Sched, bool SP2 = false>
; __device__ __forceinline__ void gemm_phase(LAS unsigned char* lds, const Gemm g, const Sched& S, const Epi& E) {
;     ...
;             PG8_WAIT_V(8); PG8_WAIT_L(0); PG8_BAR; PG8_MMA(1, 0, At, B0); PG8_MMA(1, 1, At, B1); PG8_BAR; PG8_SCHED;
;             PG8_LDB(B0, 1, 0); PG8_LDB(B1, 1, 1); PG8_SCHED; PG8_LDA(At, 1, 0); PG8_STAGE(PG8_SA(0, 1), a2 + hstep, voffA);
;             PG8_WAIT_V(8); PG8_WAIT_L(0); PG8_BAR; PG8_MMA(0, 0, At, B0); PG8_MMA(0, 1, At, B1); PG8_BAR; PG8_SCHED;
	s_setprio 1
	s_waitcnt lgkmcnt(0)
	v_mfma_f32_16x16x32_bf16 v[92:95], v[128:131], v[178:181], v[92:95]
	v_mfma_f32_16x16x32_bf16 v[88:91], v[136:139], v[178:181], v[88:91]
	v_mfma_f32_16x16x32_bf16 v[84:87], v[128:131], v[204:207], v[84:87]
	v_mfma_f32_16x16x32_bf16 v[80:83], v[136:139], v[204:207], v[80:83]
	v_mfma_f32_16x16x32_bf16 v[76:79], v[128:131], v[212:215], v[76:79]
	v_mfma_f32_16x16x32_bf16 v[72:75], v[136:139], v[212:215], v[72:75]
	v_mfma_f32_16x16x32_bf16 v[68:71], v[128:131], v[220:223], v[68:71]
	v_mfma_f32_16x16x32_bf16 v[64:67], v[136:139], v[220:223], v[64:67]
	v_mfma_f32_16x16x32_bf16 v[92:95], v[132:135], v[200:203], v[92:95]
	v_mfma_f32_16x16x32_bf16 v[88:91], v[140:143], v[200:203], v[88:91]
	v_mfma_f32_16x16x32_bf16 v[84:87], v[132:135], v[208:211], v[84:87]
	v_mfma_f32_16x16x32_bf16 v[80:83], v[140:143], v[208:211], v[80:83]
	v_mfma_f32_16x16x32_bf16 v[76:79], v[132:135], v[216:219], v[76:79]
	v_mfma_f32_16x16x32_bf16 v[72:75], v[140:143], v[216:219], v[72:75]
	v_mfma_f32_16x16x32_bf16 v[68:71], v[132:135], v[224:227], v[68:71]
	v_mfma_f32_16x16x32_bf16 v[64:67], v[140:143], v[224:227], v[64:67]
	s_setprio 0
	s_setprio 1
	v_mfma_f32_16x16x32_bf16 v[28:31], v[162:165], v[178:181], v[28:31]
	v_mfma_f32_16x16x32_bf16 v[24:27], v[170:173], v[178:181], v[24:27]
	v_mfma_f32_16x16x32_bf16 v[20:23], v[162:165], v[204:207], v[20:23]
	v_mfma_f32_16x16x32_bf16 v[16:19], v[170:173], v[204:207], v[16:19]
	v_mfma_f32_16x16x32_bf16 v[12:15], v[162:165], v[212:215], v[12:15]
	v_mfma_f32_16x16x32_bf16 v[8:11], v[170:173], v[212:215], v[8:11]
	v_mfma_f32_16x16x32_bf16 v[4:7], v[162:165], v[220:223], v[4:7]
	v_mfma_f32_16x16x32_bf16 v[0:3], v[170:173], v[220:223], v[0:3]
	v_mfma_f32_16x16x32_bf16 v[28:31], v[166:169], v[200:203], v[28:31]
	v_mfma_f32_16x16x32_bf16 v[24:27], v[174:177], v[200:203], v[24:27]
	v_mfma_f32_16x16x32_bf16 v[20:23], v[166:169], v[208:211], v[20:23]
	v_mfma_f32_16x16x32_bf16 v[16:19], v[174:177], v[208:211], v[16:19]
	v_mfma_f32_16x16x32_bf16 v[12:15], v[166:169], v[216:219], v[12:15]
	v_mfma_f32_16x16x32_bf16 v[8:11], v[174:177], v[216:219], v[8:11]
	v_mfma_f32_16x16x32_bf16 v[4:7], v[166:169], v[224:227], v[4:7]
	v_mfma_f32_16x16x32_bf16 v[0:3], v[174:177], v[224:227], v[0:3]
	s_setprio 0
	s_barrier
	s_add_i32 s13, 0, 0x18000
	s_add_i32 s14, 0, 0x1c000
	v_add_u32_e32 v140, s13, v186
	v_add_u32_e32 v152, s14, v186
	ds_read_b128 v[128:131], v140
	ds_read_b128 v[132:135], v140 offset:1024
	ds_read_b128 v[136:139], v140 offset:2048
	ds_read_b128 v[140:143], v140 offset:3072
	ds_read_b128 v[162:165], v152
	ds_read_b128 v[166:169], v152 offset:1024
	ds_read_b128 v[170:173], v152 offset:2048
	ds_read_b128 v[174:177], v152 offset:3072
	s_add_u32 s4, s4, 0x40000
	s_addc_u32 s5, s5, 0
	s_mov_b32 m0, s77
	v_lshl_add_u64 v[232:233], s[4:5], 0, v[144:145]
	ds_read_b128 v[178:181], v189 offset:32768
	ds_read_b128 v[200:203], v189 offset:33792
	ds_read_b128 v[204:207], v189 offset:34816
	ds_read_b128 v[208:211], v189 offset:35840
	ds_read_b128 v[212:215], v189 offset:36864
	ds_read_b128 v[216:219], v189 offset:37888
	ds_read_b128 v[220:223], v189 offset:38912
	ds_read_b128 v[224:227], v189 offset:39936
	global_load_lds_dwordx4 v[232:233], off
	v_lshl_add_u64 v[232:233], s[4:5], 0, v[148:149]
	s_mov_b32 m0, s96
	s_nop 0
	global_load_lds_dwordx4 v[232:233], off
	s_waitcnt vmcnt(8)
	s_waitcnt lgkmcnt(0)
	s_barrier
	s_setprio 1
	s_waitcnt lgkmcnt(0)
	v_mfma_f32_16x16x32_bf16 v[124:127], v[128:131], v[178:181], v[124:127]
	v_mfma_f32_16x16x32_bf16 v[120:123], v[136:139], v[178:181], v[120:123]
	v_mfma_f32_16x16x32_bf16 v[116:119], v[128:131], v[204:207], v[116:119]
	v_mfma_f32_16x16x32_bf16 v[112:115], v[136:139], v[204:207], v[112:115]
	v_mfma_f32_16x16x32_bf16 v[108:111], v[128:131], v[212:215], v[108:111]
	v_mfma_f32_16x16x32_bf16 v[104:107], v[136:139], v[212:215], v[104:107]
	v_mfma_f32_16x16x32_bf16 v[100:103], v[128:131], v[220:223], v[100:103]
	v_mfma_f32_16x16x32_bf16 v[96:99], v[136:139], v[220:223], v[96:99]
	v_mfma_f32_16x16x32_bf16 v[124:127], v[132:135], v[200:203], v[124:127]
	v_mfma_f32_16x16x32_bf16 v[120:123], v[140:143], v[200:203], v[120:123]
	v_mfma_f32_16x16x32_bf16 v[116:119], v[132:135], v[208:211], v[116:119]
	v_mfma_f32_16x16x32_bf16 v[112:115], v[140:143], v[208:211], v[112:115]
	v_mfma_f32_16x16x32_bf16 v[108:111], v[132:135], v[216:219], v[108:111]
	v_mfma_f32_16x16x32_bf16 v[104:107], v[140:143], v[216:219], v[104:107]
	v_mfma_f32_16x16x32_bf16 v[100:103], v[132:135], v[224:227], v[100:103]
	v_mfma_f32_16x16x32_bf16 v[96:99], v[140:143], v[224:227], v[96:99]
	s_setprio 0
	s_setprio 1
	v_mfma_f32_16x16x32_bf16 v[60:63], v[162:165], v[178:181], v[60:63]
	v_mfma_f32_16x16x32_bf16 v[56:59], v[170:173], v[178:181], v[56:59]
	v_mfma_f32_16x16x32_bf16 v[52:55], v[162:165], v[204:207], v[52:55]
	v_mfma_f32_16x16x32_bf16 v[48:51], v[170:173], v[204:207], v[48:51]
	v_mfma_f32_16x16x32_bf16 v[44:47], v[162:165], v[212:215], v[44:47]
	v_mfma_f32_16x16x32_bf16 v[40:43], v[170:173], v[212:215], v[40:43]
	v_mfma_f32_16x16x32_bf16 v[36:39], v[162:165], v[220:223], v[36:39]
	v_mfma_f32_16x16x32_bf16 v[32:35], v[170:173], v[220:223], v[32:35]
	v_mfma_f32_16x16x32_bf16 v[60:63], v[166:169], v[200:203], v[60:63]
	v_mfma_f32_16x16x32_bf16 v[56:59], v[174:177], v[200:203], v[56:59]
	v_mfma_f32_16x16x32_bf16 v[52:55], v[166:169], v[208:211], v[52:55]
	v_mfma_f32_16x16x32_bf16 v[48:51], v[174:177], v[208:211], v[48:51]
	v_mfma_f32_16x16x32_bf16 v[44:47], v[166:169], v[216:219], v[44:47]
	v_mfma_f32_16x16x32_bf16 v[40:43], v[174:177], v[216:219], v[40:43]
	v_mfma_f32_16x16x32_bf16 v[36:39], v[166:169], v[224:227], v[36:39]
	v_mfma_f32_16x16x32_bf16 v[32:35], v[174:177], v[224:227], v[32:35]
	s_setprio 0
	s_barrier
; #define PG8_STAGE(bufoff, gbase, voff) do { _Pragma("unroll") for (int _i = 0; _i < 2; ++_i) \
;         __builtin_amdgcn_global_load_lds((const unsigned*)((const char*)(gbase) + (voff)[_i]), (LAS unsigned*)(lds + (bufoff) + ldsw + _i * 8192), 16, 0, 0); } while (0)
; #define PG8_LDA(dst, b, h) do { _Pragma("unroll") for (int m = 0; m < 4; ++m) _Pragma("unroll") for (int k = 0; k < 2; ++k) dst[m][k] = *(const LAS bf16x8*)(lds + PG8_SA(b, h) + aoff + m * 2048 + k * 1024); } while (0)
; #define PG8_MMA(ai, bj, At, Bt) do { __builtin_amdgcn_s_setprio(1); _Pragma("unroll") for (int m = 0; m < 4; ++m) _Pragma("unroll") for (int n = 0; n < 2; ++n) _Pragma("unroll") for (int k = 0; k < 2; ++k) \
;         acc[ai][bj][m][n] = __builtin_amdgcn_mfma_f32_16x16x32_bf16(Bt[n][k], At[m][k], acc[ai][bj][m][n], 0, 0, 0); __builtin_amdgcn_s_setprio(0); } while (0)
; #define PG8_WAIT_V(n) asm volatile("s_waitcnt vmcnt(" #n ")" ::: "memory")
; #define PG8_WAIT_L(n) asm volatile("s_waitcnt lgkmcnt(" #n ")" ::: "memory")
; #define PG8_BAR __builtin_amdgcn_s_barrier()
; #define PG8_SCHED __builtin_amdgcn_sched_barrier(0)
; #define PG8_STAGE(bufoff, gbase, voff) do { _Pragma("unroll") for (int _i = 0; _i < 2; ++_i) \
;         __builtin_amdgcn_global_load_lds((const unsigned*)((const char*)(gbase) + (voff)[_i]), (LAS unsigned*)(lds + (bufoff) + ldsw + _i * 8192), 16, 0, 0); } while (0)
; #define PG8_LDA(dst, b, h) do { _Pragma("unroll") for (int m = 0; m < 4; ++m) _Pragma("unroll") for (int k = 0; k < 2; ++k) dst[m][k] = *(const LAS bf16x8*)(lds + PG8_SA(b, h) + aoff + m * 2048 + k * 1024); } while (0)
; #define PG8_WAIT_V(n) asm volatile("s_waitcnt vmcnt(" #n ")" ::: "memory")
; #define PG8_WAIT_L(n) asm volatile("s_waitcnt lgkmcnt(" #n ")" ::: "memory")
; #define PG8_BAR __builtin_amdgcn_s_barrier()
; #define PG8_SCHED __builtin_amdgcn_sched_barrier(0)
; template <class Epi, class Sched, bool SP2 = false>
; __device__ __forceinline__ void gemm_phase(LAS unsigned char* lds, const Gemm g, const Sched& S, const Epi& E) {
;     ...
;             PG8_LDA(At, 1, 1); PG8_STAGE(PG8_SB(1, 0), b3, voffB); PG8_STAGE(PG8_SB(1, 1), b3 + hstep, voffB); PG8_STAGE(PG8_SA(1, 0), a3, voffA);
;             PG8_WAIT_V(8); PG8_WAIT_L(0); PG8_BAR; PG8_MMA(1, 0, At, B0); PG8_MMA(1, 1, At, B1); PG8_BAR; PG8_SCHED;
	s_add_i32 s4, s13, s73
	v_lshl_add_u64 v[182:183], v[182:183], 0, s[34:35]
	s_mov_b32 m0, s4
	ds_read_b128 v[178:181], v189 offset:49152
	ds_read_b128 v[200:203], v189 offset:50176
	ds_read_b128 v[204:207], v189 offset:51200
	ds_read_b128 v[208:211], v189 offset:52224
	ds_read_b128 v[212:215], v189 offset:53248
	ds_read_b128 v[216:219], v189 offset:54272
	ds_read_b128 v[220:223], v189 offset:55296
	ds_read_b128 v[224:227], v189 offset:56320
	global_load_lds_dwordx4 v[182:183], off
	s_add_i32 m0, s4, 0x2000
	s_add_u32 s2, s2, 0x40080
	v_lshl_add_u64 v[182:183], v[196:197], 0, s[34:35]
	s_addc_u32 s3, s3, 0
	s_add_i32 s4, s14, s73
	global_load_lds_dwordx4 v[182:183], off
	v_lshl_add_u64 v[182:183], s[2:3], 0, v[146:147]
	s_mov_b32 m0, s4
	s_nop 0
	global_load_lds_dwordx4 v[182:183], off
	v_lshl_add_u64 v[182:183], s[2:3], 0, v[150:151]
	s_add_i32 m0, s4, 0x2000
	s_nop 0
	global_load_lds_dwordx4 v[182:183], off
	v_lshl_add_u64 v[182:183], v[228:229], 0, s[34:35]
	s_mov_b32 m0, s36
	s_nop 0
	global_load_lds_dwordx4 v[182:183], off
	v_lshl_add_u64 v[182:183], v[230:231], 0, s[34:35]
	s_mov_b32 m0, s37
	s_nop 0
	global_load_lds_dwordx4 v[182:183], off
	s_waitcnt vmcnt(8)
	s_waitcnt lgkmcnt(0)
	s_barrier
	s_setprio 1
	s_waitcnt lgkmcnt(0)
	v_mfma_f32_16x16x32_bf16 v[92:95], v[128:131], v[178:181], v[92:95]
	v_mfma_f32_16x16x32_bf16 v[88:91], v[136:139], v[178:181], v[88:91]
	v_mfma_f32_16x16x32_bf16 v[84:87], v[128:131], v[204:207], v[84:87]
	v_mfma_f32_16x16x32_bf16 v[80:83], v[136:139], v[204:207], v[80:83]
	v_mfma_f32_16x16x32_bf16 v[76:79], v[128:131], v[212:215], v[76:79]
	v_mfma_f32_16x16x32_bf16 v[72:75], v[136:139], v[212:215], v[72:75]
	v_mfma_f32_16x16x32_bf16 v[68:71], v[128:131], v[220:223], v[68:71]
	v_mfma_f32_16x16x32_bf16 v[64:67], v[136:139], v[220:223], v[64:67]
	v_mfma_f32_16x16x32_bf16 v[92:95], v[132:135], v[200:203], v[92:95]
	v_mfma_f32_16x16x32_bf16 v[88:91], v[140:143], v[200:203], v[88:91]
	v_mfma_f32_16x16x32_bf16 v[84:87], v[132:135], v[208:211], v[84:87]
	v_mfma_f32_16x16x32_bf16 v[80:83], v[140:143], v[208:211], v[80:83]
	v_mfma_f32_16x16x32_bf16 v[76:79], v[132:135], v[216:219], v[76:79]
	v_mfma_f32_16x16x32_bf16 v[72:75], v[140:143], v[216:219], v[72:75]
	v_mfma_f32_16x16x32_bf16 v[68:71], v[132:135], v[224:227], v[68:71]
	v_mfma_f32_16x16x32_bf16 v[64:67], v[140:143], v[224:227], v[64:67]
	s_setprio 0
	s_setprio 1
	v_mfma_f32_16x16x32_bf16 v[28:31], v[162:165], v[178:181], v[28:31]
	v_mfma_f32_16x16x32_bf16 v[24:27], v[170:173], v[178:181], v[24:27]
	v_mfma_f32_16x16x32_bf16 v[20:23], v[162:165], v[204:207], v[20:23]
	v_mfma_f32_16x16x32_bf16 v[16:19], v[170:173], v[204:207], v[16:19]
	v_mfma_f32_16x16x32_bf16 v[12:15], v[162:165], v[212:215], v[12:15]
	v_mfma_f32_16x16x32_bf16 v[8:11], v[170:173], v[212:215], v[8:11]
	v_mfma_f32_16x16x32_bf16 v[4:7], v[162:165], v[220:223], v[4:7]
	v_mfma_f32_16x16x32_bf16 v[0:3], v[170:173], v[220:223], v[0:3]
	v_mfma_f32_16x16x32_bf16 v[28:31], v[166:169], v[200:203], v[28:31]
	v_mfma_f32_16x16x32_bf16 v[24:27], v[174:177], v[200:203], v[24:27]
	v_mfma_f32_16x16x32_bf16 v[20:23], v[166:169], v[208:211], v[20:23]
	v_mfma_f32_16x16x32_bf16 v[16:19], v[174:177], v[208:211], v[16:19]
	v_mfma_f32_16x16x32_bf16 v[12:15], v[166:169], v[216:219], v[12:15]
	v_mfma_f32_16x16x32_bf16 v[8:11], v[174:177], v[216:219], v[8:11]
	v_mfma_f32_16x16x32_bf16 v[4:7], v[166:169], v[224:227], v[4:7]
	v_mfma_f32_16x16x32_bf16 v[0:3], v[174:177], v[224:227], v[0:3]
	s_setprio 0
	s_barrier
	s_add_i32 s12, s12, 2
	s_add_u32 s0, s0, 0x100
	s_addc_u32 s1, s1, 0
	s_add_u32 s10, s10, 0x100
	s_addc_u32 s11, s11, 0
	s_cmp_gt_u32 s12, 13
	s_cbranch_scc0 .LBB0_146
; #define UNROLL _Pragma("unroll")
; __device__ __forceinline__ float gelu_f(float x) { const float y = 1.5957691216f * (x + 0.044715f * x * x * x); return x * sigmoid_f(y); }
; __device__ __forceinline__ float dot4(f32x4 a) { return (a.x * a.x + a.y * a.y) + (a.z * a.z + a.w * a.w); }
;     template <int TYPE>
;     __device__ __forceinline__ void body(f32x4 (&acc)[2][2][4][2], const Unit& u, int wr, int wc, int fr, int fq) const {
;     ...
;             UNROLL for (int ai = 0; ai < 2; ++ai) UNROLL for (int m = 0; m < 4; ++m) UNROLL for (int bj = 0; bj < 2; ++bj) {
;                 f32x4 t0 = acc[ai][bj][m][0], t1 = acc[ai][bj][m][1];
;                 if (TYPE == 5) { UNROLL for (int j = 0; j < 4; ++j) { t0[j] = gelu_f(t0[j]); t1[j] = gelu_f(t1[j]); } }
;                 float s = dot4(t0) + dot4(t1);
;                 asm volatile("" : "+v"(s));
;                 s += __shfl_xor(s, 16); s += __shfl_xor(s, 32);
;                 if (fq == 0) xch[((ai * 128 + m * 16 + lrow) * 4 + wc) * 2 + bj] = s;
;     __device__ __forceinline__ void operator()(f32x4 (&acc)[2][2][4][2], const Unit& u, int wr, int wc, int fr, int fq) const {
;     ...
;         switch (u.pn >> 1) {
;             case 0: body<0>(acc, u, wr, wc, fr, fq); break;
;             case 1: body<1>(acc, u, wr, wc, fr, fq); break;
;             case 2: body<2>(acc, u, wr, wc, fr, fq); break;
;             case 3: body<3>(acc, u, wr, wc, fr, fq); break;
;             case 5: body<5>(acc, u, wr, wc, fr, fq); break;
	s_ashr_i32 s53, s76, 1
	v_mov_b32_e32 v195, v184
	v_mov_b32_e32 v196, v185
	s_mov_b64 s[0:1], -1
	s_mov_b64 s[78:79], 0
	s_cmp_lt_i32 s53, 2
	s_mov_b64 s[86:87], 0
	s_cbranch_scc1 .LBB0_368
	s_cmp_gt_i32 s53, 2
	s_cbranch_scc0 .LBB0_269
	s_cmp_gt_i32 s53, 4
	s_cbranch_scc0 .LBB0_233
	s_cmp_eq_u32 s53, 5
	s_mov_b64 s[86:87], -1
	s_cbranch_scc0 .LBB0_232
	v_mul_f32_e32 v130, 0x3d372713, v125
	v_mul_f32_e32 v128, 0x3d372713, v124
	v_mul_f32_e32 v130, v125, v130
	v_mul_f32_e32 v134, 0x3d372713, v127
	v_mul_f32_e32 v128, v124, v128
	v_fma_f32 v130, v125, v130, v125
	v_mul_f32_e32 v132, 0x3d372713, v126
	v_mul_f32_e32 v134, v127, v134
	v_fma_f32 v128, v124, v128, v124
	v_mul_f32_e32 v130, 0x3fcc422a, v130
	v_mul_f32_e32 v131, 0x3d372713, v121
	v_mul_f32_e32 v132, v126, v132
	v_fma_f32 v134, v127, v134, v127
	v_mul_f32_e32 v128, 0x3fcc422a, v128
	v_mul_f32_e32 v129, 0x3d372713, v120
	v_mul_f32_e32 v130, 0xbfb8aa3b, v130
	v_mul_f32_e32 v131, v121, v131
	v_fma_f32 v132, v126, v132, v126
	v_mul_f32_e32 v134, 0x3fcc422a, v134
	v_mul_f32_e32 v135, 0x3d372713, v123
	v_mul_f32_e32 v128, 0xbfb8aa3b, v128
	v_mul_f32_e32 v129, v120, v129
	v_exp_f32_e32 v130, v130
	v_fma_f32 v131, v121, v131, v121
	v_mul_f32_e32 v132, 0x3fcc422a, v132
	v_mul_f32_e32 v133, 0x3d372713, v122
	v_mul_f32_e32 v134, 0xbfb8aa3b, v134
	v_mul_f32_e32 v135, v123, v135
	v_exp_f32_e32 v128, v128
	v_fma_f32 v129, v120, v129, v120
	v_mul_f32_e32 v131, 0x3fcc422a, v131
	v_mul_f32_e32 v132, 0xbfb8aa3b, v132
	v_mul_f32_e32 v133, v122, v133
	v_exp_f32_e32 v134, v134
	v_fma_f32 v135, v123, v135, v123
	v_mul_f32_e32 v129, 0x3fcc422a, v129
	v_mul_f32_e32 v131, 0xbfb8aa3b, v131
	v_exp_f32_e32 v132, v132
	v_fma_f32 v133, v122, v133, v122
	v_mul_f32_e32 v135, 0x3fcc422a, v135
	v_mul_f32_e32 v129, 0xbfb8aa3b, v129
	v_exp_f32_e32 v131, v131
	v_mul_f32_e32 v133, 0x3fcc422a, v133
	v_mul_f32_e32 v135, 0xbfb8aa3b, v135
	v_exp_f32_e32 v129, v129
	v_add_f32_e32 v130, 1.0, v130
	v_mul_f32_e32 v133, 0xbfb8aa3b, v133
	v_exp_f32_e32 v135, v135
	v_add_f32_e32 v128, 1.0, v128
	v_rcp_f32_e32 v130, v130
	v_exp_f32_e32 v133, v133
	v_add_f32_e32 v134, 1.0, v134
	v_rcp_f32_e32 v128, v128
	v_add_f32_e32 v132, 1.0, v132
	v_rcp_f32_e32 v134, v134
	v_add_f32_e32 v131, 1.0, v131
	v_rcp_f32_e32 v132, v132
	v_add_f32_e32 v129, 1.0, v129
	v_rcp_f32_e32 v131, v131
	v_add_f32_e32 v135, 1.0, v135
	v_rcp_f32_e32 v129, v129
	v_mul_f32_e32 v130, v125, v130
	v_add_f32_e32 v133, 1.0, v133
	v_rcp_f32_e32 v135, v135
	v_mul_f32_e32 v128, v124, v128
	v_rcp_f32_e32 v133, v133
	v_mul_f32_e32 v134, v127, v134
	v_mul_f32_e32 v130, v130, v130
	v_mul_f32_e32 v132, v126, v132
	v_fmac_f32_e32 v130, v128, v128
	v_mul_f32_e32 v128, v134, v134
	v_mul_f32_e32 v131, v121, v131
	v_fmac_f32_e32 v128, v132, v132
	v_mul_f32_e32 v129, v120, v129
	v_mul_f32_e32 v135, v123, v135
	v_add_f32_e32 v128, v130, v128
	v_mul_f32_e32 v130, v131, v131
	v_mul_f32_e32 v133, v122, v133
	v_fmac_f32_e32 v130, v129, v129
	v_mul_f32_e32 v129, v135, v135
	v_fmac_f32_e32 v129, v133, v133
	v_add_f32_e32 v129, v130, v129
	v_and_b32_e32 v130, 64, v191
	v_add_f32_e32 v129, v128, v129
	v_xor_b32_e32 v128, 16, v191
	v_add_u32_e32 v130, 64, v130
	v_cmp_lt_i32_e32 vcc, v128, v130
	v_add_u32_e32 v173, s70, v195
	v_lshlrev_b32_e32 v168, 5, v173
	v_cndmask_b32_e32 v128, v191, v128, vcc
	v_lshlrev_b32_e32 v128, 2, v128
	ds_bpermute_b32 v131, v128, v129
	v_readlane_b32 s0, v254, 31
	s_waitcnt lgkmcnt(0)
	v_add_f32_e32 v131, v129, v131
	v_xor_b32_e32 v129, 32, v191
	v_cmp_lt_i32_e32 vcc, v129, v130
	s_nop 1
	v_cndmask_b32_e32 v129, v191, v129, vcc
	v_lshlrev_b32_e32 v130, 2, v129
	ds_bpermute_b32 v132, v130, v131
	v_cmp_eq_u32_e32 vcc, 0, v196
	v_add_u32_e32 v129, s0, v168
	s_and_saveexec_b64 s[0:1], vcc
	s_cbranch_execz .LBB0_153
	s_waitcnt lgkmcnt(0)
	v_add_f32_e32 v131, v131, v132
	ds_write_b32 v129, v131

;     template <int TYPE>
;     __device__ __forceinline__ void body(f32x4 (&acc)[2][2][4][2], const Unit& u, int wr, int wc, int fr, int fq) const {
;     ...
;             UNROLL for (int ai = 0; ai < 2; ++ai) UNROLL for (int m = 0; m < 4; ++m) {
;                 const int r = rb + ai * 128 + m * 16;
;                 if (r < MT) {
;                     f32x4 v0 = acc[ai][bj][m][0], v1 = acc[ai][bj][m][1];
;                     if (norm64) { const LAS float* xp = xch + ((ai * 128 + m * 16 + lrow) * 4 + (wc & 2)) * 2 + bj; const float rstd = rsqrtf((xp[0] + xp[2]) * (1.f / 64.f) + EPS); v0 = v0 * rstd * g0; v1 = v1 * rstd * g1; }
;                     if (TYPE == 5) { asm volatile("" : "+v"(v0), "+v"(v1));
;                         UNROLL for (int j = 0; j < 4; ++j) { v0[j] = gelu_f(v0[j]); v1[j] = gelu_f(v1[j]); } }
;                     if (norm128) { const LAS float* xp = xch + ((ai * 128 + m * 16 + lrow) * 4) * 2 + bj; const float rstd = rsqrtf(((xp[0] + xp[2]) + (xp[4] + xp[6])) * (1.f / 128.f) + EPS); v0 = v0 * rstd * g0; v1 = v1 * rstd * g1; }
;                     if (TYPE == 4) { UNROLL for (int j = 0; j < 4; ++j) { v0[j] = gelu_f(v0[j]); v1[j] = gelu_f(v1[j]); } }
;                     if (TYPE == 3 || TYPE == 6) { UNROLL for (int j = 0; j < 4; ++j) { v0[j] = silu_f(v0[j]); v1[j] = silu_f(v1[j]); } }
;                     if (TYPE == 2 && r < MP) {
;                         const bf16x8 av = __builtin_bit_cast(bf16x8, pack8(v0, v1));
;                         const int r16 = r - fr;
;                         bf16_t* vtb = bdst + (size_t)((r16 >> 13) * 8 + (col >> 6)) * (8192 * 64) + (size_t)((r16 & 8191) >> 5) * 2048 + (size_t)(((wc & 1) * 2 + ((r16 >> 4) & 1)) * 512);
;                         UNROLL for (int sel = 0; sel < 2; ++sel) {
;                             bf16x8 bsel; UNROLL for (int e = 0; e < 8; ++e) bsel[e] = (8 * fq + e == 16 * sel + fr) ? (short)0x3F80 : (short)0;
;                             const f32x4 dv = __builtin_amdgcn_mfma_f32_16x16x32_bf16(av, bsel, (f32x4){0.f, 0.f, 0.f, 0.f}, 0, 0, 0);
;                             *(u32x2*)(vtb + (size_t)((16 * sel + fr + 32 * (fq & 1)) * 8 + (fq >> 1) * 4)) = pack4(dv);
;                         }
;                     } else {
;                     const size_t bo = headlay ? (tokhead_idx<(TYPE == 1 || TYPE == 2)>(r, col >> 6) * 64 + (col & 63)) : ((size_t)r * 512 + col);
.LBB0_186:
	s_or_b64 exec, exec, s[2:3]
	s_movk_i32 s0, 0x4070
	v_add_u32_e32 v166, 16, v164
	v_cmp_gt_i32_e64 s[4:5], s0, v164
	v_readlane_b32 s0, v254, 40
	v_ashrrev_i32_e32 v167, 31, v166
	s_nop 0
	v_add_u32_e32 v197, s0, v168
	s_and_saveexec_b64 s[2:3], s[4:5]
	s_cbranch_execz .LBB0_189
	v_mov_b64_e32 v[138:139], v[118:119]
	v_mov_b64_e32 v[142:143], v[114:115]
	v_mov_b64_e32 v[136:137], v[116:117]
	v_mov_b64_e32 v[140:141], v[112:113]
	s_nop 0
	v_mul_f32_e32 v152, 0x3d372713, v136
	v_mul_f32_e32 v152, v136, v152
	v_fma_f32 v152, v136, v152, v136
	v_mul_f32_e32 v152, 0x3fcc422a, v152
	v_mul_f32_e32 v152, 0xbfb8aa3b, v152
	v_exp_f32_e32 v152, v152
	s_nop 0
	v_add_f32_e32 v152, 1.0, v152
	v_rcp_f32_e32 v168, v152
	v_mul_f32_e32 v152, 0x3d372713, v140
	v_mul_f32_e32 v152, v140, v152
	v_fma_f32 v152, v140, v152, v140
	v_mul_f32_e32 v152, 0x3fcc422a, v152
	v_mul_f32_e32 v152, 0xbfb8aa3b, v152
	v_exp_f32_e32 v152, v152
	s_nop 0
	v_add_f32_e32 v152, 1.0, v152
	v_rcp_f32_e32 v170, v152
	v_mul_f32_e32 v152, 0x3d372713, v137
	v_mul_f32_e32 v152, v137, v152
	v_fma_f32 v152, v137, v152, v137
	v_mul_f32_e32 v152, 0x3fcc422a, v152
	v_mul_f32_e32 v152, 0xbfb8aa3b, v152
	v_exp_f32_e32 v152, v152
	s_nop 0
	v_add_f32_e32 v152, 1.0, v152
	v_rcp_f32_e32 v169, v152
	v_mul_f32_e32 v152, 0x3d372713, v141
	v_mul_f32_e32 v152, v141, v152
	v_fma_f32 v152, v141, v152, v141
	v_mul_f32_e32 v152, 0x3fcc422a, v152
	v_mul_f32_e32 v152, 0xbfb8aa3b, v152
	v_exp_f32_e32 v152, v152
	v_pk_mul_f32 v[136:137], v[136:137], v[168:169]
	v_add_f32_e32 v152, 1.0, v152
	v_rcp_f32_e32 v171, v152
	v_mul_f32_e32 v152, 0x3d372713, v138
	v_mul_f32_e32 v152, v138, v152
	v_fma_f32 v152, v138, v152, v138
	v_mul_f32_e32 v152, 0x3fcc422a, v152
	v_mul_f32_e32 v152, 0xbfb8aa3b, v152
	v_exp_f32_e32 v152, v152
	v_pk_mul_f32 v[140:141], v[140:141], v[170:171]
	ds_read2_b32 v[168:169], v197 offset0:128 offset1:130
	ds_read2_b32 v[170:171], v197 offset0:132 offset1:134
	v_add_f32_e32 v152, 1.0, v152
	v_rcp_f32_e32 v174, v152
	v_mul_f32_e32 v152, 0x3d372713, v142
	v_mul_f32_e32 v152, v142, v152
	v_fma_f32 v152, v142, v152, v142
	v_mul_f32_e32 v152, 0x3fcc422a, v152
	v_mul_f32_e32 v152, 0xbfb8aa3b, v152
	v_exp_f32_e32 v152, v152
	s_nop 0
	v_add_f32_e32 v152, 1.0, v152
	v_rcp_f32_e32 v176, v152
	v_mul_f32_e32 v152, 0x3d372713, v139
	v_mul_f32_e32 v152, v139, v152
	v_fma_f32 v152, v139, v152, v139
	v_mul_f32_e32 v152, 0x3fcc422a, v152
	v_mul_f32_e32 v152, 0xbfb8aa3b, v152
	v_exp_f32_e32 v152, v152
	s_nop 0
	v_add_f32_e32 v152, 1.0, v152
	v_rcp_f32_e32 v175, v152
	v_mul_f32_e32 v152, 0x3d372713, v143
	v_mul_f32_e32 v152, v143, v152
	v_fma_f32 v152, v143, v152, v143
	v_mul_f32_e32 v152, 0x3fcc422a, v152
	v_mul_f32_e32 v152, 0xbfb8aa3b, v152
	v_exp_f32_e32 v152, v152
	v_pk_mul_f32 v[138:139], v[138:139], v[174:175]
	s_waitcnt lgkmcnt(0)
	v_mov_b32_e32 v174, v168
	v_mov_b32_e32 v175, v170
	v_mov_b32_e32 v170, v169
	v_add_f32_e32 v152, 1.0, v152
	v_pk_add_f32 v[168:169], v[174:175], v[170:171]
	v_rcp_f32_e32 v177, v152
	v_add_f32_e32 v152, v168, v169
	v_fmamk_f32 v152, v152, 0x3c000000, v190
	v_cmp_gt_f32_e64 s[0:1], s49, v152
	v_mul_f32_e32 v168, 0x4b800000, v152
	v_pk_mul_f32 v[142:143], v[142:143], v[176:177]
	v_cndmask_b32_e64 v152, v152, v168, s[0:1]
	v_rsq_f32_e32 v152, v152
	v_lshlrev_b64 v[174:175], 10, v[166:167]
	v_lshl_add_u64 v[174:175], v[182:183], 0, v[174:175]
	v_mul_f32_e32 v168, 0x45800000, v152
	v_cndmask_b32_e64 v152, v152, v168, s[0:1]
	v_pk_mul_f32 v[136:137], v[152:153], v[136:137] op_sel_hi:[0,1]
	v_pk_mul_f32 v[138:139], v[152:153], v[138:139] op_sel_hi:[0,1]
	v_pk_mul_f32 v[140:141], v[152:153], v[140:141] op_sel_hi:[0,1]
	v_pk_mul_f32 v[142:143], v[152:153], v[142:143] op_sel_hi:[0,1]
	v_pk_mul_f32 v[138:139], v[134:135], v[138:139]
	v_pk_mul_f32 v[136:137], v[132:133], v[136:137]
	v_pk_mul_f32 v[142:143], v[130:131], v[142:143]
	v_pk_mul_f32 v[140:141], v[128:129], v[140:141]
	s_movk_i32 s0, 0x3fef
	v_cvt_pk_bf16_f32 v168, v136, v137
	v_cvt_pk_bf16_f32 v169, v138, v139
	v_cvt_pk_bf16_f32 v170, v140, v141
	v_cvt_pk_bf16_f32 v171, v142, v143
	v_cmp_lt_i32_e64 s[0:1], s0, v164
	global_store_dwordx4 v[174:175], v[168:171], off
	s_and_b64 exec, exec, s[0:1]
	s_cbranch_execz .LBB0_189
	v_add_u32_e32 v152, 0xffffc010, v164
	v_readlane_b32 s0, v254, 43
	v_lshlrev_b64 v[168:169], 11, v[152:153]
	v_readlane_b32 s1, v254, 44
	s_nop 1
	v_lshl_add_u64 v[168:169], s[0:1], 0, v[168:169]
	v_lshl_add_u64 v[168:169], v[162:163], 2, v[168:169]
	global_store_dwordx4 v[168:169], v[136:139], off
	global_store_dwordx4 v[168:169], v[140:143], off offset:16
;     template <int TYPE>
;     __device__ __forceinline__ void body(f32x4 (&acc)[2][2][4][2], const Unit& u, int wr, int wc, int fr, int fq) const {
;     ...
;             UNROLL for (int ai = 0; ai < 2; ++ai) UNROLL for (int m = 0; m < 4; ++m) {
;                 const int r = rb + ai * 128 + m * 16;
;                 if (r < MT) {
;                     f32x4 v0 = acc[ai][bj][m][0], v1 = acc[ai][bj][m][1];
;                     if (norm64) { const LAS float* xp = xch + ((ai * 128 + m * 16 + lrow) * 4 + (wc & 2)) * 2 + bj; const float rstd = rsqrtf((xp[0] + xp[2]) * (1.f / 64.f) + EPS); v0 = v0 * rstd * g0; v1 = v1 * rstd * g1; }
;                     if (TYPE == 5) { asm volatile("" : "+v"(v0), "+v"(v1));
;                         UNROLL for (int j = 0; j < 4; ++j) { v0[j] = gelu_f(v0[j]); v1[j] = gelu_f(v1[j]); } }
;                     if (norm128) { const LAS float* xp = xch + ((ai * 128 + m * 16 + lrow) * 4) * 2 + bj; const float rstd = rsqrtf(((xp[0] + xp[2]) + (xp[4] + xp[6])) * (1.f / 128.f) + EPS); v0 = v0 * rstd * g0; v1 = v1 * rstd * g1; }
;                     if (TYPE == 4) { UNROLL for (int j = 0; j < 4; ++j) { v0[j] = gelu_f(v0[j]); v1[j] = gelu_f(v1[j]); } }
;                     if (TYPE == 3 || TYPE == 6) { UNROLL for (int j = 0; j < 4; ++j) { v0[j] = silu_f(v0[j]); v1[j] = silu_f(v1[j]); } }
;                     if (TYPE == 2 && r < MP) {
;                         const bf16x8 av = __builtin_bit_cast(bf16x8, pack8(v0, v1));
;                         const int r16 = r - fr;
;                         bf16_t* vtb = bdst + (size_t)((r16 >> 13) * 8 + (col >> 6)) * (8192 * 64) + (size_t)((r16 & 8191) >> 5) * 2048 + (size_t)(((wc & 1) * 2 + ((r16 >> 4) & 1)) * 512);
;                         UNROLL for (int sel = 0; sel < 2; ++sel) {
;                             bf16x8 bsel; UNROLL for (int e = 0; e < 8; ++e) bsel[e] = (8 * fq + e == 16 * sel + fr) ? (short)0x3F80 : (short)0;
;                             const f32x4 dv = __builtin_amdgcn_mfma_f32_16x16x32_bf16(av, bsel, (f32x4){0.f, 0.f, 0.f, 0.f}, 0, 0, 0);
;                             *(u32x2*)(vtb + (size_t)((16 * sel + fr + 32 * (fq & 1)) * 8 + (fq >> 1) * 4)) = pack4(dv);
;                         }
;                     } else {
;                     const size_t bo = headlay ? (tokhead_idx<(TYPE == 1 || TYPE == 2)>(r, col >> 6) * 64 + (col & 63)) : ((size_t)r * 512 + col);
.LBB0_189:
	s_or_b64 exec, exec, s[2:3]
	v_add_u32_e32 v168, 32, v164
	s_movk_i32 s0, 0x4060
	v_cmp_gt_i32_e64 s[6:7], s0, v164
	v_ashrrev_i32_e32 v169, 31, v168
	s_and_saveexec_b64 s[2:3], s[6:7]
	s_cbranch_execz .LBB0_192
	v_mov_b64_e32 v[138:139], v[110:111]
	v_mov_b64_e32 v[142:143], v[106:107]
	v_mov_b64_e32 v[136:137], v[108:109]
	v_mov_b64_e32 v[140:141], v[104:105]
	s_nop 0
	v_mul_f32_e32 v152, 0x3d372713, v136
	v_mul_f32_e32 v152, v136, v152
	v_fma_f32 v152, v136, v152, v136
	v_mul_f32_e32 v152, 0x3fcc422a, v152
	v_mul_f32_e32 v152, 0xbfb8aa3b, v152
	v_exp_f32_e32 v152, v152
	s_nop 0
	v_add_f32_e32 v152, 1.0, v152
	v_rcp_f32_e32 v170, v152
	v_mul_f32_e32 v152, 0x3d372713, v140
	v_mul_f32_e32 v152, v140, v152
	v_fma_f32 v152, v140, v152, v140
	v_mul_f32_e32 v152, 0x3fcc422a, v152
	v_mul_f32_e32 v152, 0xbfb8aa3b, v152
	v_exp_f32_e32 v152, v152
	s_nop 0
	v_add_f32_e32 v152, 1.0, v152
	v_rcp_f32_e32 v174, v152
	v_mul_f32_e32 v152, 0x3d372713, v137
	v_mul_f32_e32 v152, v137, v152
	v_fma_f32 v152, v137, v152, v137
	v_mul_f32_e32 v152, 0x3fcc422a, v152
	v_mul_f32_e32 v152, 0xbfb8aa3b, v152
	v_exp_f32_e32 v152, v152
	s_nop 0
	v_add_f32_e32 v152, 1.0, v152
	v_rcp_f32_e32 v171, v152
	v_mul_f32_e32 v152, 0x3d372713, v141
	v_mul_f32_e32 v152, v141, v152
	v_fma_f32 v152, v141, v152, v141
	v_mul_f32_e32 v152, 0x3fcc422a, v152
	v_mul_f32_e32 v152, 0xbfb8aa3b, v152
	v_exp_f32_e32 v152, v152
	v_pk_mul_f32 v[136:137], v[136:137], v[170:171]
	v_add_f32_e32 v152, 1.0, v152
	v_rcp_f32_e32 v175, v152
	v_mul_f32_e32 v152, 0x3d372713, v138
	v_mul_f32_e32 v152, v138, v152
	v_fma_f32 v152, v138, v152, v138
	v_mul_f32_e32 v152, 0x3fcc422a, v152
	v_mul_f32_e32 v152, 0xbfb8aa3b, v152
	v_exp_f32_e32 v152, v152
	v_pk_mul_f32 v[140:141], v[140:141], v[174:175]
	v_add_f32_e32 v152, 1.0, v152
	v_rcp_f32_e32 v176, v152
	v_mul_f32_e32 v152, 0x3d372713, v142
	v_mul_f32_e32 v152, v142, v152
	v_fma_f32 v152, v142, v152, v142
	v_mul_f32_e32 v152, 0x3fcc422a, v152
	v_mul_f32_e32 v152, 0xbfb8aa3b, v152
	v_exp_f32_e32 v152, v152
	s_nop 0
	v_add_f32_e32 v152, 1.0, v152
	v_rcp_f32_e32 v178, v152
	v_mul_f32_e32 v152, 0x3d372713, v139
	v_mul_f32_e32 v152, v139, v152
	v_fma_f32 v152, v139, v152, v139
	v_mul_f32_e32 v152, 0x3fcc422a, v152
	v_mul_f32_e32 v152, 0xbfb8aa3b, v152
	v_exp_f32_e32 v152, v152
	s_nop 0
	v_add_f32_e32 v152, 1.0, v152
	v_rcp_f32_e32 v177, v152
	v_mul_f32_e32 v152, 0x3d372713, v143
	v_mul_f32_e32 v152, v143, v152
	v_fma_f32 v152, v143, v152, v143
	v_mul_f32_e32 v152, 0x3fcc422a, v152
	v_mul_f32_e32 v152, 0xbfb8aa3b, v152
	v_exp_f32_e32 v152, v152
	v_pk_mul_f32 v[138:139], v[138:139], v[176:177]
	v_add_f32_e32 v152, 1.0, v152
	v_rcp_f32_e32 v179, v152
	v_add_u32_e32 v152, 0x400, v197
	ds_read2_b32 v[170:171], v152 offset1:2
	ds_read2_b32 v[174:175], v152 offset0:4 offset1:6
	v_pk_mul_f32 v[142:143], v[142:143], v[178:179]
	s_waitcnt lgkmcnt(0)
	v_mov_b32_e32 v176, v170
	v_mov_b32_e32 v177, v174
	v_mov_b32_e32 v174, v171
	v_pk_add_f32 v[170:171], v[176:177], v[174:175]
	s_nop 0
	v_add_f32_e32 v152, v170, v171
	v_fmamk_f32 v152, v152, 0x3c000000, v190
	v_cmp_gt_f32_e64 s[0:1], s49, v152
	v_mul_f32_e32 v170, 0x4b800000, v152
	s_nop 0
	v_cndmask_b32_e64 v152, v152, v170, s[0:1]
	v_rsq_f32_e32 v152, v152
	s_nop 0
	v_mul_f32_e32 v170, 0x45800000, v152
	v_cndmask_b32_e64 v152, v152, v170, s[0:1]
	v_pk_mul_f32 v[136:137], v[152:153], v[136:137] op_sel_hi:[0,1]
	v_pk_mul_f32 v[138:139], v[152:153], v[138:139] op_sel_hi:[0,1]
	v_pk_mul_f32 v[140:141], v[152:153], v[140:141] op_sel_hi:[0,1]
	v_pk_mul_f32 v[142:143], v[152:153], v[142:143] op_sel_hi:[0,1]
	v_pk_mul_f32 v[138:139], v[134:135], v[138:139]
	v_pk_mul_f32 v[136:137], v[132:133], v[136:137]
	v_pk_mul_f32 v[142:143], v[130:131], v[142:143]
	v_pk_mul_f32 v[140:141], v[128:129], v[140:141]
	v_lshlrev_b64 v[170:171], 10, v[168:169]
	s_movk_i32 s0, 0x3fdf
	v_cvt_pk_bf16_f32 v174, v136, v137
	v_cvt_pk_bf16_f32 v175, v138, v139
	v_cvt_pk_bf16_f32 v176, v140, v141
	v_cvt_pk_bf16_f32 v177, v142, v143
	v_lshl_add_u64 v[170:171], v[182:183], 0, v[170:171]
	v_cmp_lt_i32_e64 s[0:1], s0, v164
	global_store_dwordx4 v[170:171], v[174:177], off
	s_and_b64 exec, exec, s[0:1]
	s_cbranch_execz .LBB0_192
	v_add_u32_e32 v152, 0xffffc020, v164
	v_readlane_b32 s0, v254, 43
	v_lshlrev_b64 v[170:171], 11, v[152:153]
	v_readlane_b32 s1, v254, 44
	s_nop 1
	v_lshl_add_u64 v[170:171], s[0:1], 0, v[170:171]
	v_lshl_add_u64 v[170:171], v[162:163], 2, v[170:171]
	global_store_dwordx4 v[170:171], v[136:139], off
	global_store_dwordx4 v[170:171], v[140:143], off offset:16
;     template <int TYPE>
;     __device__ __forceinline__ void body(f32x4 (&acc)[2][2][4][2], const Unit& u, int wr, int wc, int fr, int fq) const {
;     ...
;             UNROLL for (int ai = 0; ai < 2; ++ai) UNROLL for (int m = 0; m < 4; ++m) {
;                 const int r = rb + ai * 128 + m * 16;
;                 if (r < MT) {
;                     f32x4 v0 = acc[ai][bj][m][0], v1 = acc[ai][bj][m][1];
;                     if (norm64) { const LAS float* xp = xch + ((ai * 128 + m * 16 + lrow) * 4 + (wc & 2)) * 2 + bj; const float rstd = rsqrtf((xp[0] + xp[2]) * (1.f / 64.f) + EPS); v0 = v0 * rstd * g0; v1 = v1 * rstd * g1; }
;                     if (TYPE == 5) { asm volatile("" : "+v"(v0), "+v"(v1));
;                         UNROLL for (int j = 0; j < 4; ++j) { v0[j] = gelu_f(v0[j]); v1[j] = gelu_f(v1[j]); } }
;                     if (norm128) { const LAS float* xp = xch + ((ai * 128 + m * 16 + lrow) * 4) * 2 + bj; const float rstd = rsqrtf(((xp[0] + xp[2]) + (xp[4] + xp[6])) * (1.f / 128.f) + EPS); v0 = v0 * rstd * g0; v1 = v1 * rstd * g1; }
;                     if (TYPE == 4) { UNROLL for (int j = 0; j < 4; ++j) { v0[j] = gelu_f(v0[j]); v1[j] = gelu_f(v1[j]); } }
;                     if (TYPE == 3 || TYPE == 6) { UNROLL for (int j = 0; j < 4; ++j) { v0[j] = silu_f(v0[j]); v1[j] = silu_f(v1[j]); } }
;                     if (TYPE == 2 && r < MP) {
;                         const bf16x8 av = __builtin_bit_cast(bf16x8, pack8(v0, v1));
;                         const int r16 = r - fr;
;                         bf16_t* vtb = bdst + (size_t)((r16 >> 13) * 8 + (col >> 6)) * (8192 * 64) + (size_t)((r16 & 8191) >> 5) * 2048 + (size_t)(((wc & 1) * 2 + ((r16 >> 4) & 1)) * 512);
;                         UNROLL for (int sel = 0; sel < 2; ++sel) {
;                             bf16x8 bsel; UNROLL for (int e = 0; e < 8; ++e) bsel[e] = (8 * fq + e == 16 * sel + fr) ? (short)0x3F80 : (short)0;
;                             const f32x4 dv = __builtin_amdgcn_mfma_f32_16x16x32_bf16(av, bsel, (f32x4){0.f, 0.f, 0.f, 0.f}, 0, 0, 0);
;                             *(u32x2*)(vtb + (size_t)((16 * sel + fr + 32 * (fq & 1)) * 8 + (fq >> 1) * 4)) = pack4(dv);
;                         }
;                     } else {
;                     const size_t bo = headlay ? (tokhead_idx<(TYPE == 1 || TYPE == 2)>(r, col >> 6) * 64 + (col & 63)) : ((size_t)r * 512 + col);
.LBB0_192:
	s_or_b64 exec, exec, s[2:3]
	v_add_u32_e32 v170, 48, v164
	s_movk_i32 s0, 0x4050
	v_cmp_gt_i32_e64 s[8:9], s0, v164
	v_ashrrev_i32_e32 v171, 31, v170
	s_and_saveexec_b64 s[2:3], s[8:9]
	s_cbranch_execz .LBB0_195
	v_mov_b64_e32 v[138:139], v[98:99]
	v_mov_b64_e32 v[142:143], v[102:103]
	v_mov_b64_e32 v[136:137], v[96:97]
	v_mov_b64_e32 v[140:141], v[100:101]
	s_nop 0
	v_mul_f32_e32 v152, 0x3d372713, v140
	v_mul_f32_e32 v152, v140, v152
	v_fma_f32 v152, v140, v152, v140
	v_mul_f32_e32 v152, 0x3fcc422a, v152
	v_mul_f32_e32 v152, 0xbfb8aa3b, v152
	v_exp_f32_e32 v152, v152
	s_nop 0
	v_add_f32_e32 v152, 1.0, v152
	v_rcp_f32_e32 v174, v152
	v_mul_f32_e32 v152, 0x3d372713, v136
	v_mul_f32_e32 v152, v136, v152
	v_fma_f32 v152, v136, v152, v136
	v_mul_f32_e32 v152, 0x3fcc422a, v152
	v_mul_f32_e32 v152, 0xbfb8aa3b, v152
	v_exp_f32_e32 v152, v152
	s_nop 0
	v_add_f32_e32 v152, 1.0, v152
	v_rcp_f32_e32 v176, v152
	v_mul_f32_e32 v152, 0x3d372713, v141
	v_mul_f32_e32 v152, v141, v152
	v_fma_f32 v152, v141, v152, v141
	v_mul_f32_e32 v152, 0x3fcc422a, v152
	v_mul_f32_e32 v152, 0xbfb8aa3b, v152
	v_exp_f32_e32 v152, v152
	s_nop 0
	v_add_f32_e32 v152, 1.0, v152
	v_rcp_f32_e32 v175, v152
	v_mul_f32_e32 v152, 0x3d372713, v137
	v_mul_f32_e32 v152, v137, v152
	v_fma_f32 v152, v137, v152, v137
	v_mul_f32_e32 v152, 0x3fcc422a, v152
	v_mul_f32_e32 v152, 0xbfb8aa3b, v152
	v_exp_f32_e32 v152, v152
	v_pk_mul_f32 v[140:141], v[140:141], v[174:175]
	v_add_f32_e32 v152, 1.0, v152
	v_rcp_f32_e32 v177, v152
	v_mul_f32_e32 v152, 0x3d372713, v142
	v_mul_f32_e32 v152, v142, v152
	v_fma_f32 v152, v142, v152, v142
	v_mul_f32_e32 v152, 0x3fcc422a, v152
	v_mul_f32_e32 v152, 0xbfb8aa3b, v152
	v_exp_f32_e32 v152, v152
	v_pk_mul_f32 v[176:177], v[136:137], v[176:177]
	v_add_f32_e32 v152, 1.0, v152
	v_rcp_f32_e32 v178, v152
	v_mul_f32_e32 v152, 0x3d372713, v138
	v_mul_f32_e32 v152, v138, v152
	v_fma_f32 v152, v138, v152, v138
	v_mul_f32_e32 v152, 0x3fcc422a, v152
	v_mul_f32_e32 v152, 0xbfb8aa3b, v152
	v_exp_f32_e32 v152, v152
	s_nop 0
	v_add_f32_e32 v152, 1.0, v152
	v_rcp_f32_e32 v200, v152
	v_mul_f32_e32 v152, 0x3d372713, v143
	v_mul_f32_e32 v152, v143, v152
	v_fma_f32 v152, v143, v152, v143
	v_mul_f32_e32 v152, 0x3fcc422a, v152
	v_mul_f32_e32 v152, 0xbfb8aa3b, v152
	v_exp_f32_e32 v152, v152
	s_nop 0
	v_add_f32_e32 v152, 1.0, v152
	v_rcp_f32_e32 v179, v152
	v_mul_f32_e32 v152, 0x3d372713, v139
	v_mul_f32_e32 v152, v139, v152
	v_fma_f32 v152, v139, v152, v139
	v_mul_f32_e32 v152, 0x3fcc422a, v152
	v_mul_f32_e32 v152, 0xbfb8aa3b, v152
	v_exp_f32_e32 v152, v152
	v_pk_mul_f32 v[142:143], v[142:143], v[178:179]
	v_add_f32_e32 v152, 1.0, v152
	v_rcp_f32_e32 v201, v152
	s_nop 0
	v_pk_mul_f32 v[174:175], v[138:139], v[200:201]
	v_add_u32_e32 v138, 0x400, v197
	ds_read2_b32 v[136:137], v138 offset0:128 offset1:130
	ds_read2_b32 v[138:139], v138 offset0:132 offset1:134
	s_waitcnt lgkmcnt(0)
	v_mov_b32_e32 v178, v136
	v_mov_b32_e32 v179, v138
	v_mov_b32_e32 v138, v137
	v_pk_add_f32 v[136:137], v[178:179], v[138:139]
	v_lshlrev_b64 v[178:179], 10, v[170:171]
	v_add_f32_e32 v136, v136, v137
	v_fmamk_f32 v136, v136, 0x3c000000, v190
	v_cmp_gt_f32_e64 s[0:1], s49, v136
	v_mul_f32_e32 v137, 0x4b800000, v136
	v_lshl_add_u64 v[178:179], v[182:183], 0, v[178:179]
	v_cndmask_b32_e64 v136, v136, v137, s[0:1]
	v_rsq_f32_e32 v136, v136
	s_nop 0
	v_mul_f32_e32 v137, 0x45800000, v136
	v_cndmask_b32_e64 v152, v136, v137, s[0:1]
	v_pk_mul_f32 v[136:137], v[152:153], v[140:141] op_sel_hi:[0,1]
	v_pk_mul_f32 v[138:139], v[152:153], v[142:143] op_sel_hi:[0,1]
	v_pk_mul_f32 v[140:141], v[152:153], v[176:177] op_sel_hi:[0,1]
	v_pk_mul_f32 v[142:143], v[152:153], v[174:175] op_sel_hi:[0,1]
	v_pk_mul_f32 v[138:139], v[134:135], v[138:139]
	v_pk_mul_f32 v[136:137], v[132:133], v[136:137]
	v_pk_mul_f32 v[142:143], v[130:131], v[142:143]
	v_pk_mul_f32 v[140:141], v[128:129], v[140:141]
	s_movk_i32 s0, 0x3fcf
	v_cvt_pk_bf16_f32 v174, v136, v137
	v_cvt_pk_bf16_f32 v175, v138, v139
	v_cvt_pk_bf16_f32 v176, v140, v141
	v_cvt_pk_bf16_f32 v177, v142, v143
	v_cmp_lt_i32_e64 s[0:1], s0, v164
	global_store_dwordx4 v[178:179], v[174:177], off
	s_and_b64 exec, exec, s[0:1]
	s_cbranch_execz .LBB0_195
	v_add_u32_e32 v152, 0xffffc030, v164
	v_readlane_b32 s0, v254, 43
	v_lshlrev_b64 v[174:175], 11, v[152:153]
	v_readlane_b32 s1, v254, 44
	s_nop 1
	v_lshl_add_u64 v[174:175], s[0:1], 0, v[174:175]
	v_lshl_add_u64 v[174:175], v[162:163], 2, v[174:175]
	global_store_dwordx4 v[174:175], v[136:139], off
	global_store_dwordx4 v[174:175], v[140:143], off offset:16
;     template <int TYPE>
;     __device__ __forceinline__ void body(f32x4 (&acc)[2][2][4][2], const Unit& u, int wr, int wc, int fr, int fq) const {
;     ...
;             UNROLL for (int ai = 0; ai < 2; ++ai) UNROLL for (int m = 0; m < 4; ++m) {
;                 const int r = rb + ai * 128 + m * 16;
;                 if (r < MT) {
;                     f32x4 v0 = acc[ai][bj][m][0], v1 = acc[ai][bj][m][1];
;                     if (norm64) { const LAS float* xp = xch + ((ai * 128 + m * 16 + lrow) * 4 + (wc & 2)) * 2 + bj; const float rstd = rsqrtf((xp[0] + xp[2]) * (1.f / 64.f) + EPS); v0 = v0 * rstd * g0; v1 = v1 * rstd * g1; }
;                     if (TYPE == 5) { asm volatile("" : "+v"(v0), "+v"(v1));
;                         UNROLL for (int j = 0; j < 4; ++j) { v0[j] = gelu_f(v0[j]); v1[j] = gelu_f(v1[j]); } }
;                     if (norm128) { const LAS float* xp = xch + ((ai * 128 + m * 16 + lrow) * 4) * 2 + bj; const float rstd = rsqrtf(((xp[0] + xp[2]) + (xp[4] + xp[6])) * (1.f / 128.f) + EPS); v0 = v0 * rstd * g0; v1 = v1 * rstd * g1; }
;                     if (TYPE == 4) { UNROLL for (int j = 0; j < 4; ++j) { v0[j] = gelu_f(v0[j]); v1[j] = gelu_f(v1[j]); } }
;                     if (TYPE == 3 || TYPE == 6) { UNROLL for (int j = 0; j < 4; ++j) { v0[j] = silu_f(v0[j]); v1[j] = silu_f(v1[j]); } }
;                     if (TYPE == 2 && r < MP) {
;                         const bf16x8 av = __builtin_bit_cast(bf16x8, pack8(v0, v1));
;                         const int r16 = r - fr;
;                         bf16_t* vtb = bdst + (size_t)((r16 >> 13) * 8 + (col >> 6)) * (8192 * 64) + (size_t)((r16 & 8191) >> 5) * 2048 + (size_t)(((wc & 1) * 2 + ((r16 >> 4) & 1)) * 512);
;                         UNROLL for (int sel = 0; sel < 2; ++sel) {
;                             bf16x8 bsel; UNROLL for (int e = 0; e < 8; ++e) bsel[e] = (8 * fq + e == 16 * sel + fr) ? (short)0x3F80 : (short)0;
;                             const f32x4 dv = __builtin_amdgcn_mfma_f32_16x16x32_bf16(av, bsel, (f32x4){0.f, 0.f, 0.f, 0.f}, 0, 0, 0);
;                             *(u32x2*)(vtb + (size_t)((16 * sel + fr + 32 * (fq & 1)) * 8 + (fq >> 1) * 4)) = pack4(dv);
;                         }
;                     } else {
;                     const size_t bo = headlay ? (tokhead_idx<(TYPE == 1 || TYPE == 2)>(r, col >> 6) * 64 + (col & 63)) : ((size_t)r * 512 + col);
.LBB0_195:
	s_or_b64 exec, exec, s[2:3]
	v_add_u32_e32 v172, 0x80, v164
	v_add_u32_e32 v198, 0x80, v173
	v_cmp_gt_i32_e64 s[10:11], s43, v164
	v_ashrrev_i32_e32 v173, 31, v172
	s_and_saveexec_b64 s[2:3], s[10:11]
	s_cbranch_execz .LBB0_198
	v_mov_b64_e32 v[138:139], v[94:95]
	v_mov_b64_e32 v[142:143], v[90:91]
	v_mov_b64_e32 v[136:137], v[92:93]
	v_mov_b64_e32 v[140:141], v[88:89]
	s_nop 0
	v_mul_f32_e32 v152, 0x3d372713, v136
	v_mul_f32_e32 v152, v136, v152
	v_fma_f32 v152, v136, v152, v136
	v_mul_f32_e32 v152, 0x3fcc422a, v152
	v_mul_f32_e32 v152, 0xbfb8aa3b, v152
	v_exp_f32_e32 v152, v152
	s_nop 0
	v_add_f32_e32 v152, 1.0, v152
	v_rcp_f32_e32 v174, v152
	v_mul_f32_e32 v152, 0x3d372713, v140
	v_mul_f32_e32 v152, v140, v152
	v_fma_f32 v152, v140, v152, v140
	v_mul_f32_e32 v152, 0x3fcc422a, v152
	v_mul_f32_e32 v152, 0xbfb8aa3b, v152
	v_exp_f32_e32 v152, v152
	s_nop 0
	v_add_f32_e32 v152, 1.0, v152
	v_rcp_f32_e32 v176, v152
	v_mul_f32_e32 v152, 0x3d372713, v137
	v_mul_f32_e32 v152, v137, v152
	v_fma_f32 v152, v137, v152, v137
	v_mul_f32_e32 v152, 0x3fcc422a, v152
	v_mul_f32_e32 v152, 0xbfb8aa3b, v152
	v_exp_f32_e32 v152, v152
	s_nop 0
	v_add_f32_e32 v152, 1.0, v152
	v_rcp_f32_e32 v175, v152
	v_mul_f32_e32 v152, 0x3d372713, v141
	v_mul_f32_e32 v152, v141, v152
	v_fma_f32 v152, v141, v152, v141
	v_mul_f32_e32 v152, 0x3fcc422a, v152
	v_mul_f32_e32 v152, 0xbfb8aa3b, v152
	v_exp_f32_e32 v152, v152
	v_pk_mul_f32 v[136:137], v[136:137], v[174:175]
	v_add_f32_e32 v152, 1.0, v152
	v_rcp_f32_e32 v177, v152
	v_mul_f32_e32 v152, 0x3d372713, v138
	v_mul_f32_e32 v152, v138, v152
	v_fma_f32 v152, v138, v152, v138
	v_mul_f32_e32 v152, 0x3fcc422a, v152
	v_mul_f32_e32 v152, 0xbfb8aa3b, v152
	v_exp_f32_e32 v152, v152
	v_pk_mul_f32 v[140:141], v[140:141], v[176:177]
	v_add_f32_e32 v152, 1.0, v152
	v_rcp_f32_e32 v178, v152
	v_mul_f32_e32 v152, 0x3d372713, v142
	v_mul_f32_e32 v152, v142, v152
	v_fma_f32 v152, v142, v152, v142
	v_mul_f32_e32 v152, 0x3fcc422a, v152
	v_mul_f32_e32 v152, 0xbfb8aa3b, v152
	v_exp_f32_e32 v152, v152
	s_nop 0
	v_add_f32_e32 v152, 1.0, v152
	v_rcp_f32_e32 v200, v152
	v_mul_f32_e32 v152, 0x3d372713, v139
	v_mul_f32_e32 v152, v139, v152
	v_fma_f32 v152, v139, v152, v139
	v_mul_f32_e32 v152, 0x3fcc422a, v152
	v_mul_f32_e32 v152, 0xbfb8aa3b, v152
	v_exp_f32_e32 v152, v152
	s_nop 0
	v_add_f32_e32 v152, 1.0, v152
	v_rcp_f32_e32 v179, v152
	v_mul_f32_e32 v152, 0x3d372713, v143
	v_mul_f32_e32 v152, v143, v152
	v_fma_f32 v152, v143, v152, v143
	v_mul_f32_e32 v152, 0x3fcc422a, v152
	v_mul_f32_e32 v152, 0xbfb8aa3b, v152
	v_exp_f32_e32 v152, v152
	v_pk_mul_f32 v[138:139], v[138:139], v[178:179]
	v_add_f32_e32 v152, 1.0, v152
	v_rcp_f32_e32 v201, v152
	v_lshl_add_u32 v152, v198, 5, 0
	v_add_u32_e32 v152, 0x20000, v152
	ds_read2_b32 v[174:175], v152 offset1:2
	ds_read2_b32 v[176:177], v152 offset0:4 offset1:6
	v_pk_mul_f32 v[142:143], v[142:143], v[200:201]
	s_waitcnt lgkmcnt(0)
	v_mov_b32_e32 v178, v174
	v_mov_b32_e32 v179, v176
	v_mov_b32_e32 v176, v175
	v_pk_add_f32 v[174:175], v[178:179], v[176:177]
	v_lshlrev_b64 v[178:179], 10, v[172:173]
	v_add_f32_e32 v152, v174, v175
	v_fmamk_f32 v152, v152, 0x3c000000, v190
	v_cmp_gt_f32_e64 s[0:1], s49, v152
	v_mul_f32_e32 v174, 0x4b800000, v152
	v_lshl_add_u64 v[178:179], v[182:183], 0, v[178:179]
	v_cndmask_b32_e64 v152, v152, v174, s[0:1]
	v_rsq_f32_e32 v152, v152
	s_nop 0
	v_mul_f32_e32 v174, 0x45800000, v152
	v_cndmask_b32_e64 v152, v152, v174, s[0:1]
	v_pk_mul_f32 v[136:137], v[152:153], v[136:137] op_sel_hi:[0,1]
	v_pk_mul_f32 v[138:139], v[152:153], v[138:139] op_sel_hi:[0,1]
	v_pk_mul_f32 v[140:141], v[152:153], v[140:141] op_sel_hi:[0,1]
	v_pk_mul_f32 v[142:143], v[152:153], v[142:143] op_sel_hi:[0,1]
	v_pk_mul_f32 v[138:139], v[134:135], v[138:139]
	v_pk_mul_f32 v[136:137], v[132:133], v[136:137]
	v_pk_mul_f32 v[142:143], v[130:131], v[142:143]
	v_pk_mul_f32 v[140:141], v[128:129], v[140:141]
	v_cvt_pk_bf16_f32 v174, v136, v137
	v_cvt_pk_bf16_f32 v175, v138, v139
	v_cvt_pk_bf16_f32 v176, v140, v141
	v_cvt_pk_bf16_f32 v177, v142, v143
	v_cmp_lt_i32_e64 s[0:1], s33, v164
	global_store_dwordx4 v[178:179], v[174:177], off
	s_and_b64 exec, exec, s[0:1]
	s_cbranch_execz .LBB0_198
	v_add_u32_e32 v152, 0xffffc080, v164
	v_readlane_b32 s0, v254, 43
	v_lshlrev_b64 v[174:175], 11, v[152:153]
	v_readlane_b32 s1, v254, 44
	s_nop 1
	v_lshl_add_u64 v[174:175], s[0:1], 0, v[174:175]
	v_lshl_add_u64 v[174:175], v[162:163], 2, v[174:175]
	global_store_dwordx4 v[174:175], v[136:139], off
	global_store_dwordx4 v[174:175], v[140:143], off offset:16
;     template <int TYPE>
;     __device__ __forceinline__ void body(f32x4 (&acc)[2][2][4][2], const Unit& u, int wr, int wc, int fr, int fq) const {
;     ...
;             UNROLL for (int ai = 0; ai < 2; ++ai) UNROLL for (int m = 0; m < 4; ++m) {
;                 const int r = rb + ai * 128 + m * 16;
;                 if (r < MT) {
;                     f32x4 v0 = acc[ai][bj][m][0], v1 = acc[ai][bj][m][1];
;                     if (norm64) { const LAS float* xp = xch + ((ai * 128 + m * 16 + lrow) * 4 + (wc & 2)) * 2 + bj; const float rstd = rsqrtf((xp[0] + xp[2]) * (1.f / 64.f) + EPS); v0 = v0 * rstd * g0; v1 = v1 * rstd * g1; }
;                     if (TYPE == 5) { asm volatile("" : "+v"(v0), "+v"(v1));
;                         UNROLL for (int j = 0; j < 4; ++j) { v0[j] = gelu_f(v0[j]); v1[j] = gelu_f(v1[j]); } }
;                     if (norm128) { const LAS float* xp = xch + ((ai * 128 + m * 16 + lrow) * 4) * 2 + bj; const float rstd = rsqrtf(((xp[0] + xp[2]) + (xp[4] + xp[6])) * (1.f / 128.f) + EPS); v0 = v0 * rstd * g0; v1 = v1 * rstd * g1; }
;                     if (TYPE == 4) { UNROLL for (int j = 0; j < 4; ++j) { v0[j] = gelu_f(v0[j]); v1[j] = gelu_f(v1[j]); } }
;                     if (TYPE == 3 || TYPE == 6) { UNROLL for (int j = 0; j < 4; ++j) { v0[j] = silu_f(v0[j]); v1[j] = silu_f(v1[j]); } }
;                     if (TYPE == 2 && r < MP) {
;                         const bf16x8 av = __builtin_bit_cast(bf16x8, pack8(v0, v1));
;                         const int r16 = r - fr;
;                         bf16_t* vtb = bdst + (size_t)((r16 >> 13) * 8 + (col >> 6)) * (8192 * 64) + (size_t)((r16 & 8191) >> 5) * 2048 + (size_t)(((wc & 1) * 2 + ((r16 >> 4) & 1)) * 512);
;                         UNROLL for (int sel = 0; sel < 2; ++sel) {
;                             bf16x8 bsel; UNROLL for (int e = 0; e < 8; ++e) bsel[e] = (8 * fq + e == 16 * sel + fr) ? (short)0x3F80 : (short)0;
;                             const f32x4 dv = __builtin_amdgcn_mfma_f32_16x16x32_bf16(av, bsel, (f32x4){0.f, 0.f, 0.f, 0.f}, 0, 0, 0);
;                             *(u32x2*)(vtb + (size_t)((16 * sel + fr + 32 * (fq & 1)) * 8 + (fq >> 1) * 4)) = pack4(dv);
;                         }
;                     } else {
;                     const size_t bo = headlay ? (tokhead_idx<(TYPE == 1 || TYPE == 2)>(r, col >> 6) * 64 + (col & 63)) : ((size_t)r * 512 + col);
.LBB0_198:
	s_or_b64 exec, exec, s[2:3]
	v_add_u32_e32 v174, 0x90, v164
	s_movk_i32 s0, 0x3ff0
	v_cmp_gt_i32_e64 s[12:13], s0, v164
	v_ashrrev_i32_e32 v175, 31, v174
	s_and_saveexec_b64 s[2:3], s[12:13]
	s_cbranch_execz .LBB0_201
	v_mov_b64_e32 v[138:139], v[82:83]
	v_mov_b64_e32 v[142:143], v[86:87]
	v_mov_b64_e32 v[136:137], v[80:81]
	v_mov_b64_e32 v[140:141], v[84:85]
	s_nop 0
	v_mul_f32_e32 v152, 0x3d372713, v140
	v_mul_f32_e32 v152, v140, v152
	v_fma_f32 v152, v140, v152, v140
	v_mul_f32_e32 v152, 0x3fcc422a, v152
	v_mul_f32_e32 v152, 0xbfb8aa3b, v152
	v_exp_f32_e32 v152, v152
	s_nop 0
	v_add_f32_e32 v152, 1.0, v152
	v_rcp_f32_e32 v176, v152
	v_mul_f32_e32 v152, 0x3d372713, v136
	v_mul_f32_e32 v152, v136, v152
	v_fma_f32 v152, v136, v152, v136
	v_mul_f32_e32 v152, 0x3fcc422a, v152
	v_mul_f32_e32 v152, 0xbfb8aa3b, v152
	v_exp_f32_e32 v152, v152
	s_nop 0
	v_add_f32_e32 v152, 1.0, v152
	v_rcp_f32_e32 v178, v152
	v_mul_f32_e32 v152, 0x3d372713, v141
	v_mul_f32_e32 v152, v141, v152
	v_fma_f32 v152, v141, v152, v141
	v_mul_f32_e32 v152, 0x3fcc422a, v152
	v_mul_f32_e32 v152, 0xbfb8aa3b, v152
	v_exp_f32_e32 v152, v152
	s_nop 0
	v_add_f32_e32 v152, 1.0, v152
	v_rcp_f32_e32 v177, v152
	v_mul_f32_e32 v152, 0x3d372713, v137
	v_mul_f32_e32 v152, v137, v152
	v_fma_f32 v152, v137, v152, v137
	v_mul_f32_e32 v152, 0x3fcc422a, v152
	v_mul_f32_e32 v152, 0xbfb8aa3b, v152
	v_exp_f32_e32 v152, v152
	v_pk_mul_f32 v[140:141], v[140:141], v[176:177]
	v_add_f32_e32 v152, 1.0, v152
	v_rcp_f32_e32 v179, v152
	v_mul_f32_e32 v152, 0x3d372713, v142
	v_mul_f32_e32 v152, v142, v152
	v_fma_f32 v152, v142, v152, v142
	v_mul_f32_e32 v152, 0x3fcc422a, v152
	v_mul_f32_e32 v152, 0xbfb8aa3b, v152
	v_exp_f32_e32 v152, v152
	v_pk_mul_f32 v[178:179], v[136:137], v[178:179]
	v_add_f32_e32 v152, 1.0, v152
	v_rcp_f32_e32 v200, v152
	v_mul_f32_e32 v152, 0x3d372713, v138
	v_mul_f32_e32 v152, v138, v152
	v_fma_f32 v152, v138, v152, v138
	v_mul_f32_e32 v152, 0x3fcc422a, v152
	v_mul_f32_e32 v152, 0xbfb8aa3b, v152
	v_exp_f32_e32 v152, v152
	s_nop 0
	v_add_f32_e32 v152, 1.0, v152
	v_rcp_f32_e32 v202, v152
	v_mul_f32_e32 v152, 0x3d372713, v143
	v_mul_f32_e32 v152, v143, v152
	v_fma_f32 v152, v143, v152, v143
	v_mul_f32_e32 v152, 0x3fcc422a, v152
	v_mul_f32_e32 v152, 0xbfb8aa3b, v152
	v_exp_f32_e32 v152, v152
	s_nop 0
	v_add_f32_e32 v152, 1.0, v152
	v_rcp_f32_e32 v201, v152
	v_mul_f32_e32 v152, 0x3d372713, v139
	v_mul_f32_e32 v152, v139, v152
	v_fma_f32 v152, v139, v152, v139
	v_mul_f32_e32 v152, 0x3fcc422a, v152
	v_mul_f32_e32 v152, 0xbfb8aa3b, v152
	v_exp_f32_e32 v152, v152
	v_pk_mul_f32 v[142:143], v[142:143], v[200:201]
	v_add_f32_e32 v152, 1.0, v152
	v_rcp_f32_e32 v203, v152
	s_nop 0
	v_pk_mul_f32 v[176:177], v[138:139], v[202:203]
	v_add_u32_e32 v138, 0x1000, v197
	ds_read2_b32 v[136:137], v138 offset0:128 offset1:130
	ds_read2_b32 v[138:139], v138 offset0:132 offset1:134
	s_waitcnt lgkmcnt(0)
	v_mov_b32_e32 v200, v136
	v_mov_b32_e32 v201, v138
	v_mov_b32_e32 v138, v137
	v_pk_add_f32 v[136:137], v[200:201], v[138:139]
	v_lshlrev_b64 v[200:201], 10, v[174:175]
	v_add_f32_e32 v136, v136, v137
	v_fmamk_f32 v136, v136, 0x3c000000, v190
	v_cmp_gt_f32_e64 s[0:1], s49, v136
	v_mul_f32_e32 v137, 0x4b800000, v136
	v_lshl_add_u64 v[200:201], v[182:183], 0, v[200:201]
	v_cndmask_b32_e64 v136, v136, v137, s[0:1]
	v_rsq_f32_e32 v136, v136
	s_nop 0
	v_mul_f32_e32 v137, 0x45800000, v136
	v_cndmask_b32_e64 v152, v136, v137, s[0:1]
	v_pk_mul_f32 v[136:137], v[152:153], v[140:141] op_sel_hi:[0,1]
	v_pk_mul_f32 v[138:139], v[152:153], v[142:143] op_sel_hi:[0,1]
	v_pk_mul_f32 v[140:141], v[152:153], v[178:179] op_sel_hi:[0,1]
	v_pk_mul_f32 v[142:143], v[152:153], v[176:177] op_sel_hi:[0,1]
	v_pk_mul_f32 v[138:139], v[134:135], v[138:139]
	v_pk_mul_f32 v[136:137], v[132:133], v[136:137]
	v_pk_mul_f32 v[142:143], v[130:131], v[142:143]
	v_pk_mul_f32 v[140:141], v[128:129], v[140:141]
	s_movk_i32 s0, 0x3f6f
	v_cvt_pk_bf16_f32 v176, v136, v137
	v_cvt_pk_bf16_f32 v177, v138, v139
	v_cvt_pk_bf16_f32 v178, v140, v141
	v_cvt_pk_bf16_f32 v179, v142, v143
	v_cmp_lt_i32_e64 s[0:1], s0, v164
	global_store_dwordx4 v[200:201], v[176:179], off
	s_and_b64 exec, exec, s[0:1]
	s_cbranch_execz .LBB0_201
	v_add_u32_e32 v152, 0xffffc090, v164
	v_readlane_b32 s0, v254, 43
	v_lshlrev_b64 v[176:177], 11, v[152:153]
	v_readlane_b32 s1, v254, 44
	s_nop 1
	v_lshl_add_u64 v[176:177], s[0:1], 0, v[176:177]
	v_lshl_add_u64 v[176:177], v[162:163], 2, v[176:177]
	global_store_dwordx4 v[176:177], v[136:139], off
	global_store_dwordx4 v[176:177], v[140:143], off offset:16
;     template <int TYPE>
;     __device__ __forceinline__ void body(f32x4 (&acc)[2][2][4][2], const Unit& u, int wr, int wc, int fr, int fq) const {
;     ...
;             UNROLL for (int ai = 0; ai < 2; ++ai) UNROLL for (int m = 0; m < 4; ++m) {
;                 const int r = rb + ai * 128 + m * 16;
;                 if (r < MT) {
;                     f32x4 v0 = acc[ai][bj][m][0], v1 = acc[ai][bj][m][1];
;                     if (norm64) { const LAS float* xp = xch + ((ai * 128 + m * 16 + lrow) * 4 + (wc & 2)) * 2 + bj; const float rstd = rsqrtf((xp[0] + xp[2]) * (1.f / 64.f) + EPS); v0 = v0 * rstd * g0; v1 = v1 * rstd * g1; }
;                     if (TYPE == 5) { asm volatile("" : "+v"(v0), "+v"(v1));
;                         UNROLL for (int j = 0; j < 4; ++j) { v0[j] = gelu_f(v0[j]); v1[j] = gelu_f(v1[j]); } }
;                     if (norm128) { const LAS float* xp = xch + ((ai * 128 + m * 16 + lrow) * 4) * 2 + bj; const float rstd = rsqrtf(((xp[0] + xp[2]) + (xp[4] + xp[6])) * (1.f / 128.f) + EPS); v0 = v0 * rstd * g0; v1 = v1 * rstd * g1; }
;                     if (TYPE == 4) { UNROLL for (int j = 0; j < 4; ++j) { v0[j] = gelu_f(v0[j]); v1[j] = gelu_f(v1[j]); } }
;                     if (TYPE == 3 || TYPE == 6) { UNROLL for (int j = 0; j < 4; ++j) { v0[j] = silu_f(v0[j]); v1[j] = silu_f(v1[j]); } }
;                     if (TYPE == 2 && r < MP) {
;                         const bf16x8 av = __builtin_bit_cast(bf16x8, pack8(v0, v1));
;                         const int r16 = r - fr;
;                         bf16_t* vtb = bdst + (size_t)((r16 >> 13) * 8 + (col >> 6)) * (8192 * 64) + (size_t)((r16 & 8191) >> 5) * 2048 + (size_t)(((wc & 1) * 2 + ((r16 >> 4) & 1)) * 512);
;                         UNROLL for (int sel = 0; sel < 2; ++sel) {
;                             bf16x8 bsel; UNROLL for (int e = 0; e < 8; ++e) bsel[e] = (8 * fq + e == 16 * sel + fr) ? (short)0x3F80 : (short)0;
;                             const f32x4 dv = __builtin_amdgcn_mfma_f32_16x16x32_bf16(av, bsel, (f32x4){0.f, 0.f, 0.f, 0.f}, 0, 0, 0);
;                             *(u32x2*)(vtb + (size_t)((16 * sel + fr + 32 * (fq & 1)) * 8 + (fq >> 1) * 4)) = pack4(dv);
;                         }
;                     } else {
;                     const size_t bo = headlay ? (tokhead_idx<(TYPE == 1 || TYPE == 2)>(r, col >> 6) * 64 + (col & 63)) : ((size_t)r * 512 + col);
.LBB0_201:
	s_or_b64 exec, exec, s[2:3]
	v_add_u32_e32 v176, 0xa0, v164
	v_cmp_gt_i32_e64 s[14:15], s30, v164
	v_ashrrev_i32_e32 v177, 31, v176
	s_and_saveexec_b64 s[2:3], s[14:15]
	s_cbranch_execz .LBB0_204
	v_mov_b64_e32 v[138:139], v[78:79]
	v_mov_b64_e32 v[142:143], v[74:75]
	v_mov_b64_e32 v[136:137], v[76:77]
	v_mov_b64_e32 v[140:141], v[72:73]
	s_nop 0
	v_mul_f32_e32 v152, 0x3d372713, v136
	v_mul_f32_e32 v152, v136, v152
	v_fma_f32 v152, v136, v152, v136
	v_mul_f32_e32 v152, 0x3fcc422a, v152
	v_mul_f32_e32 v152, 0xbfb8aa3b, v152
	v_exp_f32_e32 v152, v152
	s_nop 0
	v_add_f32_e32 v152, 1.0, v152
	v_rcp_f32_e32 v178, v152
	v_mul_f32_e32 v152, 0x3d372713, v140
	v_mul_f32_e32 v152, v140, v152
	v_fma_f32 v152, v140, v152, v140
	v_mul_f32_e32 v152, 0x3fcc422a, v152
	v_mul_f32_e32 v152, 0xbfb8aa3b, v152
	v_exp_f32_e32 v152, v152
	s_nop 0
	v_add_f32_e32 v152, 1.0, v152
	v_rcp_f32_e32 v200, v152
	v_mul_f32_e32 v152, 0x3d372713, v137
	v_mul_f32_e32 v152, v137, v152
	v_fma_f32 v152, v137, v152, v137
	v_mul_f32_e32 v152, 0x3fcc422a, v152
	v_mul_f32_e32 v152, 0xbfb8aa3b, v152
	v_exp_f32_e32 v152, v152
	s_nop 0
	v_add_f32_e32 v152, 1.0, v152
	v_rcp_f32_e32 v179, v152
	v_mul_f32_e32 v152, 0x3d372713, v141
	v_mul_f32_e32 v152, v141, v152
	v_fma_f32 v152, v141, v152, v141
	v_mul_f32_e32 v152, 0x3fcc422a, v152
	v_mul_f32_e32 v152, 0xbfb8aa3b, v152
	v_exp_f32_e32 v152, v152
	v_pk_mul_f32 v[136:137], v[136:137], v[178:179]
	v_add_f32_e32 v152, 1.0, v152
	v_rcp_f32_e32 v201, v152
	v_mul_f32_e32 v152, 0x3d372713, v138
	v_mul_f32_e32 v152, v138, v152
	v_fma_f32 v152, v138, v152, v138
	v_mul_f32_e32 v152, 0x3fcc422a, v152
	v_mul_f32_e32 v152, 0xbfb8aa3b, v152
	v_exp_f32_e32 v152, v152
	v_pk_mul_f32 v[140:141], v[140:141], v[200:201]
	v_add_f32_e32 v152, 1.0, v152
	v_rcp_f32_e32 v202, v152
	v_mul_f32_e32 v152, 0x3d372713, v142
	v_mul_f32_e32 v152, v142, v152
	v_fma_f32 v152, v142, v152, v142
	v_mul_f32_e32 v152, 0x3fcc422a, v152
	v_mul_f32_e32 v152, 0xbfb8aa3b, v152
	v_exp_f32_e32 v152, v152
	s_nop 0
	v_add_f32_e32 v152, 1.0, v152
	v_rcp_f32_e32 v204, v152
	v_mul_f32_e32 v152, 0x3d372713, v139
	v_mul_f32_e32 v152, v139, v152
	v_fma_f32 v152, v139, v152, v139
	v_mul_f32_e32 v152, 0x3fcc422a, v152
	v_mul_f32_e32 v152, 0xbfb8aa3b, v152
	v_exp_f32_e32 v152, v152
	s_nop 0
	v_add_f32_e32 v152, 1.0, v152
	v_rcp_f32_e32 v203, v152
	v_mul_f32_e32 v152, 0x3d372713, v143
	v_mul_f32_e32 v152, v143, v152
	v_fma_f32 v152, v143, v152, v143
	v_mul_f32_e32 v152, 0x3fcc422a, v152
	v_mul_f32_e32 v152, 0xbfb8aa3b, v152
	v_exp_f32_e32 v152, v152
	v_pk_mul_f32 v[138:139], v[138:139], v[202:203]
	v_add_f32_e32 v152, 1.0, v152
	v_rcp_f32_e32 v205, v152
	v_add_u32_e32 v152, 0x1400, v197
	ds_read2_b32 v[178:179], v152 offset1:2
	ds_read2_b32 v[200:201], v152 offset0:4 offset1:6
	v_pk_mul_f32 v[142:143], v[142:143], v[204:205]
	s_waitcnt lgkmcnt(0)
	v_mov_b32_e32 v202, v178
	v_mov_b32_e32 v203, v200
	v_mov_b32_e32 v200, v179
	v_pk_add_f32 v[178:179], v[202:203], v[200:201]
	s_nop 0
	v_add_f32_e32 v152, v178, v179
	v_fmamk_f32 v152, v152, 0x3c000000, v190
	v_cmp_gt_f32_e64 s[0:1], s49, v152
	v_mul_f32_e32 v178, 0x4b800000, v152
	s_nop 0
	v_cndmask_b32_e64 v152, v152, v178, s[0:1]
	v_rsq_f32_e32 v152, v152
	s_nop 0
	v_mul_f32_e32 v178, 0x45800000, v152
	v_cndmask_b32_e64 v152, v152, v178, s[0:1]
	v_pk_mul_f32 v[136:137], v[152:153], v[136:137] op_sel_hi:[0,1]
	v_pk_mul_f32 v[138:139], v[152:153], v[138:139] op_sel_hi:[0,1]
	v_pk_mul_f32 v[140:141], v[152:153], v[140:141] op_sel_hi:[0,1]
	v_pk_mul_f32 v[142:143], v[152:153], v[142:143] op_sel_hi:[0,1]
	v_pk_mul_f32 v[138:139], v[134:135], v[138:139]
	v_pk_mul_f32 v[136:137], v[132:133], v[136:137]
	v_pk_mul_f32 v[142:143], v[130:131], v[142:143]
	v_pk_mul_f32 v[140:141], v[128:129], v[140:141]
	v_lshlrev_b64 v[178:179], 10, v[176:177]
	s_movk_i32 s0, 0x3f5f
	v_cvt_pk_bf16_f32 v200, v136, v137
	v_cvt_pk_bf16_f32 v201, v138, v139
	v_cvt_pk_bf16_f32 v202, v140, v141
	v_cvt_pk_bf16_f32 v203, v142, v143
	v_lshl_add_u64 v[178:179], v[182:183], 0, v[178:179]
	v_cmp_lt_i32_e64 s[0:1], s0, v164
	global_store_dwordx4 v[178:179], v[200:203], off
	s_and_b64 exec, exec, s[0:1]
	s_cbranch_execz .LBB0_204
	v_add_u32_e32 v152, 0xffffc0a0, v164
	v_readlane_b32 s0, v254, 43
	v_lshlrev_b64 v[178:179], 11, v[152:153]
	v_readlane_b32 s1, v254, 44
	s_nop 1
	v_lshl_add_u64 v[178:179], s[0:1], 0, v[178:179]
	v_lshl_add_u64 v[178:179], v[162:163], 2, v[178:179]
	global_store_dwordx4 v[178:179], v[136:139], off
	global_store_dwordx4 v[178:179], v[140:143], off offset:16
;     template <int TYPE>
;     __device__ __forceinline__ void body(f32x4 (&acc)[2][2][4][2], const Unit& u, int wr, int wc, int fr, int fq) const {
;     ...
;             UNROLL for (int ai = 0; ai < 2; ++ai) UNROLL for (int m = 0; m < 4; ++m) {
;                 const int r = rb + ai * 128 + m * 16;
;                 if (r < MT) {
;                     f32x4 v0 = acc[ai][bj][m][0], v1 = acc[ai][bj][m][1];
;                     if (norm64) { const LAS float* xp = xch + ((ai * 128 + m * 16 + lrow) * 4 + (wc & 2)) * 2 + bj; const float rstd = rsqrtf((xp[0] + xp[2]) * (1.f / 64.f) + EPS); v0 = v0 * rstd * g0; v1 = v1 * rstd * g1; }
;                     if (TYPE == 5) { asm volatile("" : "+v"(v0), "+v"(v1));
;                         UNROLL for (int j = 0; j < 4; ++j) { v0[j] = gelu_f(v0[j]); v1[j] = gelu_f(v1[j]); } }
;                     if (norm128) { const LAS float* xp = xch + ((ai * 128 + m * 16 + lrow) * 4) * 2 + bj; const float rstd = rsqrtf(((xp[0] + xp[2]) + (xp[4] + xp[6])) * (1.f / 128.f) + EPS); v0 = v0 * rstd * g0; v1 = v1 * rstd * g1; }
;                     if (TYPE == 4) { UNROLL for (int j = 0; j < 4; ++j) { v0[j] = gelu_f(v0[j]); v1[j] = gelu_f(v1[j]); } }
;                     if (TYPE == 3 || TYPE == 6) { UNROLL for (int j = 0; j < 4; ++j) { v0[j] = silu_f(v0[j]); v1[j] = silu_f(v1[j]); } }
;                     if (TYPE == 2 && r < MP) {
;                         const bf16x8 av = __builtin_bit_cast(bf16x8, pack8(v0, v1));
;                         const int r16 = r - fr;
;                         bf16_t* vtb = bdst + (size_t)((r16 >> 13) * 8 + (col >> 6)) * (8192 * 64) + (size_t)((r16 & 8191) >> 5) * 2048 + (size_t)(((wc & 1) * 2 + ((r16 >> 4) & 1)) * 512);
;                         UNROLL for (int sel = 0; sel < 2; ++sel) {
;                             bf16x8 bsel; UNROLL for (int e = 0; e < 8; ++e) bsel[e] = (8 * fq + e == 16 * sel + fr) ? (short)0x3F80 : (short)0;
;                             const f32x4 dv = __builtin_amdgcn_mfma_f32_16x16x32_bf16(av, bsel, (f32x4){0.f, 0.f, 0.f, 0.f}, 0, 0, 0);
;                             *(u32x2*)(vtb + (size_t)((16 * sel + fr + 32 * (fq & 1)) * 8 + (fq >> 1) * 4)) = pack4(dv);
;                         }
;                     } else {
;                     const size_t bo = headlay ? (tokhead_idx<(TYPE == 1 || TYPE == 2)>(r, col >> 6) * 64 + (col & 63)) : ((size_t)r * 512 + col);
.LBB0_204:
	s_or_b64 exec, exec, s[2:3]
	v_add_u32_e32 v178, 0xb0, v164
	v_cmp_gt_i32_e64 s[16:17], s48, v164
	v_ashrrev_i32_e32 v179, 31, v178
	s_and_saveexec_b64 s[2:3], s[16:17]
	s_cbranch_execz .LBB0_207
	v_mov_b64_e32 v[138:139], v[70:71]
	v_mov_b64_e32 v[142:143], v[66:67]
	v_mov_b64_e32 v[136:137], v[68:69]
	v_mov_b64_e32 v[140:141], v[64:65]
	s_nop 0
	v_mul_f32_e32 v152, 0x3d372713, v136
	v_mul_f32_e32 v152, v136, v152
	v_fma_f32 v152, v136, v152, v136
	v_mul_f32_e32 v152, 0x3fcc422a, v152
	v_mul_f32_e32 v152, 0xbfb8aa3b, v152
	v_exp_f32_e32 v152, v152
	s_nop 0
	v_add_f32_e32 v152, 1.0, v152
	v_rcp_f32_e32 v200, v152
	v_mul_f32_e32 v152, 0x3d372713, v140
	v_mul_f32_e32 v152, v140, v152
	v_fma_f32 v152, v140, v152, v140
	v_mul_f32_e32 v152, 0x3fcc422a, v152
	v_mul_f32_e32 v152, 0xbfb8aa3b, v152
	v_exp_f32_e32 v152, v152
	s_nop 0
	v_add_f32_e32 v152, 1.0, v152
	v_rcp_f32_e32 v202, v152
	v_mul_f32_e32 v152, 0x3d372713, v137
	v_mul_f32_e32 v152, v137, v152
	v_fma_f32 v152, v137, v152, v137
	v_mul_f32_e32 v152, 0x3fcc422a, v152
	v_mul_f32_e32 v152, 0xbfb8aa3b, v152
	v_exp_f32_e32 v152, v152
	s_nop 0
	v_add_f32_e32 v152, 1.0, v152
	v_rcp_f32_e32 v201, v152
	v_mul_f32_e32 v152, 0x3d372713, v141
	v_mul_f32_e32 v152, v141, v152
	v_fma_f32 v152, v141, v152, v141
	v_mul_f32_e32 v152, 0x3fcc422a, v152
	v_mul_f32_e32 v152, 0xbfb8aa3b, v152
	v_exp_f32_e32 v152, v152
	v_pk_mul_f32 v[136:137], v[136:137], v[200:201]
	v_add_f32_e32 v152, 1.0, v152
	v_rcp_f32_e32 v203, v152
	v_mul_f32_e32 v152, 0x3d372713, v138
	v_mul_f32_e32 v152, v138, v152
	v_fma_f32 v152, v138, v152, v138
	v_mul_f32_e32 v152, 0x3fcc422a, v152
	v_mul_f32_e32 v152, 0xbfb8aa3b, v152
	v_exp_f32_e32 v152, v152
	v_pk_mul_f32 v[140:141], v[140:141], v[202:203]
	v_add_f32_e32 v152, 1.0, v152
	v_rcp_f32_e32 v204, v152
	v_mul_f32_e32 v152, 0x3d372713, v142
	v_mul_f32_e32 v152, v142, v152
	v_fma_f32 v152, v142, v152, v142
	v_mul_f32_e32 v152, 0x3fcc422a, v152
	v_mul_f32_e32 v152, 0xbfb8aa3b, v152
	v_exp_f32_e32 v152, v152
	s_nop 0
	v_add_f32_e32 v152, 1.0, v152
	v_rcp_f32_e32 v206, v152
	v_mul_f32_e32 v152, 0x3d372713, v139
	v_mul_f32_e32 v152, v139, v152
	v_fma_f32 v152, v139, v152, v139
	v_mul_f32_e32 v152, 0x3fcc422a, v152
	v_mul_f32_e32 v152, 0xbfb8aa3b, v152
	v_exp_f32_e32 v152, v152
	s_nop 0
	v_add_f32_e32 v152, 1.0, v152
	v_rcp_f32_e32 v205, v152
	v_mul_f32_e32 v152, 0x3d372713, v143
	v_mul_f32_e32 v152, v143, v152
	v_fma_f32 v152, v143, v152, v143
	v_mul_f32_e32 v152, 0x3fcc422a, v152
	v_mul_f32_e32 v152, 0xbfb8aa3b, v152
	v_exp_f32_e32 v152, v152
	v_pk_mul_f32 v[138:139], v[138:139], v[204:205]
	v_add_f32_e32 v152, 1.0, v152
	v_rcp_f32_e32 v207, v152
	v_add_u32_e32 v152, 0x1400, v197
	ds_read2_b32 v[200:201], v152 offset0:128 offset1:130
	ds_read2_b32 v[202:203], v152 offset0:132 offset1:134
	v_pk_mul_f32 v[142:143], v[142:143], v[206:207]
	s_waitcnt lgkmcnt(0)
	v_mov_b32_e32 v204, v200
	v_mov_b32_e32 v205, v202
	v_mov_b32_e32 v202, v201
	v_pk_add_f32 v[200:201], v[204:205], v[202:203]
	s_nop 0
	v_add_f32_e32 v152, v200, v201
	v_fmamk_f32 v152, v152, 0x3c000000, v190
	v_cmp_gt_f32_e64 s[0:1], s49, v152
	v_mul_f32_e32 v200, 0x4b800000, v152
	s_nop 0
	v_cndmask_b32_e64 v152, v152, v200, s[0:1]
	v_rsq_f32_e32 v152, v152
	s_nop 0
	v_mul_f32_e32 v200, 0x45800000, v152
	v_cndmask_b32_e64 v152, v152, v200, s[0:1]
	v_pk_mul_f32 v[136:137], v[152:153], v[136:137] op_sel_hi:[0,1]
	v_pk_mul_f32 v[138:139], v[152:153], v[138:139] op_sel_hi:[0,1]
	v_pk_mul_f32 v[134:135], v[134:135], v[138:139]
	v_pk_mul_f32 v[132:133], v[132:133], v[136:137]
	v_pk_mul_f32 v[136:137], v[152:153], v[140:141] op_sel_hi:[0,1]
	v_pk_mul_f32 v[138:139], v[152:153], v[142:143] op_sel_hi:[0,1]
	v_pk_mul_f32 v[130:131], v[130:131], v[138:139]
	v_pk_mul_f32 v[128:129], v[128:129], v[136:137]
	v_lshlrev_b64 v[140:141], 10, v[178:179]
	s_movk_i32 s0, 0x3f4f
	v_cvt_pk_bf16_f32 v136, v132, v133
	v_cvt_pk_bf16_f32 v137, v134, v135
	v_cvt_pk_bf16_f32 v138, v128, v129
	v_cvt_pk_bf16_f32 v139, v130, v131
	v_lshl_add_u64 v[140:141], v[182:183], 0, v[140:141]
	v_cmp_lt_i32_e64 s[0:1], s0, v164
	global_store_dwordx4 v[140:141], v[136:139], off
	s_and_b64 exec, exec, s[0:1]
	s_cbranch_execz .LBB0_207
	v_add_u32_e32 v152, 0xffffc0b0, v164
	v_readlane_b32 s0, v254, 43
	v_lshlrev_b64 v[136:137], 11, v[152:153]
	v_readlane_b32 s1, v254, 44
	s_nop 1
	v_lshl_add_u64 v[136:137], s[0:1], 0, v[136:137]
	v_lshl_add_u64 v[136:137], v[162:163], 2, v[136:137]
	global_store_dwordx4 v[136:137], v[132:135], off
	global_store_dwordx4 v[136:137], v[128:131], off offset:16

;     template <int TYPE>
;     __device__ __forceinline__ void body(f32x4 (&acc)[2][2][4][2], const Unit& u, int wr, int wc, int fr, int fq) const {
;     ...
;             UNROLL for (int ai = 0; ai < 2; ++ai) UNROLL for (int m = 0; m < 4; ++m) {
;                 const int r = rb + ai * 128 + m * 16;
;                 if (r < MT) {
;                     f32x4 v0 = acc[ai][bj][m][0], v1 = acc[ai][bj][m][1];
;                     if (norm64) { const LAS float* xp = xch + ((ai * 128 + m * 16 + lrow) * 4 + (wc & 2)) * 2 + bj; const float rstd = rsqrtf((xp[0] + xp[2]) * (1.f / 64.f) + EPS); v0 = v0 * rstd * g0; v1 = v1 * rstd * g1; }
;                     if (TYPE == 5) { asm volatile("" : "+v"(v0), "+v"(v1));
;                         UNROLL for (int j = 0; j < 4; ++j) { v0[j] = gelu_f(v0[j]); v1[j] = gelu_f(v1[j]); } }
;                     if (norm128) { const LAS float* xp = xch + ((ai * 128 + m * 16 + lrow) * 4) * 2 + bj; const float rstd = rsqrtf(((xp[0] + xp[2]) + (xp[4] + xp[6])) * (1.f / 128.f) + EPS); v0 = v0 * rstd * g0; v1 = v1 * rstd * g1; }
;                     if (TYPE == 4) { UNROLL for (int j = 0; j < 4; ++j) { v0[j] = gelu_f(v0[j]); v1[j] = gelu_f(v1[j]); } }
;                     if (TYPE == 3 || TYPE == 6) { UNROLL for (int j = 0; j < 4; ++j) { v0[j] = silu_f(v0[j]); v1[j] = silu_f(v1[j]); } }
;                     if (TYPE == 2 && r < MP) {
;                         const bf16x8 av = __builtin_bit_cast(bf16x8, pack8(v0, v1));
;                         const int r16 = r - fr;
;                         bf16_t* vtb = bdst + (size_t)((r16 >> 13) * 8 + (col >> 6)) * (8192 * 64) + (size_t)((r16 & 8191) >> 5) * 2048 + (size_t)(((wc & 1) * 2 + ((r16 >> 4) & 1)) * 512);
;                         UNROLL for (int sel = 0; sel < 2; ++sel) {
;                             bf16x8 bsel; UNROLL for (int e = 0; e < 8; ++e) bsel[e] = (8 * fq + e == 16 * sel + fr) ? (short)0x3F80 : (short)0;
;                             const f32x4 dv = __builtin_amdgcn_mfma_f32_16x16x32_bf16(av, bsel, (f32x4){0.f, 0.f, 0.f, 0.f}, 0, 0, 0);
;                             *(u32x2*)(vtb + (size_t)((16 * sel + fr + 32 * (fq & 1)) * 8 + (fq >> 1) * 4)) = pack4(dv);
;                         }
;                     } else {
;                     const size_t bo = headlay ? (tokhead_idx<(TYPE == 1 || TYPE == 2)>(r, col >> 6) * 64 + (col & 63)) : ((size_t)r * 512 + col);
.LBB0_210:
	s_or_b64 exec, exec, s[0:1]
	s_and_saveexec_b64 s[0:1], s[4:5]
	s_cbranch_execz .LBB0_213
	v_mov_b64_e32 v[138:139], v[50:51]
	v_mov_b64_e32 v[142:143], v[54:55]
	v_mov_b64_e32 v[136:137], v[48:49]
	v_mov_b64_e32 v[140:141], v[52:53]
	v_lshlrev_b64 v[166:167], 10, v[166:167]
	v_mul_f32_e32 v152, 0x3d372713, v140
	v_mul_f32_e32 v152, v140, v152
	v_fma_f32 v152, v140, v152, v140
	v_mul_f32_e32 v152, 0x3fcc422a, v152
	v_mul_f32_e32 v152, 0xbfb8aa3b, v152
	v_exp_f32_e32 v152, v152
	s_movk_i32 s2, 0x3fef
	v_lshl_add_u64 v[166:167], v[180:181], 0, v[166:167]
	v_add_f32_e32 v152, 1.0, v152
	v_rcp_f32_e32 v182, v152
	v_mul_f32_e32 v152, 0x3d372713, v136
	v_mul_f32_e32 v152, v136, v152
	v_fma_f32 v152, v136, v152, v136
	v_mul_f32_e32 v152, 0x3fcc422a, v152
	v_mul_f32_e32 v152, 0xbfb8aa3b, v152
	v_exp_f32_e32 v152, v152
	s_nop 0
	v_add_f32_e32 v152, 1.0, v152
	v_rcp_f32_e32 v200, v152
	v_mul_f32_e32 v152, 0x3d372713, v141
	v_mul_f32_e32 v152, v141, v152
	v_fma_f32 v152, v141, v152, v141
	v_mul_f32_e32 v152, 0x3fcc422a, v152
	v_mul_f32_e32 v152, 0xbfb8aa3b, v152
	v_exp_f32_e32 v152, v152
	s_nop 0
	v_add_f32_e32 v152, 1.0, v152
	v_rcp_f32_e32 v183, v152
	v_mul_f32_e32 v152, 0x3d372713, v137
	v_mul_f32_e32 v152, v137, v152
	v_fma_f32 v152, v137, v152, v137
	v_mul_f32_e32 v152, 0x3fcc422a, v152
	v_mul_f32_e32 v152, 0xbfb8aa3b, v152
	v_exp_f32_e32 v152, v152
	v_pk_mul_f32 v[140:141], v[140:141], v[182:183]
	v_add_f32_e32 v152, 1.0, v152
	v_rcp_f32_e32 v201, v152
	v_mul_f32_e32 v152, 0x3d372713, v142
	v_mul_f32_e32 v152, v142, v152
	v_fma_f32 v152, v142, v152, v142
	v_mul_f32_e32 v152, 0x3fcc422a, v152
	v_mul_f32_e32 v152, 0xbfb8aa3b, v152
	v_exp_f32_e32 v152, v152
	v_pk_mul_f32 v[200:201], v[136:137], v[200:201]
	v_add_f32_e32 v152, 1.0, v152
	v_rcp_f32_e32 v202, v152
	v_mul_f32_e32 v152, 0x3d372713, v138
	v_mul_f32_e32 v152, v138, v152
	v_fma_f32 v152, v138, v152, v138
	v_mul_f32_e32 v152, 0x3fcc422a, v152
	v_mul_f32_e32 v152, 0xbfb8aa3b, v152
	v_exp_f32_e32 v152, v152
	s_nop 0
	v_add_f32_e32 v152, 1.0, v152
	v_rcp_f32_e32 v204, v152
	v_mul_f32_e32 v152, 0x3d372713, v143
	v_mul_f32_e32 v152, v143, v152
	v_fma_f32 v152, v143, v152, v143
	v_mul_f32_e32 v152, 0x3fcc422a, v152
	v_mul_f32_e32 v152, 0xbfb8aa3b, v152
	v_exp_f32_e32 v152, v152
	s_nop 0
	v_add_f32_e32 v152, 1.0, v152
	v_rcp_f32_e32 v203, v152
	v_mul_f32_e32 v152, 0x3d372713, v139
	v_mul_f32_e32 v152, v139, v152
	v_fma_f32 v152, v139, v152, v139
	v_mul_f32_e32 v152, 0x3fcc422a, v152
	v_mul_f32_e32 v152, 0xbfb8aa3b, v152
	v_exp_f32_e32 v152, v152
	v_pk_mul_f32 v[142:143], v[142:143], v[202:203]
	v_add_f32_e32 v152, 1.0, v152
	v_rcp_f32_e32 v205, v152
	s_nop 0
	v_pk_mul_f32 v[182:183], v[138:139], v[204:205]
	ds_read2_b32 v[136:137], v197 offset0:129 offset1:131
	ds_read2_b32 v[138:139], v197 offset0:133 offset1:135
	s_waitcnt lgkmcnt(0)
	v_mov_b32_e32 v202, v136
	v_mov_b32_e32 v203, v138
	v_mov_b32_e32 v138, v137
	v_pk_add_f32 v[136:137], v[202:203], v[138:139]
	s_nop 0
	v_add_f32_e32 v136, v136, v137
	v_fmamk_f32 v136, v136, 0x3c000000, v190
	v_cmp_gt_f32_e32 vcc, s49, v136
	v_mul_f32_e32 v137, 0x4b800000, v136
	s_nop 0
	v_cndmask_b32_e32 v136, v136, v137, vcc
	v_rsq_f32_e32 v136, v136
	s_nop 0
	v_mul_f32_e32 v137, 0x45800000, v136
	v_cndmask_b32_e32 v152, v136, v137, vcc
	v_pk_mul_f32 v[136:137], v[152:153], v[140:141] op_sel_hi:[0,1]
	v_pk_mul_f32 v[138:139], v[152:153], v[142:143] op_sel_hi:[0,1]
	v_pk_mul_f32 v[140:141], v[152:153], v[200:201] op_sel_hi:[0,1]
	v_pk_mul_f32 v[142:143], v[152:153], v[182:183] op_sel_hi:[0,1]
	v_pk_mul_f32 v[138:139], v[134:135], v[138:139]
	v_pk_mul_f32 v[136:137], v[132:133], v[136:137]
	v_pk_mul_f32 v[142:143], v[130:131], v[142:143]
	v_pk_mul_f32 v[140:141], v[128:129], v[140:141]
	v_cvt_pk_bf16_f32 v200, v136, v137
	v_cvt_pk_bf16_f32 v201, v138, v139
	v_cvt_pk_bf16_f32 v202, v140, v141
	v_cvt_pk_bf16_f32 v203, v142, v143
	v_cmp_lt_i32_e32 vcc, s2, v164
	global_store_dwordx4 v[166:167], v[200:203], off
	s_and_b64 exec, exec, vcc
	s_cbranch_execz .LBB0_213
	v_add_u32_e32 v152, 0xffffc010, v164
	v_readlane_b32 s2, v254, 43
	v_lshlrev_b64 v[166:167], 11, v[152:153]
	v_readlane_b32 s3, v254, 44
	s_nop 1
	v_lshl_add_u64 v[166:167], s[2:3], 0, v[166:167]
	v_lshl_add_u64 v[166:167], v[162:163], 2, v[166:167]
	global_store_dwordx4 v[166:167], v[136:139], off offset:512
	global_store_dwordx4 v[166:167], v[140:143], off offset:528
;     template <int TYPE>
;     __device__ __forceinline__ void body(f32x4 (&acc)[2][2][4][2], const Unit& u, int wr, int wc, int fr, int fq) const {
;     ...
;             UNROLL for (int ai = 0; ai < 2; ++ai) UNROLL for (int m = 0; m < 4; ++m) {
;                 const int r = rb + ai * 128 + m * 16;
;                 if (r < MT) {
;                     f32x4 v0 = acc[ai][bj][m][0], v1 = acc[ai][bj][m][1];
;                     if (norm64) { const LAS float* xp = xch + ((ai * 128 + m * 16 + lrow) * 4 + (wc & 2)) * 2 + bj; const float rstd = rsqrtf((xp[0] + xp[2]) * (1.f / 64.f) + EPS); v0 = v0 * rstd * g0; v1 = v1 * rstd * g1; }
;                     if (TYPE == 5) { asm volatile("" : "+v"(v0), "+v"(v1));
;                         UNROLL for (int j = 0; j < 4; ++j) { v0[j] = gelu_f(v0[j]); v1[j] = gelu_f(v1[j]); } }
;                     if (norm128) { const LAS float* xp = xch + ((ai * 128 + m * 16 + lrow) * 4) * 2 + bj; const float rstd = rsqrtf(((xp[0] + xp[2]) + (xp[4] + xp[6])) * (1.f / 128.f) + EPS); v0 = v0 * rstd * g0; v1 = v1 * rstd * g1; }
;                     if (TYPE == 4) { UNROLL for (int j = 0; j < 4; ++j) { v0[j] = gelu_f(v0[j]); v1[j] = gelu_f(v1[j]); } }
;                     if (TYPE == 3 || TYPE == 6) { UNROLL for (int j = 0; j < 4; ++j) { v0[j] = silu_f(v0[j]); v1[j] = silu_f(v1[j]); } }
;                     if (TYPE == 2 && r < MP) {
;                         const bf16x8 av = __builtin_bit_cast(bf16x8, pack8(v0, v1));
;                         const int r16 = r - fr;
;                         bf16_t* vtb = bdst + (size_t)((r16 >> 13) * 8 + (col >> 6)) * (8192 * 64) + (size_t)((r16 & 8191) >> 5) * 2048 + (size_t)(((wc & 1) * 2 + ((r16 >> 4) & 1)) * 512);
;                         UNROLL for (int sel = 0; sel < 2; ++sel) {
;                             bf16x8 bsel; UNROLL for (int e = 0; e < 8; ++e) bsel[e] = (8 * fq + e == 16 * sel + fr) ? (short)0x3F80 : (short)0;
;                             const f32x4 dv = __builtin_amdgcn_mfma_f32_16x16x32_bf16(av, bsel, (f32x4){0.f, 0.f, 0.f, 0.f}, 0, 0, 0);
;                             *(u32x2*)(vtb + (size_t)((16 * sel + fr + 32 * (fq & 1)) * 8 + (fq >> 1) * 4)) = pack4(dv);
;                         }
;                     } else {
;                     const size_t bo = headlay ? (tokhead_idx<(TYPE == 1 || TYPE == 2)>(r, col >> 6) * 64 + (col & 63)) : ((size_t)r * 512 + col);
.LBB0_213:
	s_or_b64 exec, exec, s[0:1]
	s_and_saveexec_b64 s[0:1], s[6:7]
	s_cbranch_execz .LBB0_216
	v_mov_b64_e32 v[138:139], v[46:47]
	v_mov_b64_e32 v[142:143], v[42:43]
	v_mov_b64_e32 v[136:137], v[44:45]
	v_mov_b64_e32 v[140:141], v[40:41]
	s_movk_i32 s2, 0x3fdf
	v_mul_f32_e32 v152, 0x3d372713, v136
	v_mul_f32_e32 v152, v136, v152
	v_fma_f32 v152, v136, v152, v136
	v_mul_f32_e32 v152, 0x3fcc422a, v152
	v_mul_f32_e32 v152, 0xbfb8aa3b, v152
	v_exp_f32_e32 v152, v152
	s_nop 0
	v_add_f32_e32 v152, 1.0, v152
	v_rcp_f32_e32 v166, v152
	v_mul_f32_e32 v152, 0x3d372713, v140
	v_mul_f32_e32 v152, v140, v152
	v_fma_f32 v152, v140, v152, v140
	v_mul_f32_e32 v152, 0x3fcc422a, v152
	v_mul_f32_e32 v152, 0xbfb8aa3b, v152
	v_exp_f32_e32 v152, v152
	s_nop 0
	v_add_f32_e32 v152, 1.0, v152
	v_rcp_f32_e32 v182, v152
	v_mul_f32_e32 v152, 0x3d372713, v137
	v_mul_f32_e32 v152, v137, v152
	v_fma_f32 v152, v137, v152, v137
	v_mul_f32_e32 v152, 0x3fcc422a, v152
	v_mul_f32_e32 v152, 0xbfb8aa3b, v152
	v_exp_f32_e32 v152, v152
	s_nop 0
	v_add_f32_e32 v152, 1.0, v152
	v_rcp_f32_e32 v167, v152
	v_mul_f32_e32 v152, 0x3d372713, v141
	v_mul_f32_e32 v152, v141, v152
	v_fma_f32 v152, v141, v152, v141
	v_mul_f32_e32 v152, 0x3fcc422a, v152
	v_mul_f32_e32 v152, 0xbfb8aa3b, v152
	v_exp_f32_e32 v152, v152
	v_pk_mul_f32 v[136:137], v[136:137], v[166:167]
	v_add_f32_e32 v152, 1.0, v152
	v_rcp_f32_e32 v183, v152
	v_mul_f32_e32 v152, 0x3d372713, v138
	v_mul_f32_e32 v152, v138, v152
	v_fma_f32 v152, v138, v152, v138
	v_mul_f32_e32 v152, 0x3fcc422a, v152
	v_mul_f32_e32 v152, 0xbfb8aa3b, v152
	v_exp_f32_e32 v152, v152
	v_pk_mul_f32 v[140:141], v[140:141], v[182:183]
	v_add_f32_e32 v152, 1.0, v152
	v_rcp_f32_e32 v200, v152
	v_mul_f32_e32 v152, 0x3d372713, v142
	v_mul_f32_e32 v152, v142, v152
	v_fma_f32 v152, v142, v152, v142
	v_mul_f32_e32 v152, 0x3fcc422a, v152
	v_mul_f32_e32 v152, 0xbfb8aa3b, v152
	v_exp_f32_e32 v152, v152
	s_nop 0
	v_add_f32_e32 v152, 1.0, v152
	v_rcp_f32_e32 v202, v152
	v_mul_f32_e32 v152, 0x3d372713, v139
	v_mul_f32_e32 v152, v139, v152
	v_fma_f32 v152, v139, v152, v139
	v_mul_f32_e32 v152, 0x3fcc422a, v152
	v_mul_f32_e32 v152, 0xbfb8aa3b, v152
	v_exp_f32_e32 v152, v152
	s_nop 0
	v_add_f32_e32 v152, 1.0, v152
	v_rcp_f32_e32 v201, v152
	v_mul_f32_e32 v152, 0x3d372713, v143
	v_mul_f32_e32 v152, v143, v152
	v_fma_f32 v152, v143, v152, v143
	v_mul_f32_e32 v152, 0x3fcc422a, v152
	v_mul_f32_e32 v152, 0xbfb8aa3b, v152
	v_exp_f32_e32 v152, v152
	v_pk_mul_f32 v[138:139], v[138:139], v[200:201]
	v_add_f32_e32 v152, 1.0, v152
	v_rcp_f32_e32 v203, v152
	v_add_u32_e32 v152, 0x400, v197
	ds_read2_b32 v[166:167], v152 offset0:1 offset1:3
	ds_read2_b32 v[182:183], v152 offset0:5 offset1:7
	v_pk_mul_f32 v[142:143], v[142:143], v[202:203]
	s_waitcnt lgkmcnt(0)
	v_mov_b32_e32 v200, v166
	v_mov_b32_e32 v201, v182
	v_mov_b32_e32 v182, v167
	v_pk_add_f32 v[166:167], v[200:201], v[182:183]
	s_nop 0
	v_add_f32_e32 v152, v166, v167
	v_fmamk_f32 v152, v152, 0x3c000000, v190
	v_cmp_gt_f32_e32 vcc, s49, v152
	v_mul_f32_e32 v165, 0x4b800000, v152
	v_lshlrev_b64 v[166:167], 10, v[168:169]
	v_cndmask_b32_e32 v152, v152, v165, vcc
	v_rsq_f32_e32 v152, v152
	v_lshl_add_u64 v[166:167], v[180:181], 0, v[166:167]
	v_mul_f32_e32 v165, 0x45800000, v152
	v_cndmask_b32_e32 v152, v152, v165, vcc
	v_pk_mul_f32 v[136:137], v[152:153], v[136:137] op_sel_hi:[0,1]
	v_pk_mul_f32 v[138:139], v[152:153], v[138:139] op_sel_hi:[0,1]
	v_pk_mul_f32 v[140:141], v[152:153], v[140:141] op_sel_hi:[0,1]
	v_pk_mul_f32 v[142:143], v[152:153], v[142:143] op_sel_hi:[0,1]
	v_pk_mul_f32 v[138:139], v[134:135], v[138:139]
	v_pk_mul_f32 v[136:137], v[132:133], v[136:137]
	v_pk_mul_f32 v[142:143], v[130:131], v[142:143]
	v_pk_mul_f32 v[140:141], v[128:129], v[140:141]
	v_cvt_pk_bf16_f32 v200, v136, v137
	v_cvt_pk_bf16_f32 v201, v138, v139
	v_cvt_pk_bf16_f32 v202, v140, v141
	v_cvt_pk_bf16_f32 v203, v142, v143
	v_cmp_lt_i32_e32 vcc, s2, v164
	global_store_dwordx4 v[166:167], v[200:203], off
	s_and_b64 exec, exec, vcc
	s_cbranch_execz .LBB0_216
	v_add_u32_e32 v152, 0xffffc020, v164
	v_readlane_b32 s2, v254, 43
	v_lshlrev_b64 v[166:167], 11, v[152:153]
	v_readlane_b32 s3, v254, 44
	s_nop 1
	v_lshl_add_u64 v[166:167], s[2:3], 0, v[166:167]
	v_lshl_add_u64 v[166:167], v[162:163], 2, v[166:167]
	global_store_dwordx4 v[166:167], v[136:139], off offset:512
	global_store_dwordx4 v[166:167], v[140:143], off offset:528
;     template <int TYPE>
;     __device__ __forceinline__ void body(f32x4 (&acc)[2][2][4][2], const Unit& u, int wr, int wc, int fr, int fq) const {
;     ...
;             UNROLL for (int ai = 0; ai < 2; ++ai) UNROLL for (int m = 0; m < 4; ++m) {
;                 const int r = rb + ai * 128 + m * 16;
;                 if (r < MT) {
;                     f32x4 v0 = acc[ai][bj][m][0], v1 = acc[ai][bj][m][1];
;                     if (norm64) { const LAS float* xp = xch + ((ai * 128 + m * 16 + lrow) * 4 + (wc & 2)) * 2 + bj; const float rstd = rsqrtf((xp[0] + xp[2]) * (1.f / 64.f) + EPS); v0 = v0 * rstd * g0; v1 = v1 * rstd * g1; }
;                     if (TYPE == 5) { asm volatile("" : "+v"(v0), "+v"(v1));
;                         UNROLL for (int j = 0; j < 4; ++j) { v0[j] = gelu_f(v0[j]); v1[j] = gelu_f(v1[j]); } }
;                     if (norm128) { const LAS float* xp = xch + ((ai * 128 + m * 16 + lrow) * 4) * 2 + bj; const float rstd = rsqrtf(((xp[0] + xp[2]) + (xp[4] + xp[6])) * (1.f / 128.f) + EPS); v0 = v0 * rstd * g0; v1 = v1 * rstd * g1; }
;                     if (TYPE == 4) { UNROLL for (int j = 0; j < 4; ++j) { v0[j] = gelu_f(v0[j]); v1[j] = gelu_f(v1[j]); } }
;                     if (TYPE == 3 || TYPE == 6) { UNROLL for (int j = 0; j < 4; ++j) { v0[j] = silu_f(v0[j]); v1[j] = silu_f(v1[j]); } }
;                     if (TYPE == 2 && r < MP) {
;                         const bf16x8 av = __builtin_bit_cast(bf16x8, pack8(v0, v1));
;                         const int r16 = r - fr;
;                         bf16_t* vtb = bdst + (size_t)((r16 >> 13) * 8 + (col >> 6)) * (8192 * 64) + (size_t)((r16 & 8191) >> 5) * 2048 + (size_t)(((wc & 1) * 2 + ((r16 >> 4) & 1)) * 512);
;                         UNROLL for (int sel = 0; sel < 2; ++sel) {
;                             bf16x8 bsel; UNROLL for (int e = 0; e < 8; ++e) bsel[e] = (8 * fq + e == 16 * sel + fr) ? (short)0x3F80 : (short)0;
;                             const f32x4 dv = __builtin_amdgcn_mfma_f32_16x16x32_bf16(av, bsel, (f32x4){0.f, 0.f, 0.f, 0.f}, 0, 0, 0);
;                             *(u32x2*)(vtb + (size_t)((16 * sel + fr + 32 * (fq & 1)) * 8 + (fq >> 1) * 4)) = pack4(dv);
;                         }
;                     } else {
;                     const size_t bo = headlay ? (tokhead_idx<(TYPE == 1 || TYPE == 2)>(r, col >> 6) * 64 + (col & 63)) : ((size_t)r * 512 + col);
.LBB0_216:
	s_or_b64 exec, exec, s[0:1]
	s_and_saveexec_b64 s[0:1], s[8:9]
	s_cbranch_execz .LBB0_219
	v_mov_b64_e32 v[138:139], v[38:39]
	v_mov_b64_e32 v[142:143], v[34:35]
	v_mov_b64_e32 v[136:137], v[36:37]
	v_mov_b64_e32 v[140:141], v[32:33]
	v_lshlrev_b64 v[170:171], 10, v[170:171]
	v_mul_f32_e32 v152, 0x3d372713, v136
	v_mul_f32_e32 v152, v136, v152
	v_fma_f32 v152, v136, v152, v136
	v_mul_f32_e32 v152, 0x3fcc422a, v152
	v_mul_f32_e32 v152, 0xbfb8aa3b, v152
	v_exp_f32_e32 v152, v152
	s_movk_i32 s2, 0x3fcf
	v_lshl_add_u64 v[170:171], v[180:181], 0, v[170:171]
	v_add_f32_e32 v152, 1.0, v152
	v_rcp_f32_e32 v166, v152
	v_mul_f32_e32 v152, 0x3d372713, v140
	v_mul_f32_e32 v152, v140, v152
	v_fma_f32 v152, v140, v152, v140
	v_mul_f32_e32 v152, 0x3fcc422a, v152
	v_mul_f32_e32 v152, 0xbfb8aa3b, v152
	v_exp_f32_e32 v152, v152
	s_nop 0
	v_add_f32_e32 v152, 1.0, v152
	v_rcp_f32_e32 v168, v152
	v_mul_f32_e32 v152, 0x3d372713, v137
	v_mul_f32_e32 v152, v137, v152
	v_fma_f32 v152, v137, v152, v137
	v_mul_f32_e32 v152, 0x3fcc422a, v152
	v_mul_f32_e32 v152, 0xbfb8aa3b, v152
	v_exp_f32_e32 v152, v152
	s_nop 0
	v_add_f32_e32 v152, 1.0, v152
	v_rcp_f32_e32 v167, v152
	v_mul_f32_e32 v152, 0x3d372713, v141
	v_mul_f32_e32 v152, v141, v152
	v_fma_f32 v152, v141, v152, v141
	v_mul_f32_e32 v152, 0x3fcc422a, v152
	v_mul_f32_e32 v152, 0xbfb8aa3b, v152
	v_exp_f32_e32 v152, v152
	v_pk_mul_f32 v[136:137], v[136:137], v[166:167]
	v_add_f32_e32 v152, 1.0, v152
	v_rcp_f32_e32 v169, v152
	v_mul_f32_e32 v152, 0x3d372713, v138
	v_mul_f32_e32 v152, v138, v152
	v_fma_f32 v152, v138, v152, v138
	v_mul_f32_e32 v152, 0x3fcc422a, v152
	v_mul_f32_e32 v152, 0xbfb8aa3b, v152
	v_exp_f32_e32 v152, v152
	v_pk_mul_f32 v[140:141], v[140:141], v[168:169]
	v_add_f32_e32 v152, 1.0, v152
	v_rcp_f32_e32 v182, v152
	v_mul_f32_e32 v152, 0x3d372713, v142
	v_mul_f32_e32 v152, v142, v152
	v_fma_f32 v152, v142, v152, v142
	v_mul_f32_e32 v152, 0x3fcc422a, v152
	v_mul_f32_e32 v152, 0xbfb8aa3b, v152
	v_exp_f32_e32 v152, v152
	s_nop 0
	v_add_f32_e32 v152, 1.0, v152
	v_rcp_f32_e32 v200, v152
	v_mul_f32_e32 v152, 0x3d372713, v139
	v_mul_f32_e32 v152, v139, v152
	v_fma_f32 v152, v139, v152, v139
	v_mul_f32_e32 v152, 0x3fcc422a, v152
	v_mul_f32_e32 v152, 0xbfb8aa3b, v152
	v_exp_f32_e32 v152, v152
	s_nop 0
	v_add_f32_e32 v152, 1.0, v152
	v_rcp_f32_e32 v183, v152
	v_mul_f32_e32 v152, 0x3d372713, v143
	v_mul_f32_e32 v152, v143, v152
	v_fma_f32 v152, v143, v152, v143
	v_mul_f32_e32 v152, 0x3fcc422a, v152
	v_mul_f32_e32 v152, 0xbfb8aa3b, v152
	v_exp_f32_e32 v152, v152
	v_pk_mul_f32 v[138:139], v[138:139], v[182:183]
	v_add_f32_e32 v152, 1.0, v152
	v_rcp_f32_e32 v201, v152
	v_add_u32_e32 v152, 0x400, v197
	ds_read2_b32 v[166:167], v152 offset0:129 offset1:131
	ds_read2_b32 v[168:169], v152 offset0:133 offset1:135
	v_pk_mul_f32 v[142:143], v[142:143], v[200:201]
	s_waitcnt lgkmcnt(0)
	v_mov_b32_e32 v182, v166
	v_mov_b32_e32 v183, v168
	v_mov_b32_e32 v168, v167
	v_pk_add_f32 v[166:167], v[182:183], v[168:169]
	s_nop 0
	v_add_f32_e32 v152, v166, v167
	v_fmamk_f32 v152, v152, 0x3c000000, v190
	v_cmp_gt_f32_e32 vcc, s49, v152
	v_mul_f32_e32 v165, 0x4b800000, v152
	s_nop 0
	v_cndmask_b32_e32 v152, v152, v165, vcc
	v_rsq_f32_e32 v152, v152
	s_nop 0
	v_mul_f32_e32 v165, 0x45800000, v152
	v_cndmask_b32_e32 v152, v152, v165, vcc
	v_pk_mul_f32 v[136:137], v[152:153], v[136:137] op_sel_hi:[0,1]
	v_pk_mul_f32 v[138:139], v[152:153], v[138:139] op_sel_hi:[0,1]
	v_pk_mul_f32 v[140:141], v[152:153], v[140:141] op_sel_hi:[0,1]
	v_pk_mul_f32 v[142:143], v[152:153], v[142:143] op_sel_hi:[0,1]
	v_pk_mul_f32 v[138:139], v[134:135], v[138:139]
	v_pk_mul_f32 v[136:137], v[132:133], v[136:137]
	v_pk_mul_f32 v[142:143], v[130:131], v[142:143]
	v_pk_mul_f32 v[140:141], v[128:129], v[140:141]
	v_cvt_pk_bf16_f32 v166, v136, v137
	v_cvt_pk_bf16_f32 v167, v138, v139
	v_cvt_pk_bf16_f32 v168, v140, v141
	v_cvt_pk_bf16_f32 v169, v142, v143
	v_cmp_lt_i32_e32 vcc, s2, v164
	global_store_dwordx4 v[170:171], v[166:169], off
	s_and_b64 exec, exec, vcc
	s_cbranch_execz .LBB0_219
	v_add_u32_e32 v152, 0xffffc030, v164
	v_readlane_b32 s2, v254, 43
	v_lshlrev_b64 v[166:167], 11, v[152:153]
	v_readlane_b32 s3, v254, 44
	s_nop 1
	v_lshl_add_u64 v[166:167], s[2:3], 0, v[166:167]
	v_lshl_add_u64 v[166:167], v[162:163], 2, v[166:167]
	global_store_dwordx4 v[166:167], v[136:139], off offset:512
	global_store_dwordx4 v[166:167], v[140:143], off offset:528
;     template <int TYPE>
;     __device__ __forceinline__ void body(f32x4 (&acc)[2][2][4][2], const Unit& u, int wr, int wc, int fr, int fq) const {
;     ...
;             UNROLL for (int ai = 0; ai < 2; ++ai) UNROLL for (int m = 0; m < 4; ++m) {
;                 const int r = rb + ai * 128 + m * 16;
;                 if (r < MT) {
;                     f32x4 v0 = acc[ai][bj][m][0], v1 = acc[ai][bj][m][1];
;                     if (norm64) { const LAS float* xp = xch + ((ai * 128 + m * 16 + lrow) * 4 + (wc & 2)) * 2 + bj; const float rstd = rsqrtf((xp[0] + xp[2]) * (1.f / 64.f) + EPS); v0 = v0 * rstd * g0; v1 = v1 * rstd * g1; }
;                     if (TYPE == 5) { asm volatile("" : "+v"(v0), "+v"(v1));
;                         UNROLL for (int j = 0; j < 4; ++j) { v0[j] = gelu_f(v0[j]); v1[j] = gelu_f(v1[j]); } }
;                     if (norm128) { const LAS float* xp = xch + ((ai * 128 + m * 16 + lrow) * 4) * 2 + bj; const float rstd = rsqrtf(((xp[0] + xp[2]) + (xp[4] + xp[6])) * (1.f / 128.f) + EPS); v0 = v0 * rstd * g0; v1 = v1 * rstd * g1; }
;                     if (TYPE == 4) { UNROLL for (int j = 0; j < 4; ++j) { v0[j] = gelu_f(v0[j]); v1[j] = gelu_f(v1[j]); } }
;                     if (TYPE == 3 || TYPE == 6) { UNROLL for (int j = 0; j < 4; ++j) { v0[j] = silu_f(v0[j]); v1[j] = silu_f(v1[j]); } }
;                     if (TYPE == 2 && r < MP) {
;                         const bf16x8 av = __builtin_bit_cast(bf16x8, pack8(v0, v1));
;                         const int r16 = r - fr;
;                         bf16_t* vtb = bdst + (size_t)((r16 >> 13) * 8 + (col >> 6)) * (8192 * 64) + (size_t)((r16 & 8191) >> 5) * 2048 + (size_t)(((wc & 1) * 2 + ((r16 >> 4) & 1)) * 512);
;                         UNROLL for (int sel = 0; sel < 2; ++sel) {
;                             bf16x8 bsel; UNROLL for (int e = 0; e < 8; ++e) bsel[e] = (8 * fq + e == 16 * sel + fr) ? (short)0x3F80 : (short)0;
;                             const f32x4 dv = __builtin_amdgcn_mfma_f32_16x16x32_bf16(av, bsel, (f32x4){0.f, 0.f, 0.f, 0.f}, 0, 0, 0);
;                             *(u32x2*)(vtb + (size_t)((16 * sel + fr + 32 * (fq & 1)) * 8 + (fq >> 1) * 4)) = pack4(dv);
;                         }
;                     } else {
;                     const size_t bo = headlay ? (tokhead_idx<(TYPE == 1 || TYPE == 2)>(r, col >> 6) * 64 + (col & 63)) : ((size_t)r * 512 + col);
.LBB0_219:
	s_or_b64 exec, exec, s[0:1]
	s_and_saveexec_b64 s[0:1], s[10:11]
	s_cbranch_execz .LBB0_222
	v_mov_b64_e32 v[138:139], v[30:31]
	v_mov_b64_e32 v[142:143], v[26:27]
	v_mov_b64_e32 v[136:137], v[28:29]
	v_mov_b64_e32 v[140:141], v[24:25]
	v_readlane_b32 s2, v254, 40
	v_mul_f32_e32 v152, 0x3d372713, v136
	v_mul_f32_e32 v152, v136, v152
	v_fma_f32 v152, v136, v152, v136
	v_mul_f32_e32 v152, 0x3fcc422a, v152
	v_mul_f32_e32 v152, 0xbfb8aa3b, v152
	v_exp_f32_e32 v152, v152
	s_nop 0
	v_add_f32_e32 v152, 1.0, v152
	v_rcp_f32_e32 v166, v152
	v_mul_f32_e32 v152, 0x3d372713, v140
	v_mul_f32_e32 v152, v140, v152
	v_fma_f32 v152, v140, v152, v140
	v_mul_f32_e32 v152, 0x3fcc422a, v152
	v_mul_f32_e32 v152, 0xbfb8aa3b, v152
	v_exp_f32_e32 v152, v152
	s_nop 0
	v_add_f32_e32 v152, 1.0, v152
	v_rcp_f32_e32 v168, v152
	v_mul_f32_e32 v152, 0x3d372713, v137
	v_mul_f32_e32 v152, v137, v152
	v_fma_f32 v152, v137, v152, v137
	v_mul_f32_e32 v152, 0x3fcc422a, v152
	v_mul_f32_e32 v152, 0xbfb8aa3b, v152
	v_exp_f32_e32 v152, v152
	s_nop 0
	v_add_f32_e32 v152, 1.0, v152
	v_rcp_f32_e32 v167, v152
	v_mul_f32_e32 v152, 0x3d372713, v141
	v_mul_f32_e32 v152, v141, v152
	v_fma_f32 v152, v141, v152, v141
	v_mul_f32_e32 v152, 0x3fcc422a, v152
	v_mul_f32_e32 v152, 0xbfb8aa3b, v152
	v_exp_f32_e32 v152, v152
	v_pk_mul_f32 v[136:137], v[136:137], v[166:167]
	v_add_f32_e32 v152, 1.0, v152
	v_rcp_f32_e32 v169, v152
	v_mul_f32_e32 v152, 0x3d372713, v138
	v_mul_f32_e32 v152, v138, v152
	v_fma_f32 v152, v138, v152, v138
	v_mul_f32_e32 v152, 0x3fcc422a, v152
	v_mul_f32_e32 v152, 0xbfb8aa3b, v152
	v_exp_f32_e32 v152, v152
	v_pk_mul_f32 v[140:141], v[140:141], v[168:169]
	v_add_f32_e32 v152, 1.0, v152
	v_rcp_f32_e32 v170, v152
	v_mul_f32_e32 v152, 0x3d372713, v142
	v_mul_f32_e32 v152, v142, v152
	v_fma_f32 v152, v142, v152, v142
	v_mul_f32_e32 v152, 0x3fcc422a, v152
	v_mul_f32_e32 v152, 0xbfb8aa3b, v152
	v_exp_f32_e32 v152, v152
	s_nop 0
	v_add_f32_e32 v152, 1.0, v152
	v_rcp_f32_e32 v182, v152
	v_mul_f32_e32 v152, 0x3d372713, v139
	v_mul_f32_e32 v152, v139, v152
	v_fma_f32 v152, v139, v152, v139
	v_mul_f32_e32 v152, 0x3fcc422a, v152
	v_mul_f32_e32 v152, 0xbfb8aa3b, v152
	v_exp_f32_e32 v152, v152
	s_nop 0
	v_add_f32_e32 v152, 1.0, v152
	v_rcp_f32_e32 v171, v152
	v_mul_f32_e32 v152, 0x3d372713, v143
	v_mul_f32_e32 v152, v143, v152
	v_fma_f32 v152, v143, v152, v143
	v_mul_f32_e32 v152, 0x3fcc422a, v152
	v_mul_f32_e32 v152, 0xbfb8aa3b, v152
	v_exp_f32_e32 v152, v152
	v_pk_mul_f32 v[138:139], v[138:139], v[170:171]
	v_add_f32_e32 v152, 1.0, v152
	v_rcp_f32_e32 v183, v152
	v_lshl_add_u32 v152, v198, 5, s2
	ds_read2_b32 v[166:167], v152 offset0:1 offset1:3
	ds_read2_b32 v[168:169], v152 offset0:5 offset1:7
	v_pk_mul_f32 v[142:143], v[142:143], v[182:183]
	s_waitcnt lgkmcnt(0)
	v_mov_b32_e32 v170, v166
	v_mov_b32_e32 v171, v168
	v_mov_b32_e32 v168, v167
	v_pk_add_f32 v[166:167], v[170:171], v[168:169]
	v_lshlrev_b64 v[170:171], 10, v[172:173]
	v_add_f32_e32 v152, v166, v167
	v_fmamk_f32 v152, v152, 0x3c000000, v190
	v_cmp_gt_f32_e32 vcc, s49, v152
	v_mul_f32_e32 v165, 0x4b800000, v152
	v_lshl_add_u64 v[170:171], v[180:181], 0, v[170:171]
	v_cndmask_b32_e32 v152, v152, v165, vcc
	v_rsq_f32_e32 v152, v152
	s_nop 0
	v_mul_f32_e32 v165, 0x45800000, v152
	v_cndmask_b32_e32 v152, v152, v165, vcc
	v_pk_mul_f32 v[136:137], v[152:153], v[136:137] op_sel_hi:[0,1]
	v_pk_mul_f32 v[138:139], v[152:153], v[138:139] op_sel_hi:[0,1]
	v_pk_mul_f32 v[140:141], v[152:153], v[140:141] op_sel_hi:[0,1]
	v_pk_mul_f32 v[142:143], v[152:153], v[142:143] op_sel_hi:[0,1]
	v_pk_mul_f32 v[138:139], v[134:135], v[138:139]
	v_pk_mul_f32 v[136:137], v[132:133], v[136:137]
	v_pk_mul_f32 v[142:143], v[130:131], v[142:143]
	v_pk_mul_f32 v[140:141], v[128:129], v[140:141]
	v_cvt_pk_bf16_f32 v166, v136, v137
	v_cvt_pk_bf16_f32 v167, v138, v139
	v_cvt_pk_bf16_f32 v168, v140, v141
	v_cvt_pk_bf16_f32 v169, v142, v143
	v_cmp_lt_i32_e32 vcc, s33, v164
	global_store_dwordx4 v[170:171], v[166:169], off
	s_and_b64 exec, exec, vcc
	s_cbranch_execz .LBB0_222
	v_add_u32_e32 v152, 0xffffc080, v164
	v_readlane_b32 s2, v254, 43
	v_lshlrev_b64 v[166:167], 11, v[152:153]
	v_readlane_b32 s3, v254, 44
	s_nop 1
	v_lshl_add_u64 v[166:167], s[2:3], 0, v[166:167]
	v_lshl_add_u64 v[166:167], v[162:163], 2, v[166:167]
	global_store_dwordx4 v[166:167], v[136:139], off offset:512
	global_store_dwordx4 v[166:167], v[140:143], off offset:528
;     template <int TYPE>
;     __device__ __forceinline__ void body(f32x4 (&acc)[2][2][4][2], const Unit& u, int wr, int wc, int fr, int fq) const {
;     ...
;             UNROLL for (int ai = 0; ai < 2; ++ai) UNROLL for (int m = 0; m < 4; ++m) {
;                 const int r = rb + ai * 128 + m * 16;
;                 if (r < MT) {
;                     f32x4 v0 = acc[ai][bj][m][0], v1 = acc[ai][bj][m][1];
;                     if (norm64) { const LAS float* xp = xch + ((ai * 128 + m * 16 + lrow) * 4 + (wc & 2)) * 2 + bj; const float rstd = rsqrtf((xp[0] + xp[2]) * (1.f / 64.f) + EPS); v0 = v0 * rstd * g0; v1 = v1 * rstd * g1; }
;                     if (TYPE == 5) { asm volatile("" : "+v"(v0), "+v"(v1));
;                         UNROLL for (int j = 0; j < 4; ++j) { v0[j] = gelu_f(v0[j]); v1[j] = gelu_f(v1[j]); } }
;                     if (norm128) { const LAS float* xp = xch + ((ai * 128 + m * 16 + lrow) * 4) * 2 + bj; const float rstd = rsqrtf(((xp[0] + xp[2]) + (xp[4] + xp[6])) * (1.f / 128.f) + EPS); v0 = v0 * rstd * g0; v1 = v1 * rstd * g1; }
;                     if (TYPE == 4) { UNROLL for (int j = 0; j < 4; ++j) { v0[j] = gelu_f(v0[j]); v1[j] = gelu_f(v1[j]); } }
;                     if (TYPE == 3 || TYPE == 6) { UNROLL for (int j = 0; j < 4; ++j) { v0[j] = silu_f(v0[j]); v1[j] = silu_f(v1[j]); } }
;                     if (TYPE == 2 && r < MP) {
;                         const bf16x8 av = __builtin_bit_cast(bf16x8, pack8(v0, v1));
;                         const int r16 = r - fr;
;                         bf16_t* vtb = bdst + (size_t)((r16 >> 13) * 8 + (col >> 6)) * (8192 * 64) + (size_t)((r16 & 8191) >> 5) * 2048 + (size_t)(((wc & 1) * 2 + ((r16 >> 4) & 1)) * 512);
;                         UNROLL for (int sel = 0; sel < 2; ++sel) {
;                             bf16x8 bsel; UNROLL for (int e = 0; e < 8; ++e) bsel[e] = (8 * fq + e == 16 * sel + fr) ? (short)0x3F80 : (short)0;
;                             const f32x4 dv = __builtin_amdgcn_mfma_f32_16x16x32_bf16(av, bsel, (f32x4){0.f, 0.f, 0.f, 0.f}, 0, 0, 0);
;                             *(u32x2*)(vtb + (size_t)((16 * sel + fr + 32 * (fq & 1)) * 8 + (fq >> 1) * 4)) = pack4(dv);
;                         }
;                     } else {
;                     const size_t bo = headlay ? (tokhead_idx<(TYPE == 1 || TYPE == 2)>(r, col >> 6) * 64 + (col & 63)) : ((size_t)r * 512 + col);
.LBB0_222:
	s_or_b64 exec, exec, s[0:1]
	s_and_saveexec_b64 s[0:1], s[12:13]
	s_cbranch_execz .LBB0_225
	v_mov_b64_e32 v[138:139], v[22:23]
	v_mov_b64_e32 v[142:143], v[18:19]
	v_mov_b64_e32 v[136:137], v[20:21]
	v_mov_b64_e32 v[140:141], v[16:17]
	s_movk_i32 s2, 0x3f6f
	v_mul_f32_e32 v152, 0x3d372713, v136
	v_mul_f32_e32 v152, v136, v152
	v_fma_f32 v152, v136, v152, v136
	v_mul_f32_e32 v152, 0x3fcc422a, v152
	v_mul_f32_e32 v152, 0xbfb8aa3b, v152
	v_exp_f32_e32 v152, v152
	s_nop 0
	v_add_f32_e32 v152, 1.0, v152
	v_rcp_f32_e32 v166, v152
	v_mul_f32_e32 v152, 0x3d372713, v140
	v_mul_f32_e32 v152, v140, v152
	v_fma_f32 v152, v140, v152, v140
	v_mul_f32_e32 v152, 0x3fcc422a, v152
	v_mul_f32_e32 v152, 0xbfb8aa3b, v152
	v_exp_f32_e32 v152, v152
	s_nop 0
	v_add_f32_e32 v152, 1.0, v152
	v_rcp_f32_e32 v168, v152
	v_mul_f32_e32 v152, 0x3d372713, v137
	v_mul_f32_e32 v152, v137, v152
	v_fma_f32 v152, v137, v152, v137
	v_mul_f32_e32 v152, 0x3fcc422a, v152
	v_mul_f32_e32 v152, 0xbfb8aa3b, v152
	v_exp_f32_e32 v152, v152
	s_nop 0
	v_add_f32_e32 v152, 1.0, v152
	v_rcp_f32_e32 v167, v152
	v_mul_f32_e32 v152, 0x3d372713, v141
	v_mul_f32_e32 v152, v141, v152
	v_fma_f32 v152, v141, v152, v141
	v_mul_f32_e32 v152, 0x3fcc422a, v152
	v_mul_f32_e32 v152, 0xbfb8aa3b, v152
	v_exp_f32_e32 v152, v152
	v_pk_mul_f32 v[136:137], v[136:137], v[166:167]
	v_add_f32_e32 v152, 1.0, v152
	v_rcp_f32_e32 v169, v152
	v_mul_f32_e32 v152, 0x3d372713, v138
	v_mul_f32_e32 v152, v138, v152
	v_fma_f32 v152, v138, v152, v138
	v_mul_f32_e32 v152, 0x3fcc422a, v152
	v_mul_f32_e32 v152, 0xbfb8aa3b, v152
	v_exp_f32_e32 v152, v152
	v_pk_mul_f32 v[140:141], v[140:141], v[168:169]
	v_add_f32_e32 v152, 1.0, v152
	v_rcp_f32_e32 v170, v152
	v_mul_f32_e32 v152, 0x3d372713, v142
	v_mul_f32_e32 v152, v142, v152
	v_fma_f32 v152, v142, v152, v142
	v_mul_f32_e32 v152, 0x3fcc422a, v152
	v_mul_f32_e32 v152, 0xbfb8aa3b, v152
	v_exp_f32_e32 v152, v152
	s_nop 0
	v_add_f32_e32 v152, 1.0, v152
	v_rcp_f32_e32 v172, v152
	v_mul_f32_e32 v152, 0x3d372713, v139
	v_mul_f32_e32 v152, v139, v152
	v_fma_f32 v152, v139, v152, v139
	v_mul_f32_e32 v152, 0x3fcc422a, v152
	v_mul_f32_e32 v152, 0xbfb8aa3b, v152
	v_exp_f32_e32 v152, v152
	s_nop 0
	v_add_f32_e32 v152, 1.0, v152
	v_rcp_f32_e32 v171, v152
	v_mul_f32_e32 v152, 0x3d372713, v143
	v_mul_f32_e32 v152, v143, v152
	v_fma_f32 v152, v143, v152, v143
	v_mul_f32_e32 v152, 0x3fcc422a, v152
	v_mul_f32_e32 v152, 0xbfb8aa3b, v152
	v_exp_f32_e32 v152, v152
	v_pk_mul_f32 v[138:139], v[138:139], v[170:171]
	v_add_f32_e32 v152, 1.0, v152
	v_rcp_f32_e32 v173, v152
	v_add_u32_e32 v152, 0x1000, v197
	ds_read2_b32 v[166:167], v152 offset0:129 offset1:131
	ds_read2_b32 v[168:169], v152 offset0:133 offset1:135
	v_pk_mul_f32 v[142:143], v[142:143], v[172:173]
	s_waitcnt lgkmcnt(0)
	v_mov_b32_e32 v170, v166
	v_mov_b32_e32 v171, v168
	v_mov_b32_e32 v168, v167
	v_pk_add_f32 v[166:167], v[170:171], v[168:169]
	v_lshlrev_b64 v[170:171], 10, v[174:175]
	v_add_f32_e32 v152, v166, v167
	v_fmamk_f32 v152, v152, 0x3c000000, v190
	v_cmp_gt_f32_e32 vcc, s49, v152
	v_mul_f32_e32 v165, 0x4b800000, v152
	v_lshl_add_u64 v[170:171], v[180:181], 0, v[170:171]
	v_cndmask_b32_e32 v152, v152, v165, vcc
	v_rsq_f32_e32 v152, v152
	s_nop 0
	v_mul_f32_e32 v165, 0x45800000, v152
	v_cndmask_b32_e32 v152, v152, v165, vcc
	v_pk_mul_f32 v[136:137], v[152:153], v[136:137] op_sel_hi:[0,1]
	v_pk_mul_f32 v[138:139], v[152:153], v[138:139] op_sel_hi:[0,1]
	v_pk_mul_f32 v[140:141], v[152:153], v[140:141] op_sel_hi:[0,1]
	v_pk_mul_f32 v[142:143], v[152:153], v[142:143] op_sel_hi:[0,1]
	v_pk_mul_f32 v[138:139], v[134:135], v[138:139]
	v_pk_mul_f32 v[136:137], v[132:133], v[136:137]
	v_pk_mul_f32 v[142:143], v[130:131], v[142:143]
	v_pk_mul_f32 v[140:141], v[128:129], v[140:141]
	v_cvt_pk_bf16_f32 v166, v136, v137
	v_cvt_pk_bf16_f32 v167, v138, v139
	v_cvt_pk_bf16_f32 v168, v140, v141
	v_cvt_pk_bf16_f32 v169, v142, v143
	v_cmp_lt_i32_e32 vcc, s2, v164
	global_store_dwordx4 v[170:171], v[166:169], off
	s_and_b64 exec, exec, vcc
	s_cbranch_execz .LBB0_225
	v_add_u32_e32 v152, 0xffffc090, v164
	v_readlane_b32 s2, v254, 43
	v_lshlrev_b64 v[166:167], 11, v[152:153]
	v_readlane_b32 s3, v254, 44
	s_nop 1
	v_lshl_add_u64 v[166:167], s[2:3], 0, v[166:167]
	v_lshl_add_u64 v[166:167], v[162:163], 2, v[166:167]
	global_store_dwordx4 v[166:167], v[136:139], off offset:512
	global_store_dwordx4 v[166:167], v[140:143], off offset:528
;     template <int TYPE>
;     __device__ __forceinline__ void body(f32x4 (&acc)[2][2][4][2], const Unit& u, int wr, int wc, int fr, int fq) const {
;     ...
;             UNROLL for (int ai = 0; ai < 2; ++ai) UNROLL for (int m = 0; m < 4; ++m) {
;                 const int r = rb + ai * 128 + m * 16;
;                 if (r < MT) {
;                     f32x4 v0 = acc[ai][bj][m][0], v1 = acc[ai][bj][m][1];
;                     if (norm64) { const LAS float* xp = xch + ((ai * 128 + m * 16 + lrow) * 4 + (wc & 2)) * 2 + bj; const float rstd = rsqrtf((xp[0] + xp[2]) * (1.f / 64.f) + EPS); v0 = v0 * rstd * g0; v1 = v1 * rstd * g1; }
;                     if (TYPE == 5) { asm volatile("" : "+v"(v0), "+v"(v1));
;                         UNROLL for (int j = 0; j < 4; ++j) { v0[j] = gelu_f(v0[j]); v1[j] = gelu_f(v1[j]); } }
;                     if (norm128) { const LAS float* xp = xch + ((ai * 128 + m * 16 + lrow) * 4) * 2 + bj; const float rstd = rsqrtf(((xp[0] + xp[2]) + (xp[4] + xp[6])) * (1.f / 128.f) + EPS); v0 = v0 * rstd * g0; v1 = v1 * rstd * g1; }
;                     if (TYPE == 4) { UNROLL for (int j = 0; j < 4; ++j) { v0[j] = gelu_f(v0[j]); v1[j] = gelu_f(v1[j]); } }
;                     if (TYPE == 3 || TYPE == 6) { UNROLL for (int j = 0; j < 4; ++j) { v0[j] = silu_f(v0[j]); v1[j] = silu_f(v1[j]); } }
;                     if (TYPE == 2 && r < MP) {
;                         const bf16x8 av = __builtin_bit_cast(bf16x8, pack8(v0, v1));
;                         const int r16 = r - fr;
;                         bf16_t* vtb = bdst + (size_t)((r16 >> 13) * 8 + (col >> 6)) * (8192 * 64) + (size_t)((r16 & 8191) >> 5) * 2048 + (size_t)(((wc & 1) * 2 + ((r16 >> 4) & 1)) * 512);
;                         UNROLL for (int sel = 0; sel < 2; ++sel) {
;                             bf16x8 bsel; UNROLL for (int e = 0; e < 8; ++e) bsel[e] = (8 * fq + e == 16 * sel + fr) ? (short)0x3F80 : (short)0;
;                             const f32x4 dv = __builtin_amdgcn_mfma_f32_16x16x32_bf16(av, bsel, (f32x4){0.f, 0.f, 0.f, 0.f}, 0, 0, 0);
;                             *(u32x2*)(vtb + (size_t)((16 * sel + fr + 32 * (fq & 1)) * 8 + (fq >> 1) * 4)) = pack4(dv);
;                         }
;                     } else {
;                     const size_t bo = headlay ? (tokhead_idx<(TYPE == 1 || TYPE == 2)>(r, col >> 6) * 64 + (col & 63)) : ((size_t)r * 512 + col);
.LBB0_225:
	s_or_b64 exec, exec, s[0:1]
	s_and_saveexec_b64 s[0:1], s[14:15]
	s_cbranch_execz .LBB0_228
	v_mov_b64_e32 v[138:139], v[14:15]
	v_mov_b64_e32 v[142:143], v[10:11]
	v_mov_b64_e32 v[136:137], v[12:13]
	v_mov_b64_e32 v[140:141], v[8:9]
	s_movk_i32 s2, 0x3f5f
	v_mul_f32_e32 v152, 0x3d372713, v136
	v_mul_f32_e32 v152, v136, v152
	v_fma_f32 v152, v136, v152, v136
	v_mul_f32_e32 v152, 0x3fcc422a, v152
	v_mul_f32_e32 v152, 0xbfb8aa3b, v152
	v_exp_f32_e32 v152, v152
	s_nop 0
	v_add_f32_e32 v152, 1.0, v152
	v_rcp_f32_e32 v166, v152
	v_mul_f32_e32 v152, 0x3d372713, v140
	v_mul_f32_e32 v152, v140, v152
	v_fma_f32 v152, v140, v152, v140
	v_mul_f32_e32 v152, 0x3fcc422a, v152
	v_mul_f32_e32 v152, 0xbfb8aa3b, v152
	v_exp_f32_e32 v152, v152
	s_nop 0
	v_add_f32_e32 v152, 1.0, v152
	v_rcp_f32_e32 v168, v152
	v_mul_f32_e32 v152, 0x3d372713, v137
	v_mul_f32_e32 v152, v137, v152
	v_fma_f32 v152, v137, v152, v137
	v_mul_f32_e32 v152, 0x3fcc422a, v152
	v_mul_f32_e32 v152, 0xbfb8aa3b, v152
	v_exp_f32_e32 v152, v152
	s_nop 0
	v_add_f32_e32 v152, 1.0, v152
	v_rcp_f32_e32 v167, v152
	v_mul_f32_e32 v152, 0x3d372713, v141
	v_mul_f32_e32 v152, v141, v152
	v_fma_f32 v152, v141, v152, v141
	v_mul_f32_e32 v152, 0x3fcc422a, v152
	v_mul_f32_e32 v152, 0xbfb8aa3b, v152
	v_exp_f32_e32 v152, v152
	v_pk_mul_f32 v[136:137], v[136:137], v[166:167]
	v_add_f32_e32 v152, 1.0, v152
	v_rcp_f32_e32 v169, v152
	v_mul_f32_e32 v152, 0x3d372713, v138
	v_mul_f32_e32 v152, v138, v152
	v_fma_f32 v152, v138, v152, v138
	v_mul_f32_e32 v152, 0x3fcc422a, v152
	v_mul_f32_e32 v152, 0xbfb8aa3b, v152
	v_exp_f32_e32 v152, v152
	v_pk_mul_f32 v[140:141], v[140:141], v[168:169]
	v_add_f32_e32 v152, 1.0, v152
	v_rcp_f32_e32 v170, v152
	v_mul_f32_e32 v152, 0x3d372713, v142
	v_mul_f32_e32 v152, v142, v152
	v_fma_f32 v152, v142, v152, v142
	v_mul_f32_e32 v152, 0x3fcc422a, v152
	v_mul_f32_e32 v152, 0xbfb8aa3b, v152
	v_exp_f32_e32 v152, v152
	s_nop 0
	v_add_f32_e32 v152, 1.0, v152
	v_rcp_f32_e32 v172, v152
	v_mul_f32_e32 v152, 0x3d372713, v139
	v_mul_f32_e32 v152, v139, v152
	v_fma_f32 v152, v139, v152, v139
	v_mul_f32_e32 v152, 0x3fcc422a, v152
	v_mul_f32_e32 v152, 0xbfb8aa3b, v152
	v_exp_f32_e32 v152, v152
	s_nop 0
	v_add_f32_e32 v152, 1.0, v152
	v_rcp_f32_e32 v171, v152
	v_mul_f32_e32 v152, 0x3d372713, v143
	v_mul_f32_e32 v152, v143, v152
	v_fma_f32 v152, v143, v152, v143
	v_mul_f32_e32 v152, 0x3fcc422a, v152
	v_mul_f32_e32 v152, 0xbfb8aa3b, v152
	v_exp_f32_e32 v152, v152
	v_pk_mul_f32 v[138:139], v[138:139], v[170:171]
	v_add_f32_e32 v152, 1.0, v152
	v_rcp_f32_e32 v173, v152
	v_add_u32_e32 v152, 0x1400, v197
	ds_read2_b32 v[166:167], v152 offset0:1 offset1:3
	ds_read2_b32 v[168:169], v152 offset0:5 offset1:7
	v_pk_mul_f32 v[142:143], v[142:143], v[172:173]
	s_waitcnt lgkmcnt(0)
	v_mov_b32_e32 v170, v166
	v_mov_b32_e32 v171, v168
	v_mov_b32_e32 v168, v167
	v_pk_add_f32 v[166:167], v[170:171], v[168:169]
	v_lshlrev_b64 v[170:171], 10, v[176:177]
	v_add_f32_e32 v152, v166, v167
	v_fmamk_f32 v152, v152, 0x3c000000, v190
	v_cmp_gt_f32_e32 vcc, s49, v152
	v_mul_f32_e32 v165, 0x4b800000, v152
	v_lshl_add_u64 v[170:171], v[180:181], 0, v[170:171]
	v_cndmask_b32_e32 v152, v152, v165, vcc
	v_rsq_f32_e32 v152, v152
	s_nop 0
	v_mul_f32_e32 v165, 0x45800000, v152
	v_cndmask_b32_e32 v152, v152, v165, vcc
	v_pk_mul_f32 v[136:137], v[152:153], v[136:137] op_sel_hi:[0,1]
	v_pk_mul_f32 v[138:139], v[152:153], v[138:139] op_sel_hi:[0,1]
	v_pk_mul_f32 v[140:141], v[152:153], v[140:141] op_sel_hi:[0,1]
	v_pk_mul_f32 v[142:143], v[152:153], v[142:143] op_sel_hi:[0,1]
	v_pk_mul_f32 v[138:139], v[134:135], v[138:139]
	v_pk_mul_f32 v[136:137], v[132:133], v[136:137]
	v_pk_mul_f32 v[142:143], v[130:131], v[142:143]
	v_pk_mul_f32 v[140:141], v[128:129], v[140:141]
	v_cvt_pk_bf16_f32 v166, v136, v137
	v_cvt_pk_bf16_f32 v167, v138, v139
	v_cvt_pk_bf16_f32 v168, v140, v141
	v_cvt_pk_bf16_f32 v169, v142, v143
	v_cmp_lt_i32_e32 vcc, s2, v164
	global_store_dwordx4 v[170:171], v[166:169], off
	s_and_b64 exec, exec, vcc
	s_cbranch_execz .LBB0_228
	v_add_u32_e32 v152, 0xffffc0a0, v164
	v_readlane_b32 s2, v254, 43
	v_lshlrev_b64 v[166:167], 11, v[152:153]
	v_readlane_b32 s3, v254, 44
	s_nop 1
	v_lshl_add_u64 v[166:167], s[2:3], 0, v[166:167]
	v_lshl_add_u64 v[166:167], v[162:163], 2, v[166:167]
	global_store_dwordx4 v[166:167], v[136:139], off offset:512
	global_store_dwordx4 v[166:167], v[140:143], off offset:528
;     template <int TYPE>
;     __device__ __forceinline__ void body(f32x4 (&acc)[2][2][4][2], const Unit& u, int wr, int wc, int fr, int fq) const {
;     ...
;             UNROLL for (int ai = 0; ai < 2; ++ai) UNROLL for (int m = 0; m < 4; ++m) {
;                 const int r = rb + ai * 128 + m * 16;
;                 if (r < MT) {
;                     f32x4 v0 = acc[ai][bj][m][0], v1 = acc[ai][bj][m][1];
;                     if (norm64) { const LAS float* xp = xch + ((ai * 128 + m * 16 + lrow) * 4 + (wc & 2)) * 2 + bj; const float rstd = rsqrtf((xp[0] + xp[2]) * (1.f / 64.f) + EPS); v0 = v0 * rstd * g0; v1 = v1 * rstd * g1; }
;                     if (TYPE == 5) { asm volatile("" : "+v"(v0), "+v"(v1));
;                         UNROLL for (int j = 0; j < 4; ++j) { v0[j] = gelu_f(v0[j]); v1[j] = gelu_f(v1[j]); } }
;                     if (norm128) { const LAS float* xp = xch + ((ai * 128 + m * 16 + lrow) * 4) * 2 + bj; const float rstd = rsqrtf(((xp[0] + xp[2]) + (xp[4] + xp[6])) * (1.f / 128.f) + EPS); v0 = v0 * rstd * g0; v1 = v1 * rstd * g1; }
;                     if (TYPE == 4) { UNROLL for (int j = 0; j < 4; ++j) { v0[j] = gelu_f(v0[j]); v1[j] = gelu_f(v1[j]); } }
;                     if (TYPE == 3 || TYPE == 6) { UNROLL for (int j = 0; j < 4; ++j) { v0[j] = silu_f(v0[j]); v1[j] = silu_f(v1[j]); } }
;                     if (TYPE == 2 && r < MP) {
;                         const bf16x8 av = __builtin_bit_cast(bf16x8, pack8(v0, v1));
;                         const int r16 = r - fr;
;                         bf16_t* vtb = bdst + (size_t)((r16 >> 13) * 8 + (col >> 6)) * (8192 * 64) + (size_t)((r16 & 8191) >> 5) * 2048 + (size_t)(((wc & 1) * 2 + ((r16 >> 4) & 1)) * 512);
;                         UNROLL for (int sel = 0; sel < 2; ++sel) {
;                             bf16x8 bsel; UNROLL for (int e = 0; e < 8; ++e) bsel[e] = (8 * fq + e == 16 * sel + fr) ? (short)0x3F80 : (short)0;
;                             const f32x4 dv = __builtin_amdgcn_mfma_f32_16x16x32_bf16(av, bsel, (f32x4){0.f, 0.f, 0.f, 0.f}, 0, 0, 0);
;                             *(u32x2*)(vtb + (size_t)((16 * sel + fr + 32 * (fq & 1)) * 8 + (fq >> 1) * 4)) = pack4(dv);
;                         }
;                     } else {
;                     const size_t bo = headlay ? (tokhead_idx<(TYPE == 1 || TYPE == 2)>(r, col >> 6) * 64 + (col & 63)) : ((size_t)r * 512 + col);
.LBB0_228:
	s_or_b64 exec, exec, s[0:1]
	s_and_saveexec_b64 s[0:1], s[16:17]
	s_cbranch_execz .LBB0_231
	v_mov_b64_e32 v[138:139], v[2:3]
	v_mov_b64_e32 v[142:143], v[6:7]
	v_mov_b64_e32 v[136:137], v[0:1]
	v_mov_b64_e32 v[140:141], v[4:5]
	s_movk_i32 s2, 0x3f4f
	v_mul_f32_e32 v152, 0x3d372713, v140
	v_mul_f32_e32 v152, v140, v152
	v_fma_f32 v152, v140, v152, v140
	v_mul_f32_e32 v152, 0x3fcc422a, v152
	v_mul_f32_e32 v152, 0xbfb8aa3b, v152
	v_exp_f32_e32 v152, v152
	s_nop 0
	v_add_f32_e32 v152, 1.0, v152
	v_rcp_f32_e32 v166, v152
	v_mul_f32_e32 v152, 0x3d372713, v136
	v_mul_f32_e32 v152, v136, v152
	v_fma_f32 v152, v136, v152, v136
	v_mul_f32_e32 v152, 0x3fcc422a, v152
	v_mul_f32_e32 v152, 0xbfb8aa3b, v152
	v_exp_f32_e32 v152, v152
	s_nop 0
	v_add_f32_e32 v152, 1.0, v152
	v_rcp_f32_e32 v168, v152
	v_mul_f32_e32 v152, 0x3d372713, v141
	v_mul_f32_e32 v152, v141, v152
	v_fma_f32 v152, v141, v152, v141
	v_mul_f32_e32 v152, 0x3fcc422a, v152
	v_mul_f32_e32 v152, 0xbfb8aa3b, v152
	v_exp_f32_e32 v152, v152
	s_nop 0
	v_add_f32_e32 v152, 1.0, v152
	v_rcp_f32_e32 v167, v152
	v_mul_f32_e32 v152, 0x3d372713, v137
	v_mul_f32_e32 v152, v137, v152
	v_fma_f32 v152, v137, v152, v137
	v_mul_f32_e32 v152, 0x3fcc422a, v152
	v_mul_f32_e32 v152, 0xbfb8aa3b, v152
	v_exp_f32_e32 v152, v152
	v_pk_mul_f32 v[140:141], v[140:141], v[166:167]
	v_add_f32_e32 v152, 1.0, v152
	v_rcp_f32_e32 v169, v152
	v_mul_f32_e32 v152, 0x3d372713, v142
	v_mul_f32_e32 v152, v142, v152
	v_fma_f32 v152, v142, v152, v142
	v_mul_f32_e32 v152, 0x3fcc422a, v152
	v_mul_f32_e32 v152, 0xbfb8aa3b, v152
	v_exp_f32_e32 v152, v152
	v_pk_mul_f32 v[136:137], v[136:137], v[168:169]
	v_add_f32_e32 v152, 1.0, v152
	v_rcp_f32_e32 v170, v152
	v_mul_f32_e32 v152, 0x3d372713, v138
	v_mul_f32_e32 v152, v138, v152
	v_fma_f32 v152, v138, v152, v138
	v_mul_f32_e32 v152, 0x3fcc422a, v152
	v_mul_f32_e32 v152, 0xbfb8aa3b, v152
	v_exp_f32_e32 v152, v152
	s_nop 0
	v_add_f32_e32 v152, 1.0, v152
	v_rcp_f32_e32 v172, v152
	v_mul_f32_e32 v152, 0x3d372713, v143
	v_mul_f32_e32 v152, v143, v152
	v_fma_f32 v152, v143, v152, v143
	v_mul_f32_e32 v152, 0x3fcc422a, v152
	v_mul_f32_e32 v152, 0xbfb8aa3b, v152
	v_exp_f32_e32 v152, v152
	s_nop 0
	v_add_f32_e32 v152, 1.0, v152
	v_rcp_f32_e32 v171, v152
	v_mul_f32_e32 v152, 0x3d372713, v139
	v_mul_f32_e32 v152, v139, v152
	v_fma_f32 v152, v139, v152, v139
	v_mul_f32_e32 v152, 0x3fcc422a, v152
	v_mul_f32_e32 v152, 0xbfb8aa3b, v152
	v_exp_f32_e32 v152, v152
	v_pk_mul_f32 v[142:143], v[142:143], v[170:171]
	v_add_f32_e32 v152, 1.0, v152
	v_rcp_f32_e32 v173, v152
	v_add_u32_e32 v152, 0x1400, v197
	ds_read2_b32 v[166:167], v152 offset0:129 offset1:131
	ds_read2_b32 v[168:169], v152 offset0:133 offset1:135
	v_pk_mul_f32 v[138:139], v[138:139], v[172:173]
	s_waitcnt lgkmcnt(0)
	v_mov_b32_e32 v170, v166
	v_mov_b32_e32 v171, v168
	v_mov_b32_e32 v168, v167
	v_pk_add_f32 v[166:167], v[170:171], v[168:169]
	s_nop 0
	v_add_f32_e32 v152, v166, v167
	v_fmamk_f32 v152, v152, 0x3c000000, v190
	v_cmp_gt_f32_e32 vcc, s49, v152
	v_mul_f32_e32 v165, 0x4b800000, v152
	s_nop 0
	v_cndmask_b32_e32 v152, v152, v165, vcc
	v_rsq_f32_e32 v152, v152
	s_nop 0
	v_mul_f32_e32 v165, 0x45800000, v152
	v_cndmask_b32_e32 v152, v152, v165, vcc
	v_pk_mul_f32 v[140:141], v[152:153], v[140:141] op_sel_hi:[0,1]
	v_pk_mul_f32 v[142:143], v[152:153], v[142:143] op_sel_hi:[0,1]
	v_pk_mul_f32 v[136:137], v[152:153], v[136:137] op_sel_hi:[0,1]
	v_pk_mul_f32 v[138:139], v[152:153], v[138:139] op_sel_hi:[0,1]
	v_pk_mul_f32 v[134:135], v[134:135], v[142:143]
	v_pk_mul_f32 v[132:133], v[132:133], v[140:141]
	v_pk_mul_f32 v[130:131], v[130:131], v[138:139]
	v_pk_mul_f32 v[128:129], v[128:129], v[136:137]
	v_lshlrev_b64 v[140:141], 10, v[178:179]
	v_cvt_pk_bf16_f32 v136, v132, v133
	v_cvt_pk_bf16_f32 v137, v134, v135
	v_cvt_pk_bf16_f32 v138, v128, v129
	v_cvt_pk_bf16_f32 v139, v130, v131
	v_lshl_add_u64 v[140:141], v[180:181], 0, v[140:141]
	v_cmp_lt_i32_e32 vcc, s2, v164
	global_store_dwordx4 v[140:141], v[136:139], off
	s_and_b64 exec, exec, vcc
	s_cbranch_execz .LBB0_231
	v_add_u32_e32 v152, 0xffffc0b0, v164
	v_readlane_b32 s2, v254, 43
	v_lshlrev_b64 v[136:137], 11, v[152:153]
	v_readlane_b32 s3, v254, 44
	s_nop 1
	v_lshl_add_u64 v[136:137], s[2:3], 0, v[136:137]
	v_lshl_add_u64 v[136:137], v[162:163], 2, v[136:137]
	global_store_dwordx4 v[136:137], v[132:135], off offset:512
	global_store_dwordx4 v[136:137], v[128:131], off offset:528

;     template <int TYPE>
;     __device__ __forceinline__ void body(f32x4 (&acc)[2][2][4][2], const Unit& u, int wr, int wc, int fr, int fq) const {
;     ...
;                 const int r = rb + ai * 128 + m * 16;
;                 if (r < MT) {
;                     f32x4 v0 = acc[ai][bj][m][0], v1 = acc[ai][bj][m][1];
;                     if (norm64) { const LAS float* xp = xch + ((ai * 128 + m * 16 + lrow) * 4 + (wc & 2)) * 2 + bj; const float rstd = rsqrtf((xp[0] + xp[2]) * (1.f / 64.f) + EPS); v0 = v0 * rstd * g0; v1 = v1 * rstd * g1; }
;                     if (TYPE == 5) { asm volatile("" : "+v"(v0), "+v"(v1));
;                         UNROLL for (int j = 0; j < 4; ++j) { v0[j] = gelu_f(v0[j]); v1[j] = gelu_f(v1[j]); } }
;                     if (norm128) { const LAS float* xp = xch + ((ai * 128 + m * 16 + lrow) * 4) * 2 + bj; const float rstd = rsqrtf(((xp[0] + xp[2]) + (xp[4] + xp[6])) * (1.f / 128.f) + EPS); v0 = v0 * rstd * g0; v1 = v1 * rstd * g1; }
;                     if (TYPE == 4) { UNROLL for (int j = 0; j < 4; ++j) { v0[j] = gelu_f(v0[j]); v1[j] = gelu_f(v1[j]); } }
;                     if (TYPE == 3 || TYPE == 6) { UNROLL for (int j = 0; j < 4; ++j) { v0[j] = silu_f(v0[j]); v1[j] = silu_f(v1[j]); } }
;                     if (TYPE == 2 && r < MP) {
;                         const bf16x8 av = __builtin_bit_cast(bf16x8, pack8(v0, v1));
;                         const int r16 = r - fr;
;                         bf16_t* vtb = bdst + (size_t)((r16 >> 13) * 8 + (col >> 6)) * (8192 * 64) + (size_t)((r16 & 8191) >> 5) * 2048 + (size_t)(((wc & 1) * 2 + ((r16 >> 4) & 1)) * 512);
;                         UNROLL for (int sel = 0; sel < 2; ++sel) {
;                             bf16x8 bsel; UNROLL for (int e = 0; e < 8; ++e) bsel[e] = (8 * fq + e == 16 * sel + fr) ? (short)0x3F80 : (short)0;
;                             const f32x4 dv = __builtin_amdgcn_mfma_f32_16x16x32_bf16(av, bsel, (f32x4){0.f, 0.f, 0.f, 0.f}, 0, 0, 0);
;                             *(u32x2*)(vtb + (size_t)((16 * sel + fr + 32 * (fq & 1)) * 8 + (fq >> 1) * 4)) = pack4(dv);
;                         }
;                     } else {
;                     const size_t bo = headlay ? (tokhead_idx<(TYPE == 1 || TYPE == 2)>(r, col >> 6) * 64 + (col & 63)) : ((size_t)r * 512 + col);
;                     *(u32x4*)(bdst + bo) = pack8(v0, v1);
;                     }
.LBB0_408:
	s_or_b64 exec, exec, s[2:3]
	v_mov_b32_e32 v141, v153
	s_movk_i32 s0, 0x4070
	v_lshl_add_u64 v[140:141], s[82:83], 0, v[140:141]
	v_add_u32_e32 v170, 16, v166
	v_cmp_gt_i32_e64 s[0:1], s0, v166
	s_and_saveexec_b64 s[2:3], s[0:1]
	s_cbranch_execz .LBB0_414
	ds_read2_b32 v[164:165], v167 offset0:128 offset1:130
	s_movk_i32 s4, 0x3ff0
	s_movk_i32 s6, 0x3fef
	v_cmp_gt_i32_e64 s[4:5], s4, v166
	v_cmp_lt_i32_e64 s[6:7], s6, v166
	s_and_saveexec_b64 s[8:9], s[6:7]
	s_xor_b64 s[6:7], exec, s[8:9]
	v_add_u32_e32 v168, 0xffffc010, v166
	v_lshrrev_b32_e32 v142, 1, v168
	v_and_b32_e32 v142, 0x7ffffff8, v142
	v_add_u32_e32 v142, v142, v179
	v_mad_i64_i32 v[142:143], s[8:9], v142, s44, v[152:153]
	s_or_saveexec_b64 s[6:7], s[6:7]
	v_mov_b64_e32 v[162:163], 0x2020000
	s_xor_b64 exec, exec, s[6:7]
	v_ashrrev_i32_e32 v142, 10, v170
	v_and_b32_e32 v142, -8, v142
	v_add_u32_e32 v142, v142, v179
	v_ashrrev_i32_e32 v143, 31, v142
	v_lshlrev_b64 v[142:143], 13, v[142:143]
	v_and_or_b32 v142, v170, s97, v142
	v_add_u32_e32 v168, 0xffffc010, v166
	v_mov_b64_e32 v[162:163], 0x1020000
	s_or_b64 exec, exec, s[6:7]
	s_waitcnt lgkmcnt(0)
	v_add_f32_e32 v163, v164, v165
	v_fmamk_f32 v163, v163, 0x3c800000, v190
	v_mul_f32_e32 v164, 0x4b800000, v163
	v_cmp_gt_f32_e64 s[6:7], s49, v163
	v_lshlrev_b64 v[142:143], 7, v[142:143]
	v_lshl_add_u64 v[142:143], v[138:139], 0, v[142:143]
	v_cndmask_b32_e64 v163, v163, v164, s[6:7]
	v_rsq_f32_e32 v163, v163
	v_lshlrev_b32_e32 v162, 2, v162
	v_mul_f32_e32 v164, 0x45800000, v163
	v_cndmask_b32_e64 v164, v163, v164, s[6:7]
	v_pk_mul_f32 v[172:173], v[116:117], v[164:165] op_sel_hi:[1,0]
	v_pk_mul_f32 v[174:175], v[118:119], v[164:165] op_sel_hi:[1,0]
	v_pk_mul_f32 v[176:177], v[112:113], v[164:165] op_sel_hi:[1,0]
	v_pk_mul_f32 v[164:165], v[114:115], v[164:165] op_sel_hi:[1,0]
	v_pk_mul_f32 v[174:175], v[134:135], v[174:175]
	v_pk_mul_f32 v[172:173], v[132:133], v[172:173]
	v_pk_mul_f32 v[182:183], v[130:131], v[164:165]
	v_pk_mul_f32 v[180:181], v[128:129], v[176:177]
	v_cvt_pk_bf16_f32 v200, v172, v173
	v_cvt_pk_bf16_f32 v201, v174, v175
	v_cvt_pk_bf16_f32 v202, v180, v181
	v_cvt_pk_bf16_f32 v203, v182, v183
	global_store_dwordx4 v[142:143], v[200:203], off
	v_ashrrev_i32_e32 v142, 31, v170
	v_cndmask_b32_e64 v143, 0, v142, s[4:5]
	v_cndmask_b32_e64 v142, v168, v170, s[4:5]
	v_lshlrev_b64 v[142:143], 11, v[142:143]
	v_lshl_add_u64 v[142:143], s[66:67], 0, v[142:143]
	v_mov_b32_e32 v163, v153
	v_lshl_add_u64 v[142:143], v[142:143], 0, v[162:163]
	v_lshl_add_u64 v[142:143], v[136:137], 2, v[142:143]
	global_store_dwordx4 v[142:143], v[172:175], off nt
	global_store_dwordx4 v[142:143], v[180:183], off offset:16 nt
.LBB0_414:
	s_or_b64 exec, exec, s[2:3]
	s_movk_i32 s2, 0x4060
	v_add_u32_e32 v171, 32, v166
	v_cmp_gt_i32_e64 s[4:5], s2, v166
	v_add_u32_e32 v168, 0x400, v167
	s_and_saveexec_b64 s[2:3], s[4:5]
	s_cbranch_execz .LBB0_420
	ds_read2_b32 v[164:165], v168 offset1:2
	s_movk_i32 s8, 0x3fdf
	v_cmp_gt_i32_e64 s[6:7], s30, v166
	v_cmp_lt_i32_e64 s[8:9], s8, v166
	s_and_saveexec_b64 s[10:11], s[8:9]
	s_xor_b64 s[8:9], exec, s[10:11]
	v_add_u32_e32 v172, 0xffffc020, v166
	v_lshrrev_b32_e32 v142, 1, v172
	v_and_b32_e32 v142, 0x7ffffff8, v142
	v_add_u32_e32 v142, v142, v179
	v_mad_i64_i32 v[142:143], s[10:11], v142, s44, v[152:153]
	s_or_saveexec_b64 s[8:9], s[8:9]
	v_mov_b64_e32 v[162:163], 0x2020000
	s_xor_b64 exec, exec, s[8:9]
	v_ashrrev_i32_e32 v142, 10, v171
	v_and_b32_e32 v142, -8, v142
	v_add_u32_e32 v142, v142, v179
	v_ashrrev_i32_e32 v143, 31, v142
	v_lshlrev_b64 v[142:143], 13, v[142:143]
	v_and_or_b32 v142, v171, s97, v142
	v_add_u32_e32 v172, 0xffffc020, v166
	v_mov_b64_e32 v[162:163], 0x1020000
	s_or_b64 exec, exec, s[8:9]
	s_waitcnt lgkmcnt(0)
	v_add_f32_e32 v163, v164, v165
	v_fmamk_f32 v163, v163, 0x3c800000, v190
	v_mul_f32_e32 v164, 0x4b800000, v163
	v_cmp_gt_f32_e64 s[8:9], s49, v163
	v_lshlrev_b64 v[142:143], 7, v[142:143]
	v_lshl_add_u64 v[142:143], v[138:139], 0, v[142:143]
	v_cndmask_b32_e64 v163, v163, v164, s[8:9]
	v_rsq_f32_e32 v163, v163
	v_lshlrev_b32_e32 v162, 2, v162
	v_mul_f32_e32 v164, 0x45800000, v163
	v_cndmask_b32_e64 v164, v163, v164, s[8:9]
	v_pk_mul_f32 v[174:175], v[108:109], v[164:165] op_sel_hi:[1,0]
	v_pk_mul_f32 v[176:177], v[110:111], v[164:165] op_sel_hi:[1,0]
	v_pk_mul_f32 v[180:181], v[104:105], v[164:165] op_sel_hi:[1,0]
	v_pk_mul_f32 v[164:165], v[106:107], v[164:165] op_sel_hi:[1,0]
	v_pk_mul_f32 v[176:177], v[134:135], v[176:177]
	v_pk_mul_f32 v[174:175], v[132:133], v[174:175]
	v_pk_mul_f32 v[182:183], v[130:131], v[164:165]
	v_pk_mul_f32 v[180:181], v[128:129], v[180:181]
	v_cvt_pk_bf16_f32 v200, v174, v175
	v_cvt_pk_bf16_f32 v201, v176, v177
	v_cvt_pk_bf16_f32 v202, v180, v181
	v_cvt_pk_bf16_f32 v203, v182, v183
	global_store_dwordx4 v[142:143], v[200:203], off
	v_ashrrev_i32_e32 v142, 31, v171
	v_cndmask_b32_e64 v143, 0, v142, s[6:7]
	v_cndmask_b32_e64 v142, v172, v171, s[6:7]
	v_lshlrev_b64 v[142:143], 11, v[142:143]
	v_lshl_add_u64 v[142:143], s[66:67], 0, v[142:143]
	v_mov_b32_e32 v163, v153
	v_lshl_add_u64 v[142:143], v[142:143], 0, v[162:163]
	v_lshl_add_u64 v[142:143], v[136:137], 2, v[142:143]
	global_store_dwordx4 v[142:143], v[174:177], off nt
	global_store_dwordx4 v[142:143], v[180:183], off offset:16 nt
;     template <int TYPE>
;     __device__ __forceinline__ void body(f32x4 (&acc)[2][2][4][2], const Unit& u, int wr, int wc, int fr, int fq) const {
;     ...
;                 const int r = rb + ai * 128 + m * 16;
;                 if (r < MT) {
;                     f32x4 v0 = acc[ai][bj][m][0], v1 = acc[ai][bj][m][1];
;                     if (norm64) { const LAS float* xp = xch + ((ai * 128 + m * 16 + lrow) * 4 + (wc & 2)) * 2 + bj; const float rstd = rsqrtf((xp[0] + xp[2]) * (1.f / 64.f) + EPS); v0 = v0 * rstd * g0; v1 = v1 * rstd * g1; }
;                     if (TYPE == 5) { asm volatile("" : "+v"(v0), "+v"(v1));
;                         UNROLL for (int j = 0; j < 4; ++j) { v0[j] = gelu_f(v0[j]); v1[j] = gelu_f(v1[j]); } }
;                     if (norm128) { const LAS float* xp = xch + ((ai * 128 + m * 16 + lrow) * 4) * 2 + bj; const float rstd = rsqrtf(((xp[0] + xp[2]) + (xp[4] + xp[6])) * (1.f / 128.f) + EPS); v0 = v0 * rstd * g0; v1 = v1 * rstd * g1; }
;                     if (TYPE == 4) { UNROLL for (int j = 0; j < 4; ++j) { v0[j] = gelu_f(v0[j]); v1[j] = gelu_f(v1[j]); } }
;                     if (TYPE == 3 || TYPE == 6) { UNROLL for (int j = 0; j < 4; ++j) { v0[j] = silu_f(v0[j]); v1[j] = silu_f(v1[j]); } }
;                     if (TYPE == 2 && r < MP) {
;                         const bf16x8 av = __builtin_bit_cast(bf16x8, pack8(v0, v1));
;                         const int r16 = r - fr;
;                         bf16_t* vtb = bdst + (size_t)((r16 >> 13) * 8 + (col >> 6)) * (8192 * 64) + (size_t)((r16 & 8191) >> 5) * 2048 + (size_t)(((wc & 1) * 2 + ((r16 >> 4) & 1)) * 512);
;                         UNROLL for (int sel = 0; sel < 2; ++sel) {
;                             bf16x8 bsel; UNROLL for (int e = 0; e < 8; ++e) bsel[e] = (8 * fq + e == 16 * sel + fr) ? (short)0x3F80 : (short)0;
;                             const f32x4 dv = __builtin_amdgcn_mfma_f32_16x16x32_bf16(av, bsel, (f32x4){0.f, 0.f, 0.f, 0.f}, 0, 0, 0);
;                             *(u32x2*)(vtb + (size_t)((16 * sel + fr + 32 * (fq & 1)) * 8 + (fq >> 1) * 4)) = pack4(dv);
;                         }
;                     } else {
;                     const size_t bo = headlay ? (tokhead_idx<(TYPE == 1 || TYPE == 2)>(r, col >> 6) * 64 + (col & 63)) : ((size_t)r * 512 + col);
;                     *(u32x4*)(bdst + bo) = pack8(v0, v1);
;                     }
.LBB0_420:
	s_or_b64 exec, exec, s[2:3]
	s_movk_i32 s2, 0x4050
	v_add_u32_e32 v172, 48, v166
	v_cmp_gt_i32_e64 s[6:7], s2, v166
	s_and_saveexec_b64 s[2:3], s[6:7]
	s_cbranch_execz .LBB0_426
	ds_read2_b32 v[164:165], v168 offset0:128 offset1:130
	s_movk_i32 s10, 0x3fcf
	v_cmp_gt_i32_e64 s[8:9], s48, v166
	v_cmp_lt_i32_e64 s[10:11], s10, v166
	s_and_saveexec_b64 s[12:13], s[10:11]
	s_xor_b64 s[10:11], exec, s[12:13]
	v_add_u32_e32 v173, 0xffffc030, v166
	v_lshrrev_b32_e32 v142, 1, v173
	v_and_b32_e32 v142, 0x7ffffff8, v142
	v_add_u32_e32 v142, v142, v179
	v_mad_i64_i32 v[142:143], s[12:13], v142, s44, v[152:153]
	s_or_saveexec_b64 s[10:11], s[10:11]
	v_mov_b64_e32 v[162:163], 0x2020000
	s_xor_b64 exec, exec, s[10:11]
	v_ashrrev_i32_e32 v142, 10, v172
	v_and_b32_e32 v142, -8, v142
	v_add_u32_e32 v142, v142, v179
	v_ashrrev_i32_e32 v143, 31, v142
	v_lshlrev_b64 v[142:143], 13, v[142:143]
	v_and_or_b32 v142, v172, s97, v142
	v_add_u32_e32 v173, 0xffffc030, v166
	v_mov_b64_e32 v[162:163], 0x1020000
	s_or_b64 exec, exec, s[10:11]
	s_waitcnt lgkmcnt(0)
	v_add_f32_e32 v163, v164, v165
	v_fmamk_f32 v163, v163, 0x3c800000, v190
	v_mul_f32_e32 v164, 0x4b800000, v163
	v_cmp_gt_f32_e64 s[10:11], s49, v163
	v_lshlrev_b64 v[142:143], 7, v[142:143]
	v_lshl_add_u64 v[142:143], v[138:139], 0, v[142:143]
	v_cndmask_b32_e64 v163, v163, v164, s[10:11]
	v_rsq_f32_e32 v163, v163
	v_lshlrev_b32_e32 v162, 2, v162
	v_mul_f32_e32 v164, 0x45800000, v163
	v_cndmask_b32_e64 v164, v163, v164, s[10:11]
	v_pk_mul_f32 v[174:175], v[100:101], v[164:165] op_sel_hi:[1,0]
	v_pk_mul_f32 v[176:177], v[102:103], v[164:165] op_sel_hi:[1,0]
	v_pk_mul_f32 v[180:181], v[96:97], v[164:165] op_sel_hi:[1,0]
	v_pk_mul_f32 v[164:165], v[98:99], v[164:165] op_sel_hi:[1,0]
	v_pk_mul_f32 v[176:177], v[134:135], v[176:177]
	v_pk_mul_f32 v[174:175], v[132:133], v[174:175]
	v_pk_mul_f32 v[182:183], v[130:131], v[164:165]
	v_pk_mul_f32 v[180:181], v[128:129], v[180:181]
	v_cvt_pk_bf16_f32 v200, v174, v175
	v_cvt_pk_bf16_f32 v201, v176, v177
	v_cvt_pk_bf16_f32 v202, v180, v181
	v_cvt_pk_bf16_f32 v203, v182, v183
	global_store_dwordx4 v[142:143], v[200:203], off
	v_ashrrev_i32_e32 v142, 31, v172
	v_cndmask_b32_e64 v143, 0, v142, s[8:9]
	v_cndmask_b32_e64 v142, v173, v172, s[8:9]
	v_lshlrev_b64 v[142:143], 11, v[142:143]
	v_lshl_add_u64 v[142:143], s[66:67], 0, v[142:143]
	v_mov_b32_e32 v163, v153
	v_lshl_add_u64 v[142:143], v[142:143], 0, v[162:163]
	v_lshl_add_u64 v[142:143], v[136:137], 2, v[142:143]
	global_store_dwordx4 v[142:143], v[174:177], off nt
	global_store_dwordx4 v[142:143], v[180:183], off offset:16 nt
.LBB0_426:
	s_or_b64 exec, exec, s[2:3]
	v_add_u32_e32 v142, 0x80, v169
	s_movk_i32 s2, 0x3fff
	v_add_u32_e32 v173, 0x80, v166
	v_cmp_lt_i32_e64 s[16:17], s2, v166
	v_cmp_gt_i32_e64 s[8:9], s43, v166
	v_lshl_add_u32 v177, v142, 5, s45
	s_and_saveexec_b64 s[2:3], s[8:9]
	s_cbranch_execz .LBB0_432
	ds_read2_b32 v[164:165], v177 offset1:2
	s_movk_i32 s10, 0x3f80
	v_cmp_gt_i32_e64 s[10:11], s10, v166
	v_cmp_lt_i32_e64 s[12:13], s33, v166
	s_and_saveexec_b64 s[14:15], s[12:13]
	s_xor_b64 s[12:13], exec, s[14:15]
	v_add_u32_e32 v169, 0xffffc080, v166
	v_lshrrev_b32_e32 v142, 1, v169
	v_and_b32_e32 v142, 0x7ffffff8, v142
	v_add_u32_e32 v142, v142, v179
	v_mad_i64_i32 v[142:143], s[14:15], v142, s44, v[152:153]
	s_or_saveexec_b64 s[12:13], s[12:13]
	v_mov_b64_e32 v[162:163], 0x2020000
	s_xor_b64 exec, exec, s[12:13]
	v_ashrrev_i32_e32 v142, 10, v173
	v_and_b32_e32 v142, -8, v142
	v_add_u32_e32 v142, v142, v179
	v_ashrrev_i32_e32 v143, 31, v142
	v_lshlrev_b64 v[142:143], 13, v[142:143]
	v_and_or_b32 v142, v173, s97, v142
	v_add_u32_e32 v169, 0xffffc080, v166
	v_mov_b64_e32 v[162:163], 0x1020000
	s_or_b64 exec, exec, s[12:13]
	s_waitcnt lgkmcnt(0)
	v_add_f32_e32 v163, v164, v165
	v_fmamk_f32 v163, v163, 0x3c800000, v190
	v_mul_f32_e32 v164, 0x4b800000, v163
	v_cmp_gt_f32_e64 s[12:13], s49, v163
	v_lshlrev_b64 v[142:143], 7, v[142:143]
	v_lshl_add_u64 v[142:143], v[138:139], 0, v[142:143]
	v_cndmask_b32_e64 v163, v163, v164, s[12:13]
	v_rsq_f32_e32 v163, v163
	v_lshlrev_b32_e32 v162, 2, v162
	v_mul_f32_e32 v164, 0x45800000, v163
	v_cndmask_b32_e64 v164, v163, v164, s[12:13]
	v_pk_mul_f32 v[174:175], v[92:93], v[164:165] op_sel_hi:[1,0]
	v_pk_mul_f32 v[180:181], v[94:95], v[164:165] op_sel_hi:[1,0]
	v_mov_b32_e32 v163, v153
	v_pk_mul_f32 v[182:183], v[134:135], v[180:181]
	v_pk_mul_f32 v[180:181], v[132:133], v[174:175]
	v_pk_mul_f32 v[174:175], v[88:89], v[164:165] op_sel_hi:[1,0]
	v_pk_mul_f32 v[164:165], v[90:91], v[164:165] op_sel_hi:[1,0]
	v_pk_mul_f32 v[200:201], v[128:129], v[174:175]
	v_pk_mul_f32 v[202:203], v[130:131], v[164:165]
	v_cvt_pk_bf16_f32 v204, v180, v181
	v_cvt_pk_bf16_f32 v205, v182, v183
	v_cvt_pk_bf16_f32 v206, v200, v201
	v_cvt_pk_bf16_f32 v207, v202, v203
	global_store_dwordx4 v[142:143], v[204:207], off
	v_ashrrev_i32_e32 v142, 31, v173
	v_cndmask_b32_e64 v143, 0, v142, s[10:11]
	v_cndmask_b32_e64 v142, v169, v173, s[10:11]
	v_lshlrev_b64 v[142:143], 11, v[142:143]
	v_lshl_add_u64 v[142:143], s[66:67], 0, v[142:143]
	v_lshl_add_u64 v[142:143], v[142:143], 0, v[162:163]
	v_lshl_add_u64 v[142:143], v[136:137], 2, v[142:143]
	global_store_dwordx4 v[142:143], v[180:183], off nt
	global_store_dwordx4 v[142:143], v[200:203], off offset:16 nt
;     template <int TYPE>
;     __device__ __forceinline__ void body(f32x4 (&acc)[2][2][4][2], const Unit& u, int wr, int wc, int fr, int fq) const {
;     ...
;                 const int r = rb + ai * 128 + m * 16;
;                 if (r < MT) {
;                     f32x4 v0 = acc[ai][bj][m][0], v1 = acc[ai][bj][m][1];
;                     if (norm64) { const LAS float* xp = xch + ((ai * 128 + m * 16 + lrow) * 4 + (wc & 2)) * 2 + bj; const float rstd = rsqrtf((xp[0] + xp[2]) * (1.f / 64.f) + EPS); v0 = v0 * rstd * g0; v1 = v1 * rstd * g1; }
;                     if (TYPE == 5) { asm volatile("" : "+v"(v0), "+v"(v1));
;                         UNROLL for (int j = 0; j < 4; ++j) { v0[j] = gelu_f(v0[j]); v1[j] = gelu_f(v1[j]); } }
;                     if (norm128) { const LAS float* xp = xch + ((ai * 128 + m * 16 + lrow) * 4) * 2 + bj; const float rstd = rsqrtf(((xp[0] + xp[2]) + (xp[4] + xp[6])) * (1.f / 128.f) + EPS); v0 = v0 * rstd * g0; v1 = v1 * rstd * g1; }
;                     if (TYPE == 4) { UNROLL for (int j = 0; j < 4; ++j) { v0[j] = gelu_f(v0[j]); v1[j] = gelu_f(v1[j]); } }
;                     if (TYPE == 3 || TYPE == 6) { UNROLL for (int j = 0; j < 4; ++j) { v0[j] = silu_f(v0[j]); v1[j] = silu_f(v1[j]); } }
;                     if (TYPE == 2 && r < MP) {
;                         const bf16x8 av = __builtin_bit_cast(bf16x8, pack8(v0, v1));
;                         const int r16 = r - fr;
;                         bf16_t* vtb = bdst + (size_t)((r16 >> 13) * 8 + (col >> 6)) * (8192 * 64) + (size_t)((r16 & 8191) >> 5) * 2048 + (size_t)(((wc & 1) * 2 + ((r16 >> 4) & 1)) * 512);
;                         UNROLL for (int sel = 0; sel < 2; ++sel) {
;                             bf16x8 bsel; UNROLL for (int e = 0; e < 8; ++e) bsel[e] = (8 * fq + e == 16 * sel + fr) ? (short)0x3F80 : (short)0;
;                             const f32x4 dv = __builtin_amdgcn_mfma_f32_16x16x32_bf16(av, bsel, (f32x4){0.f, 0.f, 0.f, 0.f}, 0, 0, 0);
;                             *(u32x2*)(vtb + (size_t)((16 * sel + fr + 32 * (fq & 1)) * 8 + (fq >> 1) * 4)) = pack4(dv);
;                         }
;                     } else {
;                     const size_t bo = headlay ? (tokhead_idx<(TYPE == 1 || TYPE == 2)>(r, col >> 6) * 64 + (col & 63)) : ((size_t)r * 512 + col);
;                     *(u32x4*)(bdst + bo) = pack8(v0, v1);
;                     }
.LBB0_432:
	s_or_b64 exec, exec, s[2:3]
	s_movk_i32 s2, 0x3fef
	v_cmp_lt_i32_e64 s[18:19], s2, v166
	s_movk_i32 s2, 0x3ff0
	v_add_u32_e32 v174, 0x90, v166
	v_cmp_gt_i32_e64 s[10:11], s2, v166
	v_add_u32_e32 v178, 0x1000, v167
	s_and_saveexec_b64 s[2:3], s[10:11]
	s_cbranch_execz .LBB0_438
	ds_read2_b32 v[164:165], v178 offset0:128 offset1:130
	s_movk_i32 s12, 0x3f70
	s_movk_i32 s14, 0x3f6f
	v_cmp_gt_i32_e64 s[12:13], s12, v166
	v_cmp_lt_i32_e64 s[14:15], s14, v166
	s_and_saveexec_b64 s[20:21], s[14:15]
	s_xor_b64 s[14:15], exec, s[20:21]
	v_add_u32_e32 v169, 0xffffc090, v166
	v_lshrrev_b32_e32 v142, 1, v169
	v_and_b32_e32 v142, 0x7ffffff8, v142
	v_add_u32_e32 v142, v142, v179
	v_mad_i64_i32 v[142:143], s[20:21], v142, s44, v[152:153]
	s_or_saveexec_b64 s[14:15], s[14:15]
	v_mov_b64_e32 v[162:163], 0x2020000
	s_xor_b64 exec, exec, s[14:15]
	v_ashrrev_i32_e32 v142, 10, v174
	v_and_b32_e32 v142, -8, v142
	v_add_u32_e32 v142, v142, v179
	v_ashrrev_i32_e32 v143, 31, v142
	v_lshlrev_b64 v[142:143], 13, v[142:143]
	v_and_or_b32 v142, v174, s97, v142
	v_add_u32_e32 v169, 0xffffc090, v166
	v_mov_b64_e32 v[162:163], 0x1020000
	s_or_b64 exec, exec, s[14:15]
	s_waitcnt lgkmcnt(0)
	v_add_f32_e32 v163, v164, v165
	v_fmamk_f32 v163, v163, 0x3c800000, v190
	v_mul_f32_e32 v164, 0x4b800000, v163
	v_cmp_gt_f32_e64 s[14:15], s49, v163
	v_lshlrev_b64 v[142:143], 7, v[142:143]
	v_lshl_add_u64 v[142:143], v[138:139], 0, v[142:143]
	v_cndmask_b32_e64 v163, v163, v164, s[14:15]
	v_rsq_f32_e32 v163, v163
	v_lshlrev_b32_e32 v162, 2, v162
	v_mul_f32_e32 v164, 0x45800000, v163
	v_cndmask_b32_e64 v164, v163, v164, s[14:15]
	v_pk_mul_f32 v[180:181], v[84:85], v[164:165] op_sel_hi:[1,0]
	v_pk_mul_f32 v[182:183], v[86:87], v[164:165] op_sel_hi:[1,0]
	v_pk_mul_f32 v[200:201], v[80:81], v[164:165] op_sel_hi:[1,0]
	v_pk_mul_f32 v[164:165], v[82:83], v[164:165] op_sel_hi:[1,0]
	v_pk_mul_f32 v[182:183], v[134:135], v[182:183]
	v_pk_mul_f32 v[180:181], v[132:133], v[180:181]
	v_pk_mul_f32 v[202:203], v[130:131], v[164:165]
	v_pk_mul_f32 v[200:201], v[128:129], v[200:201]
	v_cvt_pk_bf16_f32 v204, v180, v181
	v_cvt_pk_bf16_f32 v205, v182, v183
	v_cvt_pk_bf16_f32 v206, v200, v201
	v_cvt_pk_bf16_f32 v207, v202, v203
	global_store_dwordx4 v[142:143], v[204:207], off
	v_ashrrev_i32_e32 v142, 31, v174
	v_cndmask_b32_e64 v143, 0, v142, s[12:13]
	v_cndmask_b32_e64 v142, v169, v174, s[12:13]
	v_lshlrev_b64 v[142:143], 11, v[142:143]
	v_lshl_add_u64 v[142:143], s[66:67], 0, v[142:143]
	v_mov_b32_e32 v163, v153
	v_lshl_add_u64 v[142:143], v[142:143], 0, v[162:163]
	v_lshl_add_u64 v[142:143], v[136:137], 2, v[142:143]
	global_store_dwordx4 v[142:143], v[180:183], off nt
	global_store_dwordx4 v[142:143], v[200:203], off offset:16 nt
;     template <int TYPE>
;     __device__ __forceinline__ void body(f32x4 (&acc)[2][2][4][2], const Unit& u, int wr, int wc, int fr, int fq) const {
;     ...
;                 const int r = rb + ai * 128 + m * 16;
;                 if (r < MT) {
;                     f32x4 v0 = acc[ai][bj][m][0], v1 = acc[ai][bj][m][1];
;                     if (norm64) { const LAS float* xp = xch + ((ai * 128 + m * 16 + lrow) * 4 + (wc & 2)) * 2 + bj; const float rstd = rsqrtf((xp[0] + xp[2]) * (1.f / 64.f) + EPS); v0 = v0 * rstd * g0; v1 = v1 * rstd * g1; }
;                     if (TYPE == 5) { asm volatile("" : "+v"(v0), "+v"(v1));
;                         UNROLL for (int j = 0; j < 4; ++j) { v0[j] = gelu_f(v0[j]); v1[j] = gelu_f(v1[j]); } }
;                     if (norm128) { const LAS float* xp = xch + ((ai * 128 + m * 16 + lrow) * 4) * 2 + bj; const float rstd = rsqrtf(((xp[0] + xp[2]) + (xp[4] + xp[6])) * (1.f / 128.f) + EPS); v0 = v0 * rstd * g0; v1 = v1 * rstd * g1; }
;                     if (TYPE == 4) { UNROLL for (int j = 0; j < 4; ++j) { v0[j] = gelu_f(v0[j]); v1[j] = gelu_f(v1[j]); } }
;                     if (TYPE == 3 || TYPE == 6) { UNROLL for (int j = 0; j < 4; ++j) { v0[j] = silu_f(v0[j]); v1[j] = silu_f(v1[j]); } }
;                     if (TYPE == 2 && r < MP) {
;                         const bf16x8 av = __builtin_bit_cast(bf16x8, pack8(v0, v1));
;                         const int r16 = r - fr;
;                         bf16_t* vtb = bdst + (size_t)((r16 >> 13) * 8 + (col >> 6)) * (8192 * 64) + (size_t)((r16 & 8191) >> 5) * 2048 + (size_t)(((wc & 1) * 2 + ((r16 >> 4) & 1)) * 512);
;                         UNROLL for (int sel = 0; sel < 2; ++sel) {
;                             bf16x8 bsel; UNROLL for (int e = 0; e < 8; ++e) bsel[e] = (8 * fq + e == 16 * sel + fr) ? (short)0x3F80 : (short)0;
;                             const f32x4 dv = __builtin_amdgcn_mfma_f32_16x16x32_bf16(av, bsel, (f32x4){0.f, 0.f, 0.f, 0.f}, 0, 0, 0);
;                             *(u32x2*)(vtb + (size_t)((16 * sel + fr + 32 * (fq & 1)) * 8 + (fq >> 1) * 4)) = pack4(dv);
;                         }
;                     } else {
;                     const size_t bo = headlay ? (tokhead_idx<(TYPE == 1 || TYPE == 2)>(r, col >> 6) * 64 + (col & 63)) : ((size_t)r * 512 + col);
;                     *(u32x4*)(bdst + bo) = pack8(v0, v1);
;                     }
.LBB0_438:
	s_or_b64 exec, exec, s[2:3]
	s_movk_i32 s2, 0x3fdf
	v_add_u32_e32 v176, 0xa0, v166
	v_cmp_lt_i32_e64 s[20:21], s2, v166
	v_cmp_gt_i32_e64 s[12:13], s30, v166
	v_add_u32_e32 v169, 0x1400, v167
	s_and_saveexec_b64 s[2:3], s[12:13]
	s_cbranch_execz .LBB0_444
	ds_read2_b32 v[164:165], v169 offset1:2
	s_movk_i32 s14, 0x3f60
	s_movk_i32 s22, 0x3f5f
	v_cmp_gt_i32_e64 s[14:15], s14, v166
	v_cmp_lt_i32_e64 s[22:23], s22, v166
	s_and_saveexec_b64 s[24:25], s[22:23]
	s_xor_b64 s[22:23], exec, s[24:25]
	v_add_u32_e32 v175, 0xffffc0a0, v166
	v_lshrrev_b32_e32 v142, 1, v175
	v_and_b32_e32 v142, 0x7ffffff8, v142
	v_add_u32_e32 v142, v142, v179
	v_mad_i64_i32 v[142:143], s[24:25], v142, s44, v[152:153]
	s_or_saveexec_b64 s[22:23], s[22:23]
	v_mov_b64_e32 v[162:163], 0x2020000
	s_xor_b64 exec, exec, s[22:23]
	v_ashrrev_i32_e32 v142, 10, v176
	v_and_b32_e32 v142, -8, v142
	v_add_u32_e32 v142, v142, v179
	v_ashrrev_i32_e32 v143, 31, v142
	v_lshlrev_b64 v[142:143], 13, v[142:143]
	v_and_or_b32 v142, v176, s97, v142
	v_add_u32_e32 v175, 0xffffc0a0, v166
	v_mov_b64_e32 v[162:163], 0x1020000
	s_or_b64 exec, exec, s[22:23]
	s_waitcnt lgkmcnt(0)
	v_add_f32_e32 v163, v164, v165
	v_fmamk_f32 v163, v163, 0x3c800000, v190
	v_mul_f32_e32 v164, 0x4b800000, v163
	v_cmp_gt_f32_e64 s[22:23], s49, v163
	v_lshlrev_b64 v[142:143], 7, v[142:143]
	v_lshl_add_u64 v[142:143], v[138:139], 0, v[142:143]
	v_cndmask_b32_e64 v163, v163, v164, s[22:23]
	v_rsq_f32_e32 v163, v163
	v_lshlrev_b32_e32 v162, 2, v162
	v_mul_f32_e32 v164, 0x45800000, v163
	v_cndmask_b32_e64 v164, v163, v164, s[22:23]
	v_pk_mul_f32 v[180:181], v[76:77], v[164:165] op_sel_hi:[1,0]
	v_pk_mul_f32 v[182:183], v[78:79], v[164:165] op_sel_hi:[1,0]
	v_pk_mul_f32 v[200:201], v[72:73], v[164:165] op_sel_hi:[1,0]
	v_pk_mul_f32 v[164:165], v[74:75], v[164:165] op_sel_hi:[1,0]
	v_pk_mul_f32 v[182:183], v[134:135], v[182:183]
	v_pk_mul_f32 v[180:181], v[132:133], v[180:181]
	v_pk_mul_f32 v[202:203], v[130:131], v[164:165]
	v_pk_mul_f32 v[200:201], v[128:129], v[200:201]
	v_cvt_pk_bf16_f32 v204, v180, v181
	v_cvt_pk_bf16_f32 v205, v182, v183
	v_cvt_pk_bf16_f32 v206, v200, v201
	v_cvt_pk_bf16_f32 v207, v202, v203
	global_store_dwordx4 v[142:143], v[204:207], off
	v_ashrrev_i32_e32 v142, 31, v176
	v_cndmask_b32_e64 v143, 0, v142, s[14:15]
	v_cndmask_b32_e64 v142, v175, v176, s[14:15]
	v_lshlrev_b64 v[142:143], 11, v[142:143]
	v_lshl_add_u64 v[142:143], s[66:67], 0, v[142:143]
	v_mov_b32_e32 v163, v153
	v_lshl_add_u64 v[142:143], v[142:143], 0, v[162:163]
	v_lshl_add_u64 v[142:143], v[136:137], 2, v[142:143]
	global_store_dwordx4 v[142:143], v[180:183], off nt
	global_store_dwordx4 v[142:143], v[200:203], off offset:16 nt
.LBB0_444:
	s_or_b64 exec, exec, s[2:3]
	s_movk_i32 s2, 0x3fcf
	v_add_u32_e32 v175, 0xb0, v166
	v_cmp_lt_i32_e64 s[22:23], s2, v166
	v_cmp_gt_i32_e64 s[14:15], s48, v166
	s_and_saveexec_b64 s[2:3], s[14:15]
	s_cbranch_execz .LBB0_450
	ds_read2_b32 v[162:163], v169 offset0:128 offset1:130
	s_movk_i32 s24, 0x3f50
	s_movk_i32 s28, 0x3f4f
	v_cmp_gt_i32_e64 s[24:25], s24, v166
	v_cmp_lt_i32_e64 s[28:29], s28, v166
	s_and_saveexec_b64 s[62:63], s[28:29]
	s_xor_b64 s[28:29], exec, s[62:63]
	v_add_u32_e32 v180, 0xffffc0b0, v166
	v_lshrrev_b32_e32 v142, 1, v180
	v_and_b32_e32 v142, 0x7ffffff8, v142
	v_add_u32_e32 v142, v142, v179
	v_mad_i64_i32 v[142:143], s[62:63], v142, s44, v[152:153]
	s_or_saveexec_b64 s[28:29], s[28:29]
	v_mov_b64_e32 v[164:165], 0x2020000
	s_xor_b64 exec, exec, s[28:29]
	v_ashrrev_i32_e32 v142, 10, v175
	v_and_b32_e32 v142, -8, v142
	v_add_u32_e32 v142, v142, v179
	v_ashrrev_i32_e32 v143, 31, v142
	v_lshlrev_b64 v[142:143], 13, v[142:143]
	v_and_or_b32 v142, v175, s97, v142
	v_add_u32_e32 v180, 0xffffc0b0, v166
	v_mov_b64_e32 v[164:165], 0x1020000
	s_or_b64 exec, exec, s[28:29]
	s_waitcnt lgkmcnt(0)
	v_add_f32_e32 v162, v162, v163
	v_fmamk_f32 v162, v162, 0x3c800000, v190
	v_mul_f32_e32 v163, 0x4b800000, v162
	v_cmp_gt_f32_e64 s[28:29], s49, v162
	v_lshlrev_b64 v[142:143], 7, v[142:143]
	v_lshl_add_u64 v[142:143], v[138:139], 0, v[142:143]
	v_cndmask_b32_e64 v162, v162, v163, s[28:29]
	v_rsq_f32_e32 v162, v162
	s_nop 0
	v_mul_f32_e32 v163, 0x45800000, v162
	v_cndmask_b32_e64 v162, v162, v163, s[28:29]
	v_pk_mul_f32 v[182:183], v[68:69], v[162:163] op_sel_hi:[1,0]
	v_pk_mul_f32 v[200:201], v[70:71], v[162:163] op_sel_hi:[1,0]
	v_pk_mul_f32 v[132:133], v[132:133], v[182:183]
	v_pk_mul_f32 v[182:183], v[64:65], v[162:163] op_sel_hi:[1,0]
	v_pk_mul_f32 v[162:163], v[66:67], v[162:163] op_sel_hi:[1,0]
	v_pk_mul_f32 v[134:135], v[134:135], v[200:201]
	v_pk_mul_f32 v[130:131], v[130:131], v[162:163]
	v_pk_mul_f32 v[128:129], v[128:129], v[182:183]
	v_cvt_pk_bf16_f32 v200, v132, v133
	v_cvt_pk_bf16_f32 v201, v134, v135
	v_cvt_pk_bf16_f32 v202, v128, v129
	v_cvt_pk_bf16_f32 v203, v130, v131
	global_store_dwordx4 v[142:143], v[200:203], off
	v_ashrrev_i32_e32 v142, 31, v175
	v_cndmask_b32_e64 v143, 0, v142, s[24:25]
	v_cndmask_b32_e64 v142, v180, v175, s[24:25]
	v_lshlrev_b64 v[142:143], 11, v[142:143]
	v_lshl_add_u64 v[142:143], s[66:67], 0, v[142:143]
	v_lshlrev_b32_e32 v162, 2, v164
	v_mov_b32_e32 v163, v153
	v_lshl_add_u64 v[142:143], v[142:143], 0, v[162:163]
	v_lshl_add_u64 v[142:143], v[136:137], 2, v[142:143]
	global_store_dwordx4 v[142:143], v[132:135], off nt
	global_store_dwordx4 v[142:143], v[128:131], off offset:16 nt

;     template <int TYPE>
;     __device__ __forceinline__ void body(f32x4 (&acc)[2][2][4][2], const Unit& u, int wr, int wc, int fr, int fq) const {
;     ...
;                 const int r = rb + ai * 128 + m * 16;
;                 if (r < MT) {
;                     f32x4 v0 = acc[ai][bj][m][0], v1 = acc[ai][bj][m][1];
;                     if (norm64) { const LAS float* xp = xch + ((ai * 128 + m * 16 + lrow) * 4 + (wc & 2)) * 2 + bj; const float rstd = rsqrtf((xp[0] + xp[2]) * (1.f / 64.f) + EPS); v0 = v0 * rstd * g0; v1 = v1 * rstd * g1; }
;                     if (TYPE == 5) { asm volatile("" : "+v"(v0), "+v"(v1));
;                         UNROLL for (int j = 0; j < 4; ++j) { v0[j] = gelu_f(v0[j]); v1[j] = gelu_f(v1[j]); } }
;                     if (norm128) { const LAS float* xp = xch + ((ai * 128 + m * 16 + lrow) * 4) * 2 + bj; const float rstd = rsqrtf(((xp[0] + xp[2]) + (xp[4] + xp[6])) * (1.f / 128.f) + EPS); v0 = v0 * rstd * g0; v1 = v1 * rstd * g1; }
;                     if (TYPE == 4) { UNROLL for (int j = 0; j < 4; ++j) { v0[j] = gelu_f(v0[j]); v1[j] = gelu_f(v1[j]); } }
;                     if (TYPE == 3 || TYPE == 6) { UNROLL for (int j = 0; j < 4; ++j) { v0[j] = silu_f(v0[j]); v1[j] = silu_f(v1[j]); } }
;                     if (TYPE == 2 && r < MP) {
;                         const bf16x8 av = __builtin_bit_cast(bf16x8, pack8(v0, v1));
;                         const int r16 = r - fr;
;                         bf16_t* vtb = bdst + (size_t)((r16 >> 13) * 8 + (col >> 6)) * (8192 * 64) + (size_t)((r16 & 8191) >> 5) * 2048 + (size_t)(((wc & 1) * 2 + ((r16 >> 4) & 1)) * 512);
;                         UNROLL for (int sel = 0; sel < 2; ++sel) {
;                             bf16x8 bsel; UNROLL for (int e = 0; e < 8; ++e) bsel[e] = (8 * fq + e == 16 * sel + fr) ? (short)0x3F80 : (short)0;
;                             const f32x4 dv = __builtin_amdgcn_mfma_f32_16x16x32_bf16(av, bsel, (f32x4){0.f, 0.f, 0.f, 0.f}, 0, 0, 0);
;                             *(u32x2*)(vtb + (size_t)((16 * sel + fr + 32 * (fq & 1)) * 8 + (fq >> 1) * 4)) = pack4(dv);
;                         }
;                     } else {
;                     const size_t bo = headlay ? (tokhead_idx<(TYPE == 1 || TYPE == 2)>(r, col >> 6) * 64 + (col & 63)) : ((size_t)r * 512 + col);
;                     *(u32x4*)(bdst + bo) = pack8(v0, v1);
;                     }
.LBB0_456:
	s_or_b64 exec, exec, s[2:3]
	s_and_saveexec_b64 s[2:3], s[0:1]
	s_cbranch_execz .LBB0_462
	ds_read2_b32 v[162:163], v167 offset0:129 offset1:131
	v_add_u32_e32 v165, 0xffffc010, v166
	s_and_saveexec_b64 s[0:1], s[18:19]
	s_xor_b64 s[0:1], exec, s[0:1]
	v_add_u32_e32 v165, 0xffffc010, v166
	v_lshrrev_b32_e32 v140, 1, v165
	v_and_b32_e32 v140, 0x7ffffff8, v140
	v_add_u32_e32 v140, v140, v164
	v_mad_i64_i32 v[140:141], s[16:17], v140, s44, v[152:153]
	s_or_saveexec_b64 s[0:1], s[0:1]
	v_mov_b64_e32 v[142:143], 0x2020000
	s_xor_b64 exec, exec, s[0:1]
	v_ashrrev_i32_e32 v140, 10, v170
	v_and_b32_e32 v140, -8, v140
	v_add_u32_e32 v140, v140, v164
	v_ashrrev_i32_e32 v141, 31, v140
	v_lshlrev_b64 v[140:141], 13, v[140:141]
	v_and_or_b32 v140, v170, s97, v140
	v_mov_b64_e32 v[142:143], 0x1020000
	s_or_b64 exec, exec, s[0:1]
	s_waitcnt lgkmcnt(0)
	v_add_f32_e32 v143, v162, v163
	v_fmamk_f32 v143, v143, 0x3c800000, v190
	v_mul_f32_e32 v162, 0x4b800000, v143
	v_cmp_gt_f32_e32 vcc, s49, v143
	v_lshlrev_b64 v[140:141], 7, v[140:141]
	v_lshl_add_u64 v[140:141], v[138:139], 0, v[140:141]
	v_cndmask_b32_e32 v143, v143, v162, vcc
	v_rsq_f32_e32 v143, v143
	v_lshlrev_b32_e32 v142, 2, v142
	v_mul_f32_e32 v162, 0x45800000, v143
	v_cndmask_b32_e32 v162, v143, v162, vcc
	v_pk_mul_f32 v[180:181], v[52:53], v[162:163] op_sel_hi:[1,0]
	v_pk_mul_f32 v[182:183], v[54:55], v[162:163] op_sel_hi:[1,0]
	v_pk_mul_f32 v[200:201], v[48:49], v[162:163] op_sel_hi:[1,0]
	v_pk_mul_f32 v[162:163], v[50:51], v[162:163] op_sel_hi:[1,0]
	v_pk_mul_f32 v[182:183], v[134:135], v[182:183]
	v_pk_mul_f32 v[180:181], v[132:133], v[180:181]
	v_pk_mul_f32 v[202:203], v[130:131], v[162:163]
	v_pk_mul_f32 v[200:201], v[128:129], v[200:201]
	v_cvt_pk_bf16_f32 v204, v180, v181
	v_cvt_pk_bf16_f32 v205, v182, v183
	v_cvt_pk_bf16_f32 v206, v200, v201
	v_cvt_pk_bf16_f32 v207, v202, v203
	global_store_dwordx4 v[140:141], v[204:207], off
	v_ashrrev_i32_e32 v140, 31, v170
	v_cndmask_b32_e64 v141, 0, v140, s[10:11]
	v_cndmask_b32_e64 v140, v165, v170, s[10:11]
	v_lshlrev_b64 v[140:141], 11, v[140:141]
	v_lshl_add_u64 v[140:141], s[66:67], 0, v[140:141]
	v_mov_b32_e32 v143, v153
	v_lshl_add_u64 v[140:141], v[140:141], 0, v[142:143]
	v_lshl_add_u64 v[140:141], v[136:137], 2, v[140:141]
	global_store_dwordx4 v[140:141], v[180:183], off offset:512 nt
	global_store_dwordx4 v[140:141], v[200:203], off offset:528 nt
.LBB0_462:
	s_or_b64 exec, exec, s[2:3]
	s_and_saveexec_b64 s[0:1], s[4:5]
	s_cbranch_execz .LBB0_468
	ds_read2_b32 v[162:163], v168 offset0:1 offset1:3
	v_add_u32_e32 v165, 0xffffc020, v166
	s_and_saveexec_b64 s[2:3], s[20:21]
	s_xor_b64 s[2:3], exec, s[2:3]
	v_add_u32_e32 v165, 0xffffc020, v166
	v_lshrrev_b32_e32 v140, 1, v165
	v_and_b32_e32 v140, 0x7ffffff8, v140
	v_add_u32_e32 v140, v140, v164
	v_mad_i64_i32 v[140:141], s[4:5], v140, s44, v[152:153]
	s_or_saveexec_b64 s[2:3], s[2:3]
	v_mov_b64_e32 v[142:143], 0x2020000
	s_xor_b64 exec, exec, s[2:3]
	v_ashrrev_i32_e32 v140, 10, v171
	v_and_b32_e32 v140, -8, v140
	v_add_u32_e32 v140, v140, v164
	v_ashrrev_i32_e32 v141, 31, v140
	v_lshlrev_b64 v[140:141], 13, v[140:141]
	v_and_or_b32 v140, v171, s97, v140
	v_mov_b64_e32 v[142:143], 0x1020000
	s_or_b64 exec, exec, s[2:3]
	s_waitcnt lgkmcnt(0)
	v_add_f32_e32 v143, v162, v163
	v_fmamk_f32 v143, v143, 0x3c800000, v190
	v_mul_f32_e32 v162, 0x4b800000, v143
	v_cmp_gt_f32_e32 vcc, s49, v143
	v_lshlrev_b64 v[140:141], 7, v[140:141]
	v_lshl_add_u64 v[140:141], v[138:139], 0, v[140:141]
	v_cndmask_b32_e32 v143, v143, v162, vcc
	v_rsq_f32_e32 v143, v143
	v_lshlrev_b32_e32 v142, 2, v142
	v_mul_f32_e32 v162, 0x45800000, v143
	v_cndmask_b32_e32 v162, v143, v162, vcc
	v_pk_mul_f32 v[180:181], v[44:45], v[162:163] op_sel_hi:[1,0]
	v_pk_mul_f32 v[182:183], v[46:47], v[162:163] op_sel_hi:[1,0]
	v_pk_mul_f32 v[200:201], v[40:41], v[162:163] op_sel_hi:[1,0]
	v_pk_mul_f32 v[162:163], v[42:43], v[162:163] op_sel_hi:[1,0]
	v_pk_mul_f32 v[182:183], v[134:135], v[182:183]
	v_pk_mul_f32 v[180:181], v[132:133], v[180:181]
	v_pk_mul_f32 v[202:203], v[130:131], v[162:163]
	v_pk_mul_f32 v[200:201], v[128:129], v[200:201]
	v_cvt_pk_bf16_f32 v204, v180, v181
	v_cvt_pk_bf16_f32 v205, v182, v183
	v_cvt_pk_bf16_f32 v206, v200, v201
	v_cvt_pk_bf16_f32 v207, v202, v203
	global_store_dwordx4 v[140:141], v[204:207], off
	v_ashrrev_i32_e32 v140, 31, v171
	v_cndmask_b32_e64 v141, 0, v140, s[12:13]
	v_cndmask_b32_e64 v140, v165, v171, s[12:13]
	v_lshlrev_b64 v[140:141], 11, v[140:141]
	v_lshl_add_u64 v[140:141], s[66:67], 0, v[140:141]
	v_mov_b32_e32 v143, v153
	v_lshl_add_u64 v[140:141], v[140:141], 0, v[142:143]
	v_lshl_add_u64 v[140:141], v[136:137], 2, v[140:141]
	global_store_dwordx4 v[140:141], v[180:183], off offset:512 nt
	global_store_dwordx4 v[140:141], v[200:203], off offset:528 nt
;     template <int TYPE>
;     __device__ __forceinline__ void body(f32x4 (&acc)[2][2][4][2], const Unit& u, int wr, int wc, int fr, int fq) const {
;     ...
;                 const int r = rb + ai * 128 + m * 16;
;                 if (r < MT) {
;                     f32x4 v0 = acc[ai][bj][m][0], v1 = acc[ai][bj][m][1];
;                     if (norm64) { const LAS float* xp = xch + ((ai * 128 + m * 16 + lrow) * 4 + (wc & 2)) * 2 + bj; const float rstd = rsqrtf((xp[0] + xp[2]) * (1.f / 64.f) + EPS); v0 = v0 * rstd * g0; v1 = v1 * rstd * g1; }
;                     if (TYPE == 5) { asm volatile("" : "+v"(v0), "+v"(v1));
;                         UNROLL for (int j = 0; j < 4; ++j) { v0[j] = gelu_f(v0[j]); v1[j] = gelu_f(v1[j]); } }
;                     if (norm128) { const LAS float* xp = xch + ((ai * 128 + m * 16 + lrow) * 4) * 2 + bj; const float rstd = rsqrtf(((xp[0] + xp[2]) + (xp[4] + xp[6])) * (1.f / 128.f) + EPS); v0 = v0 * rstd * g0; v1 = v1 * rstd * g1; }
;                     if (TYPE == 4) { UNROLL for (int j = 0; j < 4; ++j) { v0[j] = gelu_f(v0[j]); v1[j] = gelu_f(v1[j]); } }
;                     if (TYPE == 3 || TYPE == 6) { UNROLL for (int j = 0; j < 4; ++j) { v0[j] = silu_f(v0[j]); v1[j] = silu_f(v1[j]); } }
;                     if (TYPE == 2 && r < MP) {
;                         const bf16x8 av = __builtin_bit_cast(bf16x8, pack8(v0, v1));
;                         const int r16 = r - fr;
;                         bf16_t* vtb = bdst + (size_t)((r16 >> 13) * 8 + (col >> 6)) * (8192 * 64) + (size_t)((r16 & 8191) >> 5) * 2048 + (size_t)(((wc & 1) * 2 + ((r16 >> 4) & 1)) * 512);
;                         UNROLL for (int sel = 0; sel < 2; ++sel) {
;                             bf16x8 bsel; UNROLL for (int e = 0; e < 8; ++e) bsel[e] = (8 * fq + e == 16 * sel + fr) ? (short)0x3F80 : (short)0;
;                             const f32x4 dv = __builtin_amdgcn_mfma_f32_16x16x32_bf16(av, bsel, (f32x4){0.f, 0.f, 0.f, 0.f}, 0, 0, 0);
;                             *(u32x2*)(vtb + (size_t)((16 * sel + fr + 32 * (fq & 1)) * 8 + (fq >> 1) * 4)) = pack4(dv);
;                         }
;                     } else {
;                     const size_t bo = headlay ? (tokhead_idx<(TYPE == 1 || TYPE == 2)>(r, col >> 6) * 64 + (col & 63)) : ((size_t)r * 512 + col);
;                     *(u32x4*)(bdst + bo) = pack8(v0, v1);
;                     }
.LBB0_468:
	s_or_b64 exec, exec, s[0:1]
	s_and_saveexec_b64 s[0:1], s[6:7]
	s_cbranch_execz .LBB0_474
	ds_read2_b32 v[162:163], v168 offset0:129 offset1:131
	v_add_u32_e32 v165, 0xffffc030, v166
	s_and_saveexec_b64 s[2:3], s[22:23]
	s_xor_b64 s[2:3], exec, s[2:3]
	v_add_u32_e32 v165, 0xffffc030, v166
	v_lshrrev_b32_e32 v140, 1, v165
	v_and_b32_e32 v140, 0x7ffffff8, v140
	v_add_u32_e32 v140, v140, v164
	v_mad_i64_i32 v[140:141], s[4:5], v140, s44, v[152:153]
	s_or_saveexec_b64 s[2:3], s[2:3]
	v_mov_b64_e32 v[142:143], 0x2020000
	s_xor_b64 exec, exec, s[2:3]
	v_ashrrev_i32_e32 v140, 10, v172
	v_and_b32_e32 v140, -8, v140
	v_add_u32_e32 v140, v140, v164
	v_ashrrev_i32_e32 v141, 31, v140
	v_lshlrev_b64 v[140:141], 13, v[140:141]
	v_and_or_b32 v140, v172, s97, v140
	v_mov_b64_e32 v[142:143], 0x1020000
	s_or_b64 exec, exec, s[2:3]
	s_waitcnt lgkmcnt(0)
	v_add_f32_e32 v143, v162, v163
	v_fmamk_f32 v143, v143, 0x3c800000, v190
	v_mul_f32_e32 v162, 0x4b800000, v143
	v_cmp_gt_f32_e32 vcc, s49, v143
	v_lshlrev_b64 v[140:141], 7, v[140:141]
	v_lshl_add_u64 v[140:141], v[138:139], 0, v[140:141]
	v_cndmask_b32_e32 v143, v143, v162, vcc
	v_rsq_f32_e32 v143, v143
	v_lshlrev_b32_e32 v142, 2, v142
	v_mul_f32_e32 v162, 0x45800000, v143
	v_cndmask_b32_e32 v162, v143, v162, vcc
	v_pk_mul_f32 v[170:171], v[36:37], v[162:163] op_sel_hi:[1,0]
	v_pk_mul_f32 v[180:181], v[38:39], v[162:163] op_sel_hi:[1,0]
	v_mov_b32_e32 v143, v153
	v_pk_mul_f32 v[182:183], v[134:135], v[180:181]
	v_pk_mul_f32 v[180:181], v[132:133], v[170:171]
	v_pk_mul_f32 v[170:171], v[32:33], v[162:163] op_sel_hi:[1,0]
	v_pk_mul_f32 v[162:163], v[34:35], v[162:163] op_sel_hi:[1,0]
	v_pk_mul_f32 v[200:201], v[128:129], v[170:171]
	v_pk_mul_f32 v[202:203], v[130:131], v[162:163]
	v_cvt_pk_bf16_f32 v204, v180, v181
	v_cvt_pk_bf16_f32 v205, v182, v183
	v_cvt_pk_bf16_f32 v206, v200, v201
	v_cvt_pk_bf16_f32 v207, v202, v203
	global_store_dwordx4 v[140:141], v[204:207], off
	v_ashrrev_i32_e32 v140, 31, v172
	v_cndmask_b32_e64 v141, 0, v140, s[14:15]
	v_cndmask_b32_e64 v140, v165, v172, s[14:15]
	v_lshlrev_b64 v[140:141], 11, v[140:141]
	v_lshl_add_u64 v[140:141], s[66:67], 0, v[140:141]
	v_lshl_add_u64 v[140:141], v[140:141], 0, v[142:143]
	v_lshl_add_u64 v[140:141], v[136:137], 2, v[140:141]
	global_store_dwordx4 v[140:141], v[180:183], off offset:512 nt
	global_store_dwordx4 v[140:141], v[200:203], off offset:528 nt
.LBB0_474:
	s_or_b64 exec, exec, s[0:1]
	s_and_saveexec_b64 s[2:3], s[8:9]
	s_cbranch_execz .LBB0_480
	ds_read2_b32 v[142:143], v177 offset0:1 offset1:3
	s_movk_i32 s0, 0x3f80
	v_cmp_gt_i32_e32 vcc, s0, v166
	v_cmp_lt_i32_e64 s[0:1], s33, v166
	v_add_u32_e32 v165, 0xffffc080, v166
	s_and_saveexec_b64 s[4:5], s[0:1]
	s_xor_b64 s[0:1], exec, s[4:5]
	v_add_u32_e32 v165, 0xffffc080, v166
	v_lshrrev_b32_e32 v140, 1, v165
	v_and_b32_e32 v140, 0x7ffffff8, v140
	v_add_u32_e32 v140, v140, v164
	v_mad_i64_i32 v[140:141], s[4:5], v140, s44, v[152:153]
	s_or_saveexec_b64 s[0:1], s[0:1]
	v_mov_b64_e32 v[162:163], 0x2020000
	s_xor_b64 exec, exec, s[0:1]
	v_ashrrev_i32_e32 v140, 10, v173
	v_and_b32_e32 v140, -8, v140
	v_add_u32_e32 v140, v140, v164
	v_ashrrev_i32_e32 v141, 31, v140
	v_lshlrev_b64 v[140:141], 13, v[140:141]
	v_and_or_b32 v140, v173, s97, v140
	v_mov_b64_e32 v[162:163], 0x1020000
	s_or_b64 exec, exec, s[0:1]
	s_waitcnt lgkmcnt(0)
	v_add_f32_e32 v142, v142, v143
	v_fmamk_f32 v142, v142, 0x3c800000, v190
	v_mul_f32_e32 v143, 0x4b800000, v142
	v_cmp_gt_f32_e64 s[0:1], s49, v142
	v_lshlrev_b64 v[140:141], 7, v[140:141]
	v_lshl_add_u64 v[140:141], v[138:139], 0, v[140:141]
	v_cndmask_b32_e64 v142, v142, v143, s[0:1]
	v_rsq_f32_e32 v142, v142
	s_nop 0
	v_mul_f32_e32 v143, 0x45800000, v142
	v_cndmask_b32_e64 v142, v142, v143, s[0:1]
	v_pk_mul_f32 v[170:171], v[28:29], v[142:143] op_sel_hi:[1,0]
	v_pk_mul_f32 v[180:181], v[30:31], v[142:143] op_sel_hi:[1,0]
	v_pk_mul_f32 v[182:183], v[134:135], v[180:181]
	v_pk_mul_f32 v[180:181], v[132:133], v[170:171]
	v_pk_mul_f32 v[170:171], v[24:25], v[142:143] op_sel_hi:[1,0]
	v_pk_mul_f32 v[142:143], v[26:27], v[142:143] op_sel_hi:[1,0]
	v_pk_mul_f32 v[200:201], v[128:129], v[170:171]
	v_pk_mul_f32 v[202:203], v[130:131], v[142:143]
	v_cvt_pk_bf16_f32 v204, v180, v181
	v_cvt_pk_bf16_f32 v205, v182, v183
	v_cvt_pk_bf16_f32 v206, v200, v201
	v_cvt_pk_bf16_f32 v207, v202, v203
	global_store_dwordx4 v[140:141], v[204:207], off
	v_ashrrev_i32_e32 v140, 31, v173
	v_cndmask_b32_e32 v141, 0, v140, vcc
	v_cndmask_b32_e32 v140, v165, v173, vcc
	v_lshlrev_b64 v[140:141], 11, v[140:141]
	v_lshl_add_u64 v[140:141], s[66:67], 0, v[140:141]
	v_lshlrev_b32_e32 v142, 2, v162
	v_mov_b32_e32 v143, v153
	v_lshl_add_u64 v[140:141], v[140:141], 0, v[142:143]
	v_lshl_add_u64 v[140:141], v[136:137], 2, v[140:141]
	global_store_dwordx4 v[140:141], v[180:183], off offset:512 nt
	global_store_dwordx4 v[140:141], v[200:203], off offset:528 nt
;     template <int TYPE>
;     __device__ __forceinline__ void body(f32x4 (&acc)[2][2][4][2], const Unit& u, int wr, int wc, int fr, int fq) const {
;     ...
;                 const int r = rb + ai * 128 + m * 16;
;                 if (r < MT) {
;                     f32x4 v0 = acc[ai][bj][m][0], v1 = acc[ai][bj][m][1];
;                     if (norm64) { const LAS float* xp = xch + ((ai * 128 + m * 16 + lrow) * 4 + (wc & 2)) * 2 + bj; const float rstd = rsqrtf((xp[0] + xp[2]) * (1.f / 64.f) + EPS); v0 = v0 * rstd * g0; v1 = v1 * rstd * g1; }
;                     if (TYPE == 5) { asm volatile("" : "+v"(v0), "+v"(v1));
;                         UNROLL for (int j = 0; j < 4; ++j) { v0[j] = gelu_f(v0[j]); v1[j] = gelu_f(v1[j]); } }
;                     if (norm128) { const LAS float* xp = xch + ((ai * 128 + m * 16 + lrow) * 4) * 2 + bj; const float rstd = rsqrtf(((xp[0] + xp[2]) + (xp[4] + xp[6])) * (1.f / 128.f) + EPS); v0 = v0 * rstd * g0; v1 = v1 * rstd * g1; }
;                     if (TYPE == 4) { UNROLL for (int j = 0; j < 4; ++j) { v0[j] = gelu_f(v0[j]); v1[j] = gelu_f(v1[j]); } }
;                     if (TYPE == 3 || TYPE == 6) { UNROLL for (int j = 0; j < 4; ++j) { v0[j] = silu_f(v0[j]); v1[j] = silu_f(v1[j]); } }
;                     if (TYPE == 2 && r < MP) {
;                         const bf16x8 av = __builtin_bit_cast(bf16x8, pack8(v0, v1));
;                         const int r16 = r - fr;
;                         bf16_t* vtb = bdst + (size_t)((r16 >> 13) * 8 + (col >> 6)) * (8192 * 64) + (size_t)((r16 & 8191) >> 5) * 2048 + (size_t)(((wc & 1) * 2 + ((r16 >> 4) & 1)) * 512);
;                         UNROLL for (int sel = 0; sel < 2; ++sel) {
;                             bf16x8 bsel; UNROLL for (int e = 0; e < 8; ++e) bsel[e] = (8 * fq + e == 16 * sel + fr) ? (short)0x3F80 : (short)0;
;                             const f32x4 dv = __builtin_amdgcn_mfma_f32_16x16x32_bf16(av, bsel, (f32x4){0.f, 0.f, 0.f, 0.f}, 0, 0, 0);
;                             *(u32x2*)(vtb + (size_t)((16 * sel + fr + 32 * (fq & 1)) * 8 + (fq >> 1) * 4)) = pack4(dv);
;                         }
;                     } else {
;                     const size_t bo = headlay ? (tokhead_idx<(TYPE == 1 || TYPE == 2)>(r, col >> 6) * 64 + (col & 63)) : ((size_t)r * 512 + col);
;                     *(u32x4*)(bdst + bo) = pack8(v0, v1);
;                     }
.LBB0_480:
	s_or_b64 exec, exec, s[2:3]
	s_and_saveexec_b64 s[2:3], s[10:11]
	s_cbranch_execz .LBB0_486
	ds_read2_b32 v[142:143], v178 offset0:129 offset1:131
	s_movk_i32 s0, 0x3f70
	v_cmp_gt_i32_e32 vcc, s0, v166
	s_movk_i32 s0, 0x3f6f
	v_cmp_lt_i32_e64 s[0:1], s0, v166
	v_add_u32_e32 v165, 0xffffc090, v166
	s_and_saveexec_b64 s[4:5], s[0:1]
	s_xor_b64 s[0:1], exec, s[4:5]
	v_add_u32_e32 v165, 0xffffc090, v166
	v_lshrrev_b32_e32 v140, 1, v165
	v_and_b32_e32 v140, 0x7ffffff8, v140
	v_add_u32_e32 v140, v140, v164
	v_mad_i64_i32 v[140:141], s[4:5], v140, s44, v[152:153]
	s_or_saveexec_b64 s[0:1], s[0:1]
	v_mov_b64_e32 v[162:163], 0x2020000
	s_xor_b64 exec, exec, s[0:1]
	v_ashrrev_i32_e32 v140, 10, v174
	v_and_b32_e32 v140, -8, v140
	v_add_u32_e32 v140, v140, v164
	v_ashrrev_i32_e32 v141, 31, v140
	v_lshlrev_b64 v[140:141], 13, v[140:141]
	v_and_or_b32 v140, v174, s97, v140
	v_mov_b64_e32 v[162:163], 0x1020000
	s_or_b64 exec, exec, s[0:1]
	s_waitcnt lgkmcnt(0)
	v_add_f32_e32 v142, v142, v143
	v_fmamk_f32 v142, v142, 0x3c800000, v190
	v_mul_f32_e32 v143, 0x4b800000, v142
	v_cmp_gt_f32_e64 s[0:1], s49, v142
	v_lshlrev_b64 v[140:141], 7, v[140:141]
	v_lshl_add_u64 v[140:141], v[138:139], 0, v[140:141]
	v_cndmask_b32_e64 v142, v142, v143, s[0:1]
	v_rsq_f32_e32 v142, v142
	s_nop 0
	v_mul_f32_e32 v143, 0x45800000, v142
	v_cndmask_b32_e64 v142, v142, v143, s[0:1]
	v_pk_mul_f32 v[170:171], v[20:21], v[142:143] op_sel_hi:[1,0]
	v_pk_mul_f32 v[172:173], v[22:23], v[142:143] op_sel_hi:[1,0]
	v_pk_mul_f32 v[178:179], v[16:17], v[142:143] op_sel_hi:[1,0]
	v_pk_mul_f32 v[142:143], v[18:19], v[142:143] op_sel_hi:[1,0]
	v_pk_mul_f32 v[172:173], v[134:135], v[172:173]
	v_pk_mul_f32 v[170:171], v[132:133], v[170:171]
	v_pk_mul_f32 v[180:181], v[130:131], v[142:143]
	v_pk_mul_f32 v[178:179], v[128:129], v[178:179]
	v_cvt_pk_bf16_f32 v200, v170, v171
	v_cvt_pk_bf16_f32 v201, v172, v173
	v_cvt_pk_bf16_f32 v202, v178, v179
	v_cvt_pk_bf16_f32 v203, v180, v181
	global_store_dwordx4 v[140:141], v[200:203], off
	v_ashrrev_i32_e32 v140, 31, v174
	v_cndmask_b32_e32 v141, 0, v140, vcc
	v_cndmask_b32_e32 v140, v165, v174, vcc
	v_lshlrev_b64 v[140:141], 11, v[140:141]
	v_lshl_add_u64 v[140:141], s[66:67], 0, v[140:141]
	v_lshlrev_b32_e32 v142, 2, v162
	v_mov_b32_e32 v143, v153
	v_lshl_add_u64 v[140:141], v[140:141], 0, v[142:143]
	v_lshl_add_u64 v[140:141], v[136:137], 2, v[140:141]
	global_store_dwordx4 v[140:141], v[170:173], off offset:512 nt
	global_store_dwordx4 v[140:141], v[178:181], off offset:528 nt
;     template <int TYPE>
;     __device__ __forceinline__ void body(f32x4 (&acc)[2][2][4][2], const Unit& u, int wr, int wc, int fr, int fq) const {
;     ...
;                 const int r = rb + ai * 128 + m * 16;
;                 if (r < MT) {
;                     f32x4 v0 = acc[ai][bj][m][0], v1 = acc[ai][bj][m][1];
;                     if (norm64) { const LAS float* xp = xch + ((ai * 128 + m * 16 + lrow) * 4 + (wc & 2)) * 2 + bj; const float rstd = rsqrtf((xp[0] + xp[2]) * (1.f / 64.f) + EPS); v0 = v0 * rstd * g0; v1 = v1 * rstd * g1; }
;                     if (TYPE == 5) { asm volatile("" : "+v"(v0), "+v"(v1));
;                         UNROLL for (int j = 0; j < 4; ++j) { v0[j] = gelu_f(v0[j]); v1[j] = gelu_f(v1[j]); } }
;                     if (norm128) { const LAS float* xp = xch + ((ai * 128 + m * 16 + lrow) * 4) * 2 + bj; const float rstd = rsqrtf(((xp[0] + xp[2]) + (xp[4] + xp[6])) * (1.f / 128.f) + EPS); v0 = v0 * rstd * g0; v1 = v1 * rstd * g1; }
;                     if (TYPE == 4) { UNROLL for (int j = 0; j < 4; ++j) { v0[j] = gelu_f(v0[j]); v1[j] = gelu_f(v1[j]); } }
;                     if (TYPE == 3 || TYPE == 6) { UNROLL for (int j = 0; j < 4; ++j) { v0[j] = silu_f(v0[j]); v1[j] = silu_f(v1[j]); } }
;                     if (TYPE == 2 && r < MP) {
;                         const bf16x8 av = __builtin_bit_cast(bf16x8, pack8(v0, v1));
;                         const int r16 = r - fr;
;                         bf16_t* vtb = bdst + (size_t)((r16 >> 13) * 8 + (col >> 6)) * (8192 * 64) + (size_t)((r16 & 8191) >> 5) * 2048 + (size_t)(((wc & 1) * 2 + ((r16 >> 4) & 1)) * 512);
;                         UNROLL for (int sel = 0; sel < 2; ++sel) {
;                             bf16x8 bsel; UNROLL for (int e = 0; e < 8; ++e) bsel[e] = (8 * fq + e == 16 * sel + fr) ? (short)0x3F80 : (short)0;
;                             const f32x4 dv = __builtin_amdgcn_mfma_f32_16x16x32_bf16(av, bsel, (f32x4){0.f, 0.f, 0.f, 0.f}, 0, 0, 0);
;                             *(u32x2*)(vtb + (size_t)((16 * sel + fr + 32 * (fq & 1)) * 8 + (fq >> 1) * 4)) = pack4(dv);
;                         }
;                     } else {
;                     const size_t bo = headlay ? (tokhead_idx<(TYPE == 1 || TYPE == 2)>(r, col >> 6) * 64 + (col & 63)) : ((size_t)r * 512 + col);
;                     *(u32x4*)(bdst + bo) = pack8(v0, v1);
;                     }
.LBB0_486:
	s_or_b64 exec, exec, s[2:3]
	s_and_saveexec_b64 s[2:3], s[12:13]
	s_cbranch_execz .LBB0_492
	ds_read2_b32 v[142:143], v169 offset0:1 offset1:3
	s_movk_i32 s0, 0x3f60
	v_cmp_gt_i32_e32 vcc, s0, v166
	s_movk_i32 s0, 0x3f5f
	v_cmp_lt_i32_e64 s[0:1], s0, v166
	v_add_u32_e32 v165, 0xffffc0a0, v166
	s_and_saveexec_b64 s[4:5], s[0:1]
	s_xor_b64 s[0:1], exec, s[4:5]
	v_add_u32_e32 v165, 0xffffc0a0, v166
	v_lshrrev_b32_e32 v140, 1, v165
	v_and_b32_e32 v140, 0x7ffffff8, v140
	v_add_u32_e32 v140, v140, v164
	v_mad_i64_i32 v[140:141], s[4:5], v140, s44, v[152:153]
	s_or_saveexec_b64 s[0:1], s[0:1]
	v_mov_b64_e32 v[162:163], 0x2020000
	s_xor_b64 exec, exec, s[0:1]
	v_ashrrev_i32_e32 v140, 10, v176
	v_and_b32_e32 v140, -8, v140
	v_add_u32_e32 v140, v140, v164
	v_ashrrev_i32_e32 v141, 31, v140
	v_lshlrev_b64 v[140:141], 13, v[140:141]
	v_and_or_b32 v140, v176, s97, v140
	v_mov_b64_e32 v[162:163], 0x1020000
	s_or_b64 exec, exec, s[0:1]
	s_waitcnt lgkmcnt(0)
	v_add_f32_e32 v142, v142, v143
	v_fmamk_f32 v142, v142, 0x3c800000, v190
	v_mul_f32_e32 v143, 0x4b800000, v142
	v_cmp_gt_f32_e64 s[0:1], s49, v142
	v_lshlrev_b64 v[140:141], 7, v[140:141]
	v_lshl_add_u64 v[140:141], v[138:139], 0, v[140:141]
	v_cndmask_b32_e64 v142, v142, v143, s[0:1]
	v_rsq_f32_e32 v142, v142
	s_nop 0
	v_mul_f32_e32 v143, 0x45800000, v142
	v_cndmask_b32_e64 v142, v142, v143, s[0:1]
	v_pk_mul_f32 v[170:171], v[12:13], v[142:143] op_sel_hi:[1,0]
	v_pk_mul_f32 v[172:173], v[14:15], v[142:143] op_sel_hi:[1,0]
	v_pk_mul_f32 v[178:179], v[8:9], v[142:143] op_sel_hi:[1,0]
	v_pk_mul_f32 v[142:143], v[10:11], v[142:143] op_sel_hi:[1,0]
	v_pk_mul_f32 v[172:173], v[134:135], v[172:173]
	v_pk_mul_f32 v[170:171], v[132:133], v[170:171]
	v_pk_mul_f32 v[180:181], v[130:131], v[142:143]
	v_pk_mul_f32 v[178:179], v[128:129], v[178:179]
	v_cvt_pk_bf16_f32 v200, v170, v171
	v_cvt_pk_bf16_f32 v201, v172, v173
	v_cvt_pk_bf16_f32 v202, v178, v179
	v_cvt_pk_bf16_f32 v203, v180, v181
	global_store_dwordx4 v[140:141], v[200:203], off
	v_ashrrev_i32_e32 v140, 31, v176
	v_cndmask_b32_e32 v141, 0, v140, vcc
	v_cndmask_b32_e32 v140, v165, v176, vcc
	v_lshlrev_b64 v[140:141], 11, v[140:141]
	v_lshl_add_u64 v[140:141], s[66:67], 0, v[140:141]
	v_lshlrev_b32_e32 v142, 2, v162
	v_mov_b32_e32 v143, v153
	v_lshl_add_u64 v[140:141], v[140:141], 0, v[142:143]
	v_lshl_add_u64 v[140:141], v[136:137], 2, v[140:141]
	global_store_dwordx4 v[140:141], v[170:173], off offset:512 nt
	global_store_dwordx4 v[140:141], v[178:181], off offset:528 nt
.LBB0_492:
	s_or_b64 exec, exec, s[2:3]
	s_and_saveexec_b64 s[2:3], s[14:15]
	s_cbranch_execz .LBB0_498
	ds_read2_b32 v[142:143], v169 offset0:129 offset1:131
	s_movk_i32 s0, 0x3f50
	v_cmp_gt_i32_e32 vcc, s0, v166
	s_movk_i32 s0, 0x3f4f
	v_cmp_lt_i32_e64 s[0:1], s0, v166
	v_add_u32_e32 v165, 0xffffc0b0, v166
	s_and_saveexec_b64 s[4:5], s[0:1]
	s_xor_b64 s[0:1], exec, s[4:5]
	v_add_u32_e32 v165, 0xffffc0b0, v166
	v_lshrrev_b32_e32 v140, 1, v165
	v_and_b32_e32 v140, 0x7ffffff8, v140
	v_add_u32_e32 v140, v140, v164
	v_mad_i64_i32 v[140:141], s[4:5], v140, s44, v[152:153]
	s_or_saveexec_b64 s[0:1], s[0:1]
	v_mov_b64_e32 v[162:163], 0x2020000
	s_xor_b64 exec, exec, s[0:1]
	v_ashrrev_i32_e32 v140, 10, v175
	v_and_b32_e32 v140, -8, v140
	v_add_u32_e32 v140, v140, v164
	v_ashrrev_i32_e32 v141, 31, v140
	v_lshlrev_b64 v[140:141], 13, v[140:141]
	v_and_or_b32 v140, v175, s97, v140
	v_mov_b64_e32 v[162:163], 0x1020000
	s_or_b64 exec, exec, s[0:1]
	s_waitcnt lgkmcnt(0)
	v_add_f32_e32 v142, v142, v143
	v_fmamk_f32 v142, v142, 0x3c800000, v190
	v_mul_f32_e32 v143, 0x4b800000, v142
	v_cmp_gt_f32_e64 s[0:1], s49, v142
	v_lshlrev_b64 v[140:141], 7, v[140:141]
	v_lshl_add_u64 v[138:139], v[138:139], 0, v[140:141]
	v_cndmask_b32_e64 v142, v142, v143, s[0:1]
	v_rsq_f32_e32 v142, v142
	v_lshlrev_b32_e32 v152, 2, v162
	v_mul_f32_e32 v143, 0x45800000, v142
	v_cndmask_b32_e64 v142, v142, v143, s[0:1]
	v_pk_mul_f32 v[166:167], v[4:5], v[142:143] op_sel_hi:[1,0]
	v_pk_mul_f32 v[168:169], v[6:7], v[142:143] op_sel_hi:[1,0]
	v_pk_mul_f32 v[132:133], v[132:133], v[166:167]
	v_pk_mul_f32 v[166:167], v[0:1], v[142:143] op_sel_hi:[1,0]
	v_pk_mul_f32 v[142:143], v[2:3], v[142:143] op_sel_hi:[1,0]
	v_pk_mul_f32 v[134:135], v[134:135], v[168:169]
	v_pk_mul_f32 v[130:131], v[130:131], v[142:143]
	v_pk_mul_f32 v[128:129], v[128:129], v[166:167]
	v_cvt_pk_bf16_f32 v166, v132, v133
	v_cvt_pk_bf16_f32 v167, v134, v135
	v_cvt_pk_bf16_f32 v168, v128, v129
	v_cvt_pk_bf16_f32 v169, v130, v131
	global_store_dwordx4 v[138:139], v[166:169], off
	v_ashrrev_i32_e32 v138, 31, v175
	v_cndmask_b32_e32 v139, 0, v138, vcc
	v_cndmask_b32_e32 v138, v165, v175, vcc
	v_lshlrev_b64 v[138:139], 11, v[138:139]
	v_lshl_add_u64 v[138:139], s[66:67], 0, v[138:139]
	v_lshl_add_u64 v[138:139], v[138:139], 0, v[152:153]
	v_lshl_add_u64 v[136:137], v[136:137], 2, v[138:139]
	global_store_dwordx4 v[136:137], v[132:135], off offset:512 nt
	global_store_dwordx4 v[136:137], v[128:131], off offset:528 nt

; #define UNROLL _Pragma("unroll")
; __device__ __forceinline__ unsigned pk2(float a, float b) { f32x2 v = {a, b}; return __builtin_bit_cast(unsigned, __builtin_convertvector(v, bf2_t)); }
; __device__ __forceinline__ float bflo(unsigned w) { return __uint_as_float(w << 16); }
; __device__ __forceinline__ float bfhi(unsigned w) { return __uint_as_float(w & 0xffff0000u); }
; __device__ __forceinline__ void swap_halves(unsigned& a, unsigned& b) { const auto r = __builtin_amdgcn_permlane32_swap(a, b, false, false); a = r[0]; b = r[1]; }
; __device__ __forceinline__ void ld_group_pair(const bf16_t* rowp16, int hh, bool ok, u32x2& g0, u32x2& g1) {
;     u32x4 v = {0u, 0u, 0u, 0u};
;     if (ok) v = *(const u32x4*)(rowp16 + 8 * hh);
;     unsigned a0 = v.x, a1 = v.y, b0 = v.z, b1 = v.w;
;     swap_halves(a0, b0); swap_halves(a1, b1);
;     g0.x = a0; g0.y = a1; g1.x = b0; g1.y = b1;
; }
; __device__ __forceinline__ void st_group_pair(bf16_t* rowp16, int hh, bool ok, u32x2 g0, u32x2 g1) {
;     unsigned a0 = g0.x, a1 = g0.y, b0 = g1.x, b1 = g1.y;
;     swap_halves(a0, b0); swap_halves(a1, b1);
;     if (ok) { u32x4 v; v.x = a0; v.y = a1; v.z = b0; v.w = b1; *(u32x4*)(rowp16 + 8 * hh) = v; }
; }
; template <bool VT>
; __device__ __forceinline__ void attn_item(const Params& P, const bf16_t* qp, const bf16_t* kb0, const bf16_t* vb0, int qb, int nq, int r, int head, int lane, const bf16x8 I0, const bf16x8 I1) {
;     ...
;     {
;         const bf16_t* sg = (const bf16_t*)(P.ws + WS_SG) + (size_t)r * 512 + head * 64;
;         bf16_t* ob = (bf16_t*)(P.ws + WS_O) + (size_t)r * 1024 + head * 64;
;         UNROLL for (int dt = 0; dt < 2; ++dt) UNROLL for (int p = 0; p < 2; ++p) {
;             u32x2 s0, s1;
;             ld_group_pair(sg + 32 * dt + 16 * p, hh, qvalid, s0, s1);
;             const f32x16& o = dt ? o1 : o0;
;             u32x2 a, b2;
;             a.x = pk2(o[8 * p] * bflo(s0.x), o[8 * p + 1] * bfhi(s0.x)); a.y = pk2(o[8 * p + 2] * bflo(s0.y), o[8 * p + 3] * bfhi(s0.y));
;             b2.x = pk2(o[8 * p + 4] * bflo(s1.x), o[8 * p + 5] * bfhi(s1.x)); b2.y = pk2(o[8 * p + 6] * bflo(s1.y), o[8 * p + 7] * bfhi(s1.y));
;             st_group_pair(ob + 32 * dt + 16 * p, hh, qvalid, a, b2);
;         }
;     }
.LBB0_858:
	s_or_b64 exec, exec, s[60:61]
	v_lshlrev_b32_e32 v32, 2, v115
	v_and_b32_e32 v32, 0x7fffe000, v32
	v_or3_b32 v162, v159, v32, v65
	v_lshlrev_b64 v[32:33], 10, v[162:163]
	v_lshlrev_b32_e32 v34, 7, v64
	v_lshl_add_u64 v[32:33], s[90:91], 0, v[32:33]
	v_and_b32_e32 v34, 0x380, v34
	v_mov_b32_e32 v35, v163
	v_lshl_add_u64 v[32:33], v[32:33], 0, v[34:35]
	v_lshlrev_b64 v[36:37], 11, v[162:163]
	v_lshlrev_b32_e32 v162, 1, v160
	v_lshl_add_u64 v[36:37], s[76:77], 0, v[36:37]
	v_lshl_add_u64 v[38:39], v[32:33], 0, v[162:163]
	v_lshl_add_u64 v[36:37], v[36:37], 0, v[34:35]
	global_load_dwordx4 v[236:239], v[38:39], off
	global_load_dwordx4 v[240:243], v[38:39], off offset:32
	global_load_dwordx4 v[244:247], v[38:39], off offset:64
	global_load_dwordx4 v[248:251], v[38:39], off offset:96
	v_lshl_add_u64 v[40:41], v[36:37], 0, v[162:163]
	s_mov_b64 s[60:61], exec
	s_waitcnt vmcnt(3)
	v_mov_b32_e32 v32, v236
	v_mov_b32_e32 v33, v237
	v_mov_b32_e32 v34, v238
	v_mov_b32_e32 v35, v239
	v_mov_b32_e32 v42, v34
	v_mov_b32_e32 v43, v35
	s_nop 0
	v_permlane32_swap_b32_e32 v32, v42
	v_permlane32_swap_b32_e32 v33, v43
	v_lshlrev_b32_e32 v34, 16, v32
	v_and_b32_e32 v35, 0xffff0000, v32
	v_lshlrev_b32_e32 v32, 16, v33
	v_and_b32_e32 v33, 0xffff0000, v33
	v_pk_mul_f32 v[16:17], v[16:17], v[34:35]
	v_pk_mul_f32 v[18:19], v[18:19], v[32:33]
	v_cvt_pk_bf16_f32 v16, v16, v17
	v_cvt_pk_bf16_f32 v17, v18, v19
	v_lshlrev_b32_e32 v18, 16, v42
	v_and_b32_e32 v19, 0xffff0000, v42
	v_pk_mul_f32 v[18:19], v[20:21], v[18:19]
	v_lshlrev_b32_e32 v20, 16, v43
	v_and_b32_e32 v21, 0xffff0000, v43
	v_pk_mul_f32 v[20:21], v[22:23], v[20:21]
	v_cvt_pk_bf16_f32 v18, v18, v19
	v_cvt_pk_bf16_f32 v19, v20, v21
	s_nop 0
	v_permlane32_swap_b32_e32 v16, v18
	v_permlane32_swap_b32_e32 v17, v19
	global_store_dwordx4 v[40:41], v[16:19], off
	s_waitcnt vmcnt(3)
	s_nop 1
	v_mov_b32_e32 v16, v240
	v_mov_b32_e32 v17, v241
	v_mov_b32_e32 v18, v242
	v_mov_b32_e32 v19, v243
	v_mov_b32_e32 v20, v18
	s_nop 1
	v_permlane32_swap_b32_e32 v16, v20
	v_mov_b32_e32 v21, v19
	v_lshlrev_b32_e32 v18, 16, v16
	v_and_b32_e32 v19, 0xffff0000, v16
	v_permlane32_swap_b32_e32 v17, v21
	v_pk_mul_f32 v[18:19], v[24:25], v[18:19]
	s_nop 0
	v_cvt_pk_bf16_f32 v16, v18, v19
	v_lshlrev_b32_e32 v18, 16, v17
	v_and_b32_e32 v19, 0xffff0000, v17
	v_pk_mul_f32 v[18:19], v[26:27], v[18:19]
	s_nop 0
	v_cvt_pk_bf16_f32 v17, v18, v19
	v_lshlrev_b32_e32 v18, 16, v20
	v_and_b32_e32 v19, 0xffff0000, v20
	v_lshlrev_b32_e32 v20, 16, v21
	v_and_b32_e32 v21, 0xffff0000, v21
	v_pk_mul_f32 v[18:19], v[28:29], v[18:19]
	v_pk_mul_f32 v[20:21], v[30:31], v[20:21]
	v_cvt_pk_bf16_f32 v18, v18, v19
	v_cvt_pk_bf16_f32 v19, v20, v21
	s_nop 0
	v_permlane32_swap_b32_e32 v16, v18
	v_permlane32_swap_b32_e32 v17, v19
	global_store_dwordx4 v[40:41], v[16:19], off offset:32
	s_waitcnt vmcnt(3)
	s_nop 1
	v_mov_b32_e32 v16, v244
	v_mov_b32_e32 v17, v245
	v_mov_b32_e32 v18, v246
	v_mov_b32_e32 v19, v247
	v_mov_b32_e32 v20, v18
	v_mov_b32_e32 v21, v19
	s_nop 0
	v_permlane32_swap_b32_e32 v16, v20
	v_permlane32_swap_b32_e32 v17, v21
	v_lshlrev_b32_e32 v18, 16, v16
	v_and_b32_e32 v19, 0xffff0000, v16
	v_lshlrev_b32_e32 v16, 16, v17
	v_and_b32_e32 v17, 0xffff0000, v17
	v_pk_mul_f32 v[0:1], v[0:1], v[18:19]
	v_pk_mul_f32 v[2:3], v[2:3], v[16:17]
	v_cvt_pk_bf16_f32 v0, v0, v1
	v_cvt_pk_bf16_f32 v1, v2, v3
	v_lshlrev_b32_e32 v2, 16, v20
	v_and_b32_e32 v3, 0xffff0000, v20
	v_pk_mul_f32 v[2:3], v[4:5], v[2:3]
	v_lshlrev_b32_e32 v4, 16, v21
	v_and_b32_e32 v5, 0xffff0000, v21
	v_pk_mul_f32 v[4:5], v[6:7], v[4:5]
	v_cvt_pk_bf16_f32 v2, v2, v3
	v_cvt_pk_bf16_f32 v3, v4, v5
	s_nop 0
	v_permlane32_swap_b32_e32 v0, v2
	v_permlane32_swap_b32_e32 v1, v3
	global_store_dwordx4 v[40:41], v[0:3], off offset:64
	s_waitcnt vmcnt(3)
	s_nop 1
	v_mov_b32_e32 v0, v248
	v_mov_b32_e32 v1, v249
	v_mov_b32_e32 v2, v250
	v_mov_b32_e32 v3, v251
	v_mov_b32_e32 v4, v2
	s_nop 1
	v_permlane32_swap_b32_e32 v0, v4
	v_mov_b32_e32 v5, v3
	v_lshlrev_b32_e32 v2, 16, v0
	v_and_b32_e32 v3, 0xffff0000, v0
	v_permlane32_swap_b32_e32 v1, v5
	v_pk_mul_f32 v[2:3], v[8:9], v[2:3]
	s_nop 0
	v_cvt_pk_bf16_f32 v0, v2, v3
	v_lshlrev_b32_e32 v2, 16, v1
	v_and_b32_e32 v3, 0xffff0000, v1
	v_pk_mul_f32 v[2:3], v[10:11], v[2:3]
	s_nop 0
	v_cvt_pk_bf16_f32 v1, v2, v3
	v_lshlrev_b32_e32 v2, 16, v4
	v_and_b32_e32 v3, 0xffff0000, v4
	v_lshlrev_b32_e32 v4, 16, v5
	v_and_b32_e32 v5, 0xffff0000, v5
	v_pk_mul_f32 v[2:3], v[12:13], v[2:3]
	v_pk_mul_f32 v[4:5], v[14:15], v[4:5]
	v_cvt_pk_bf16_f32 v2, v2, v3
	v_cvt_pk_bf16_f32 v3, v4, v5
	s_nop 0
	v_permlane32_swap_b32_e32 v0, v2
	v_permlane32_swap_b32_e32 v1, v3
	s_andn2_saveexec_b64 s[0:1], s[0:1]
	s_cbranch_execz .LBB0_853

; #define UNROLL _Pragma("unroll")
; __device__ __forceinline__ float dot4(f32x4 a) { return (a.x * a.x + a.y * a.y) + (a.z * a.z + a.w * a.w); }
; __device__ __forceinline__ u32x2 pack4(f32x4 a) { u32x2 w; w.x = pk2(a.x, a.y); w.y = pk2(a.z, a.w); return w; }
; #define MFMA16(a, b, c) __builtin_amdgcn_mfma_f32_16x16x32_bf16((a), (b), (c), 0, 0, 0)
; __device__ __forceinline__ void p3_sample(const Params& P, LAS unsigned char* lds) {
;     ...
;     for (int T = blockIdx.x * 2 + slot; T < 512; T += gridDim.x * 2) {
;         const int r0 = MP + 16 * (T >> 6), c0 = 16 * (T & 63), ct = T & 63;
;         const bf16_t* A = (const bf16_t*)(ws + WS_O) + (size_t)(r0 + fr) * 1024 + 256 * kq + 8 * fq;
;         const bf16_t* B = (const bf16_t*)(ws + WS_WOUT) + (size_t)(c0 + fr) * 1024 + 256 * kq + 8 * fq;
;         bf16x8 a[8], b[8];
;         UNROLL for (int i = 0; i < 8; ++i) { a[i] = *(const bf16x8*)(A + 32 * i); b[i] = *(const bf16x8*)(B + 32 * i); }
;         f32x4 acc = (f32x4){0.f, 0.f, 0.f, 0.f};
;         UNROLL for (int i = 0; i < 8; ++i) acc = MFMA16(b[i], a[i], acc);
;         red[(slot * 4 + kq) * 64 + lane] = acc;
;         __syncthreads();
;         if (kq == 0) {
;             const f32x4 t = (red[(slot * 4) * 64 + lane] + red[(slot * 4 + 1) * 64 + lane]) + (red[(slot * 4 + 2) * 64 + lane] + red[(slot * 4 + 3) * 64 + lane]);
;             const int r = r0 + fr, c = c0 + 4 * fq;
;             const f32x4 hv = *(const f32x4*)(P.x_s + (size_t)(r - MP) * 1024 + c) + t;
;             *(u32x2*)((bf16_t*)(ws + WS_HB) + (size_t)r * 1024 + c) = pack4(hv);
;             float s = dot4(hv);
;             s += __shfl_xor(s, 16); s += __shfl_xor(s, 32);
;             if (fq == 0) ((float*)(ws + WS_SSQS))[(r - MP) * 64 + ct] = s;
;         }
.LBB0_930:
	v_ashrrev_i32_e32 v0, 2, v10
	v_and_b32_e32 v21, 63, v10
	v_and_b32_e32 v0, -16, v0
	v_lshlrev_b32_e32 v8, 4, v21
	v_add_u32_e32 v6, v0, v12
	v_or_b32_e32 v0, v8, v11
	v_lshlrev_b32_e32 v0, 11, v0
	v_lshl_add_u64 v[58:59], v[4:5], 0, v[0:1]
	v_readlane_b32 s18, v254, 7
	v_readlane_b32 s19, v254, 8
	v_or_b32_e32 v96, v8, v16
	v_add_u32_e32 v98, 0xffffc000, v6
	v_ashrrev_i32_e32 v99, 31, v98
	v_lshlrev_b64 v[100:101], 12, v[98:99]
	v_lshlrev_b32_e32 v96, 2, v96
	v_mov_b32_e32 v97, 0
	v_lshl_add_u64 v[100:101], s[18:19], 0, v[100:101]
	v_lshl_add_u64 v[100:101], v[100:101], 0, v[96:97]
	global_load_dwordx4 v[92:95], v[100:101], off
	global_load_dwordx4 v[22:25], v[58:59], off
	v_ashrrev_i32_e32 v7, 31, v6
	v_lshlrev_b64 v[26:27], 11, v[6:7]
	v_lshl_add_u64 v[60:61], v[2:3], 0, v[26:27]
	global_load_dwordx4 v[26:29], v[60:61], off
	global_load_dwordx4 v[30:33], v[58:59], off offset:64
	global_load_dwordx4 v[34:37], v[58:59], off offset:128
	global_load_dwordx4 v[38:41], v[60:61], off offset:64
	global_load_dwordx4 v[42:45], v[60:61], off offset:128
	global_load_dwordx4 v[46:49], v[58:59], off offset:192
	global_load_dwordx4 v[50:53], v[60:61], off offset:192
	global_load_dwordx4 v[64:67], v[58:59], off offset:256
	global_load_dwordx4 v[54:57], v[58:59], off offset:320
	global_load_dwordx4 v[68:71], v[60:61], off offset:256
	global_load_dwordx4 v[72:75], v[60:61], off offset:320
	global_load_dwordx4 v[76:79], v[58:59], off offset:384
	global_load_dwordx4 v[80:83], v[58:59], off offset:448
	global_load_dwordx4 v[84:87], v[60:61], off offset:384
	global_load_dwordx4 v[88:91], v[60:61], off offset:448
	s_waitcnt vmcnt(14)
	v_mfma_f32_16x16x32_bf16 v[22:25], v[22:25], v[26:29], 0
	s_waitcnt vmcnt(11)
	v_mfma_f32_16x16x32_bf16 v[22:25], v[30:33], v[38:41], v[22:25]
	s_waitcnt vmcnt(10)
	v_mfma_f32_16x16x32_bf16 v[22:25], v[34:37], v[42:45], v[22:25]
	s_waitcnt vmcnt(8)
	v_mfma_f32_16x16x32_bf16 v[22:25], v[46:49], v[50:53], v[22:25]
	s_waitcnt vmcnt(5)
	v_mfma_f32_16x16x32_bf16 v[22:25], v[64:67], v[68:71], v[22:25]
	s_waitcnt vmcnt(4)
	v_mfma_f32_16x16x32_bf16 v[22:25], v[54:57], v[72:75], v[22:25]
	s_waitcnt vmcnt(1)
	v_mfma_f32_16x16x32_bf16 v[22:25], v[76:79], v[84:87], v[22:25]
	s_waitcnt vmcnt(0)
	v_mfma_f32_16x16x32_bf16 v[22:25], v[80:83], v[88:91], v[22:25]
	s_nop 7
	ds_write_b128 v13, v[22:25]
	s_waitcnt lgkmcnt(0)
	s_barrier
	s_and_saveexec_b64 s[10:11], vcc
	s_cbranch_execz .LBB0_929
	v_or_b32_e32 v44, v8, v16
	v_add_u32_e32 v8, 0xffffc000, v6
	v_ashrrev_i32_e32 v9, 31, v8
	v_readlane_b32 s16, v254, 5
	v_lshlrev_b64 v[22:23], 12, v[8:9]
	v_readlane_b32 s18, v254, 7
	v_readlane_b32 s19, v254, 8
	v_lshlrev_b32_e32 v0, 2, v44
	v_lshlrev_b64 v[42:43], 10, v[6:7]
	v_lshl_add_u64 v[22:23], s[18:19], 0, v[22:23]
	v_lshl_add_u64 v[22:23], v[22:23], 0, v[0:1]
	ds_read_b128 v[26:29], v14
	ds_read_b128 v[30:33], v14 offset:1024
	ds_read_b128 v[34:37], v14 offset:2048
	ds_read_b128 v[38:41], v15
	v_cmp_lt_i32_e64 s[4:5], v18, v19
	v_readlane_b32 s17, v254, 6
	s_waitcnt lgkmcnt(2)
	v_pk_add_f32 v[6:7], v[28:29], v[32:33]
	v_pk_add_f32 v[26:27], v[26:27], v[30:31]
	s_waitcnt lgkmcnt(0)
	v_pk_add_f32 v[28:29], v[36:37], v[40:41]
	v_pk_add_f32 v[30:31], v[34:35], v[38:39]
	v_pk_add_f32 v[6:7], v[6:7], v[28:29]
	v_pk_add_f32 v[26:27], v[26:27], v[30:31]
	v_cndmask_b32_e64 v0, v17, v18, s[4:5]
	v_lshlrev_b32_e32 v0, 2, v0
	v_cmp_lt_i32_e64 s[4:5], v20, v19
	v_readlane_b32 s20, v254, 9
	v_readlane_b32 s21, v254, 10
	v_readlane_b32 s22, v254, 11
	v_readlane_b32 s23, v254, 12
	v_readlane_b32 s24, v254, 13
	v_readlane_b32 s25, v254, 14
	v_readlane_b32 s26, v254, 15
	v_readlane_b32 s27, v254, 16
	v_readlane_b32 s28, v254, 17
	v_readlane_b32 s29, v254, 18
	v_readlane_b32 s30, v254, 19
	v_readlane_b32 s31, v254, 20
	s_waitcnt vmcnt(0)
	v_pk_add_f32 v[6:7], v[94:95], v[6:7]
	v_pk_add_f32 v[22:23], v[92:93], v[26:27]
	v_mul_f32_e32 v24, v7, v7
	v_mul_f32_e32 v9, v23, v23
	v_fmac_f32_e32 v9, v22, v22
	v_fmac_f32_e32 v24, v6, v6
	v_add_f32_e32 v9, v9, v24
	ds_bpermute_b32 v0, v0, v9
	v_cndmask_b32_e64 v24, v17, v20, s[4:5]
	v_cvt_pk_bf16_f32 v22, v22, v23
	v_cvt_pk_bf16_f32 v23, v6, v7
	s_waitcnt lgkmcnt(0)
	v_add_f32_e32 v6, v9, v0
	v_lshlrev_b32_e32 v0, 2, v24
	ds_bpermute_b32 v7, v0, v6
	v_lshl_add_u64 v[24:25], v[42:43], 1, s[68:69]
	v_lshlrev_b32_e32 v0, 1, v44
	v_lshl_add_u64 v[24:25], v[24:25], 0, v[0:1]
	global_store_dwordx2 v[24:25], v[22:23], off
	s_and_b64 exec, exec, s[0:1]
	s_cbranch_execz .LBB0_929
	s_waitcnt lgkmcnt(0)
	v_add_f32_e32 v0, v6, v7
	v_lshl_or_b32 v6, v8, 6, v21
	v_ashrrev_i32_e32 v7, 31, v6
	v_lshl_add_u64 v[6:7], v[6:7], 2, s[6:7]
	global_store_dword v[6:7], v0, off
	s_branch .LBB0_929
